# attention NOMAX main loops: each step now leads with its first QK MFMA (operands resident) ahead of the V-frag reads and row-sum/cvt VALU; on top of v16
# speedup vs baseline: 1.0177x; 1.0051x over previous
; #define WAIT_BAR(N) asm volatile("s_waitcnt vmcnt(" #N ") lgkmcnt(0)\n\ts_barrier":::"memory")
;   #define RESC() do{ if(!NOMAX&&resc){ asm volatile("s_waitcnt lgkmcnt(0)":::"memory"); \
;       _Pragma("unroll") for(int d_=0;d_<2*VM;++d_) _Pragma("unroll") for(int r=0;r<16;++r)o[d_][r]*=wsf[crow(r,hi)]; } }while(0)
;   #define ROT() do{sl_prev=sl_cur;sl_cur=sl_next;sl_next=(sl_next==(NSLOT-1)*SLOTB)?0:sl_next+SLOTB;}while(0)
; template<int THRL,int VM,bool NOMAX> __device__ __forceinline__ void attn_unit(const bf16*Qb,const bf16*__restrict__ Kh,const bf16*__restrict__ Vh,bf16*Ob,const int NT,const int sp,float*wscr,char*shm){
;     ...
;   int t=1;
;   for(;t+5<NT;t+=2){
;     STEP(pB0,pB1,pA0,pA1,t,true,true,true);     if constexpr(VM==2){WAIT_BAR(3);}else{WAIT_BAR(2);} RESC(); ROT();
;     STEP(pA0,pA1,pB0,pB1,t+1,true,true,true);   if constexpr(VM==2){WAIT_BAR(3);}else{WAIT_BAR(2);} RESC(); ROT();
;   }
.LBB0_863:
	v_mfma_f32_32x32x16_bf16 v[112:127], v[100:103], v[218:221], 0
	v_lshl_add_u32 v206, s89, 1, v168
	ds_read_b64_tr_b16 v[194:195], v206 offset:24576
	ds_read_b64_tr_b16 v[196:197], v206 offset:25088
	v_add_f32_e32 v108, v80, v81
	v_add_f32_e32 v108, v82, v108
	v_add_f32_e32 v108, v83, v108
	v_add_f32_e32 v108, v84, v108
	v_add_f32_e32 v108, v85, v108
	v_cvt_pk_bf16_f32 v156, v80, v81
	v_cvt_pk_bf16_f32 v157, v82, v83
	ds_read_b64_tr_b16 v[80:81], v206 offset:28672
	ds_read_b64_tr_b16 v[82:83], v206 offset:29184
	v_add_f32_e32 v104, v86, v108
	v_add_f32_e32 v104, v87, v104
	v_add_f32_e32 v104, v88, v104
	v_add_f32_e32 v144, v89, v104
	v_mfma_f32_32x32x16_bf16 v[96:111], v[96:99], v[218:221], 0
	v_cvt_pk_bf16_f32 v158, v84, v85
	v_cvt_pk_bf16_f32 v159, v86, v87
	ds_read_b64_tr_b16 v[84:85], v206 offset:25600
	ds_read_b64_tr_b16 v[86:87], v206 offset:26112
	v_add_f32_e32 v144, v90, v144
	v_add_f32_e32 v144, v91, v144
	v_add_f32_e32 v144, v92, v144
	v_add_f32_e32 v144, v93, v144
	v_cvt_pk_bf16_f32 v152, v88, v89
	v_cvt_pk_bf16_f32 v153, v90, v91
	v_mfma_f32_32x32x16_bf16 v[112:127], v[164:167], v[222:225], v[112:127]
	ds_read_b64_tr_b16 v[88:89], v206 offset:29696
	ds_read_b64_tr_b16 v[90:91], v206 offset:30208
	v_add_f32_e32 v144, v94, v144
	v_add_f32_e32 v144, v95, v144
	v_add_f32_e32 v144, v64, v144
	v_add_f32_e32 v144, v65, v144
	v_mfma_f32_32x32x16_bf16 v[96:111], v[160:163], v[222:225], v[96:111]
	v_cvt_pk_bf16_f32 v154, v92, v93
	v_cvt_pk_bf16_f32 v155, v94, v95
	ds_read_b64_tr_b16 v[92:93], v206 offset:26624
	ds_read_b64_tr_b16 v[94:95], v206 offset:27136
	v_add_f32_e32 v144, v66, v144
	v_add_f32_e32 v144, v67, v144
	v_add_f32_e32 v144, v68, v144
	v_add_f32_e32 v144, v69, v144
	v_cvt_pk_bf16_f32 v148, v64, v65
	v_cvt_pk_bf16_f32 v149, v66, v67
	v_mfma_f32_32x32x16_bf16 v[112:127], v[140:143], v[226:229], v[112:127]
	ds_read_b64_tr_b16 v[198:199], v206 offset:30720
	ds_read_b64_tr_b16 v[200:201], v206 offset:31232
	v_add_f32_e32 v140, v70, v144
	v_add_f32_e32 v140, v71, v140
	v_add_f32_e32 v140, v72, v140
	v_add_f32_e32 v140, v73, v140
	v_mfma_f32_32x32x16_bf16 v[96:111], v[136:139], v[226:229], v[96:111]
	v_cvt_pk_bf16_f32 v150, v68, v69
	v_cvt_pk_bf16_f32 v151, v70, v71
	ds_read_b64_tr_b16 v[202:203], v206 offset:27648
	ds_read_b64_tr_b16 v[204:205], v206 offset:28160
	v_add_f32_e32 v68, v74, v140
	v_add_f32_e32 v68, v75, v68
	v_add_f32_e32 v68, v76, v68
	v_add_f32_e32 v68, v77, v68
	v_cvt_pk_bf16_f32 v144, v72, v73
	v_cvt_pk_bf16_f32 v145, v74, v75
	v_mfma_f32_32x32x16_bf16 v[112:127], v[132:135], v[230:233], v[112:127]
	ds_read_b64_tr_b16 v[72:73], v206 offset:31744
	ds_read_b64_tr_b16 v[74:75], v206 offset:32256
	v_add_f32_e32 v68, v78, v68
	v_add_f32_e32 v68, v79, v68
	v_add_f32_e32 v68, 0, v68
	v_cvt_pk_bf16_f32 v146, v76, v77
	v_mfma_f32_32x32x16_bf16 v[96:111], v[128:131], v[230:233], v[96:111]
	v_cvt_pk_bf16_f32 v147, v78, v79
	s_add_i32 s88, s87, s35
	v_lshl_add_u64 v[64:65], v[180:181], 0, s[54:55]
	s_mov_b32 s89, m0
	s_mov_b32 m0, s88
	s_nop 0
	global_load_lds_dwordx4 v[64:65], off
	s_mov_b32 m0, s89
	s_lshl_b32 s88, s86, 1
	v_lshl_add_u64 v[64:65], v[178:179], 0, s[54:55]
	s_add_i32 s88, s88, s16
	s_mov_b32 s89, m0
	s_mov_b32 m0, s88
	s_nop 0
	global_load_lds_dwordx4 v[64:65], off
	s_mov_b32 m0, s89
	v_lshl_add_u64 v[64:65], v[176:177], 0, s[54:55]
	s_addk_i32 s88, 0x2000
	s_mov_b32 s89, m0
	s_mov_b32 m0, s88
	s_nop 0
	global_load_lds_dwordx4 v[64:65], off
	s_mov_b32 m0, s89
	v_add_f32_e32 v193, v193, v68
	s_waitcnt lgkmcnt(12)
	v_mfma_f32_32x32x16_bf16 v[48:63], v[156:159], v[194:197], v[48:63]
	ds_read_b64_tr_b16 v[76:77], v206 offset:32768
	ds_read_b64_tr_b16 v[78:79], v206 offset:33280
	v_exp_f32_e32 v112, v112
	v_exp_f32_e32 v113, v113
	v_mfma_f32_32x32x16_bf16 v[32:47], v[156:159], v[80:83], v[32:47]
	ds_read_b64_tr_b16 v[194:195], v206 offset:36864
	ds_read_b64_tr_b16 v[196:197], v206 offset:37376
	v_exp_f32_e32 v114, v114
	v_exp_f32_e32 v115, v115
	v_add_u32_e32 v128, s86, v189
	ds_read_b128 v[68:71], v128
	ds_read_b128 v[64:67], v128 offset:512
	s_waitcnt lgkmcnt(14)
	v_mfma_f32_32x32x16_bf16 v[48:63], v[152:155], v[84:87], v[48:63]
	ds_read_b64_tr_b16 v[80:81], v206 offset:33792
	ds_read_b64_tr_b16 v[82:83], v206 offset:34304
	v_exp_f32_e32 v116, v116
	v_exp_f32_e32 v117, v117
	ds_read_b128 v[164:167], v128 offset:2048
	ds_read_b128 v[140:143], v128 offset:2560
	v_mfma_f32_32x32x16_bf16 v[32:47], v[152:155], v[88:91], v[32:47]
	ds_read_b64_tr_b16 v[84:85], v206 offset:37888
	ds_read_b64_tr_b16 v[86:87], v206 offset:38400
	v_exp_f32_e32 v118, v118
	v_exp_f32_e32 v119, v119
	ds_read_b128 v[160:163], v128 offset:4096
	ds_read_b128 v[132:135], v128 offset:4608
	s_waitcnt lgkmcnt(14)
	v_mfma_f32_32x32x16_bf16 v[48:63], v[148:151], v[92:95], v[48:63]
	ds_read_b64_tr_b16 v[88:89], v206 offset:34816
	ds_read_b64_tr_b16 v[90:91], v206 offset:35328
	v_exp_f32_e32 v120, v120
	v_exp_f32_e32 v121, v121
	ds_read_b128 v[136:139], v128 offset:6144
	ds_read_b128 v[128:131], v128 offset:6656
	v_mfma_f32_32x32x16_bf16 v[32:47], v[148:151], v[198:201], v[32:47]
	ds_read_b64_tr_b16 v[92:93], v206 offset:38912
	ds_read_b64_tr_b16 v[94:95], v206 offset:39424
	v_exp_f32_e32 v122, v122
	v_exp_f32_e32 v123, v123
	s_waitcnt lgkmcnt(14)
	v_mfma_f32_32x32x16_bf16 v[48:63], v[144:147], v[202:205], v[48:63]
	ds_read_b64_tr_b16 v[198:199], v206 offset:35840
	ds_read_b64_tr_b16 v[200:201], v206 offset:36352
	v_exp_f32_e32 v124, v124
	v_exp_f32_e32 v125, v125
	v_mfma_f32_32x32x16_bf16 v[32:47], v[144:147], v[72:75], v[32:47]
	ds_read_b64_tr_b16 v[202:203], v206 offset:39936
	ds_read_b64_tr_b16 v[204:205], v206 offset:40448
	v_exp_f32_e32 v126, v126
	v_exp_f32_e32 v127, v127
	s_waitcnt lgkmcnt(14)
	v_mfma_f32_32x32x16_bf16 v[16:31], v[156:159], v[76:79], v[16:31]
	v_exp_f32_e32 v96, v96
	v_exp_f32_e32 v97, v97
	v_mfma_f32_32x32x16_bf16 v[0:15], v[156:159], v[194:197], v[0:15]
	v_exp_f32_e32 v98, v98
	v_exp_f32_e32 v99, v99
	v_mfma_f32_32x32x16_bf16 v[16:31], v[152:155], v[80:83], v[16:31]
	v_exp_f32_e32 v100, v100
	v_exp_f32_e32 v101, v101
	s_waitcnt lgkmcnt(12)
	v_mfma_f32_32x32x16_bf16 v[0:15], v[152:155], v[84:87], v[0:15]
	v_exp_f32_e32 v102, v102
	v_exp_f32_e32 v103, v103
	s_waitcnt lgkmcnt(8)
	v_mfma_f32_32x32x16_bf16 v[16:31], v[148:151], v[88:91], v[16:31]
	v_exp_f32_e32 v104, v104
	v_exp_f32_e32 v105, v105
	s_waitcnt lgkmcnt(4)
	v_mfma_f32_32x32x16_bf16 v[0:15], v[148:151], v[92:95], v[0:15]
	v_exp_f32_e32 v106, v106
	v_exp_f32_e32 v107, v107
	s_waitcnt lgkmcnt(2)
	v_mfma_f32_32x32x16_bf16 v[16:31], v[144:147], v[198:201], v[16:31]
	v_exp_f32_e32 v108, v108
	v_exp_f32_e32 v109, v109
	s_waitcnt lgkmcnt(0)
	v_mfma_f32_32x32x16_bf16 v[0:15], v[144:147], v[202:205], v[0:15]
	v_exp_f32_e32 v110, v110
	v_exp_f32_e32 v111, v111
	s_waitcnt vmcnt(3) lgkmcnt(0)
	s_barrier
; #define WAIT_BAR(N) asm volatile("s_waitcnt vmcnt(" #N ") lgkmcnt(0)\n\ts_barrier":::"memory")
;   #define RESC() do{ if(!NOMAX&&resc){ asm volatile("s_waitcnt lgkmcnt(0)":::"memory"); \
;       _Pragma("unroll") for(int d_=0;d_<2*VM;++d_) _Pragma("unroll") for(int r=0;r<16;++r)o[d_][r]*=wsf[crow(r,hi)]; } }while(0)
;   #define ROT() do{sl_prev=sl_cur;sl_cur=sl_next;sl_next=(sl_next==(NSLOT-1)*SLOTB)?0:sl_next+SLOTB;}while(0)
; template<int THRL,int VM,bool NOMAX> __device__ __forceinline__ void attn_unit(const bf16*Qb,const bf16*__restrict__ Kh,const bf16*__restrict__ Vh,bf16*Ob,const int NT,const int sp,float*wscr,char*shm){
;     ...
;   int t=1;
;   for(;t+5<NT;t+=2){
;     STEP(pB0,pB1,pA0,pA1,t,true,true,true);     if constexpr(VM==2){WAIT_BAR(3);}else{WAIT_BAR(2);} RESC(); ROT();
;     STEP(pA0,pA1,pB0,pB1,t+1,true,true,true);   if constexpr(VM==2){WAIT_BAR(3);}else{WAIT_BAR(2);} RESC(); ROT();
;   }
	v_mfma_f32_32x32x16_bf16 v[80:95], v[68:71], v[218:221], 0
	s_add_i32 s88, s86, 0x2000
	s_cmpk_lg_i32 s86, 0x4000
	s_cselect_b32 s88, s88, 0
	v_lshl_add_u32 v206, s87, 1, v168
	ds_read_b64_tr_b16 v[194:195], v206 offset:24576
	ds_read_b64_tr_b16 v[196:197], v206 offset:25088
	v_add_f32_e32 v76, v112, v113
	v_add_f32_e32 v76, v114, v76
	v_add_f32_e32 v76, v115, v76
	v_add_f32_e32 v76, v116, v76
	v_add_f32_e32 v76, v117, v76
	v_cvt_pk_bf16_f32 v156, v112, v113
	v_cvt_pk_bf16_f32 v157, v114, v115
	ds_read_b64_tr_b16 v[112:113], v206 offset:28672
	ds_read_b64_tr_b16 v[114:115], v206 offset:29184
	v_add_f32_e32 v72, v118, v76
	v_add_f32_e32 v72, v119, v72
	v_add_f32_e32 v72, v120, v72
	v_add_f32_e32 v144, v121, v72
	v_mfma_f32_32x32x16_bf16 v[64:79], v[64:67], v[218:221], 0
	v_cvt_pk_bf16_f32 v158, v116, v117
	v_cvt_pk_bf16_f32 v159, v118, v119
	ds_read_b64_tr_b16 v[116:117], v206 offset:25600
	ds_read_b64_tr_b16 v[118:119], v206 offset:26112
	v_add_f32_e32 v144, v122, v144
	v_add_f32_e32 v144, v123, v144
	v_add_f32_e32 v144, v124, v144
	v_add_f32_e32 v144, v125, v144
	v_mfma_f32_32x32x16_bf16 v[80:95], v[164:167], v[222:225], v[80:95]
	v_cvt_pk_bf16_f32 v152, v120, v121
	v_cvt_pk_bf16_f32 v153, v122, v123
	ds_read_b64_tr_b16 v[120:121], v206 offset:29696
	ds_read_b64_tr_b16 v[122:123], v206 offset:30208
	v_add_f32_e32 v144, v126, v144
	v_add_f32_e32 v144, v127, v144
	v_add_f32_e32 v144, v96, v144
	v_add_f32_e32 v144, v97, v144
	v_mfma_f32_32x32x16_bf16 v[64:79], v[140:143], v[222:225], v[64:79]
	v_cvt_pk_bf16_f32 v154, v124, v125
	v_cvt_pk_bf16_f32 v155, v126, v127
	ds_read_b64_tr_b16 v[124:125], v206 offset:26624
	ds_read_b64_tr_b16 v[126:127], v206 offset:27136
	v_add_f32_e32 v144, v98, v144
	v_add_f32_e32 v144, v99, v144
	v_add_f32_e32 v144, v100, v144
	v_add_f32_e32 v144, v101, v144
	v_mfma_f32_32x32x16_bf16 v[80:95], v[160:163], v[226:229], v[80:95]
	v_cvt_pk_bf16_f32 v148, v96, v97
	v_cvt_pk_bf16_f32 v149, v98, v99
	ds_read_b64_tr_b16 v[198:199], v206 offset:30720
	ds_read_b64_tr_b16 v[200:201], v206 offset:31232
	v_add_f32_e32 v140, v102, v144
	v_add_f32_e32 v140, v103, v140
	v_add_f32_e32 v140, v104, v140
	v_add_f32_e32 v140, v105, v140
	v_mfma_f32_32x32x16_bf16 v[64:79], v[132:135], v[226:229], v[64:79]
	v_cvt_pk_bf16_f32 v150, v100, v101
	v_cvt_pk_bf16_f32 v151, v102, v103
	ds_read_b64_tr_b16 v[202:203], v206 offset:27648
	ds_read_b64_tr_b16 v[204:205], v206 offset:28160
	v_add_f32_e32 v100, v106, v140
	v_add_f32_e32 v100, v107, v100
	v_add_f32_e32 v100, v108, v100
	v_add_f32_e32 v100, v109, v100
	v_mfma_f32_32x32x16_bf16 v[80:95], v[136:139], v[230:233], v[80:95]
	v_cvt_pk_bf16_f32 v144, v104, v105
	v_cvt_pk_bf16_f32 v145, v106, v107
	ds_read_b64_tr_b16 v[104:105], v206 offset:31744
	ds_read_b64_tr_b16 v[106:107], v206 offset:32256
	v_add_f32_e32 v100, v110, v100
	v_add_f32_e32 v100, v111, v100
	v_add_f32_e32 v100, 0, v100
	v_cvt_pk_bf16_f32 v146, v108, v109
	v_mfma_f32_32x32x16_bf16 v[64:79], v[128:131], v[230:233], v[64:79]
	v_cvt_pk_bf16_f32 v147, v110, v111
	s_add_i32 s87, s86, s35
	s_mov_b32 s89, m0
	s_mov_b32 m0, s87
	s_nop 0
	global_load_lds_dwordx4 v[180:181], off
	s_mov_b32 m0, s89
	s_lshl_b32 s87, s88, 1
	s_add_i32 s87, s87, s16
	s_mov_b32 s89, m0
	s_mov_b32 m0, s87
	s_nop 0
	global_load_lds_dwordx4 v[178:179], off
	s_mov_b32 m0, s89
	s_addk_i32 s87, 0x2000
	s_mov_b32 s89, m0
	s_mov_b32 m0, s87
	s_nop 0
	global_load_lds_dwordx4 v[176:177], off
	s_mov_b32 m0, s89
	v_add_f32_e32 v193, v193, v100
	s_waitcnt lgkmcnt(12)
	v_mfma_f32_32x32x16_bf16 v[48:63], v[156:159], v[194:197], v[48:63]
	ds_read_b64_tr_b16 v[108:109], v206 offset:32768
	ds_read_b64_tr_b16 v[110:111], v206 offset:33280
	v_exp_f32_e32 v80, v80
	v_exp_f32_e32 v81, v81
	v_mfma_f32_32x32x16_bf16 v[32:47], v[156:159], v[112:115], v[32:47]
	ds_read_b64_tr_b16 v[194:195], v206 offset:36864
	ds_read_b64_tr_b16 v[196:197], v206 offset:37376
	v_exp_f32_e32 v82, v82
	v_exp_f32_e32 v83, v83
	v_add_u32_e32 v128, s88, v189
	ds_read_b128 v[100:103], v128
	ds_read_b128 v[96:99], v128 offset:512
	s_waitcnt lgkmcnt(14)
	v_mfma_f32_32x32x16_bf16 v[48:63], v[152:155], v[116:119], v[48:63]
	ds_read_b64_tr_b16 v[112:113], v206 offset:33792
	ds_read_b64_tr_b16 v[114:115], v206 offset:34304
	v_exp_f32_e32 v84, v84
	v_exp_f32_e32 v85, v85
	ds_read_b128 v[164:167], v128 offset:2048
	ds_read_b128 v[160:163], v128 offset:2560
	v_mfma_f32_32x32x16_bf16 v[32:47], v[152:155], v[120:123], v[32:47]
	ds_read_b64_tr_b16 v[116:117], v206 offset:37888
	ds_read_b64_tr_b16 v[118:119], v206 offset:38400
	v_exp_f32_e32 v86, v86
	v_exp_f32_e32 v87, v87
	ds_read_b128 v[140:143], v128 offset:4096
	ds_read_b128 v[136:139], v128 offset:4608
	s_waitcnt lgkmcnt(14)
	v_mfma_f32_32x32x16_bf16 v[48:63], v[148:151], v[124:127], v[48:63]
	ds_read_b64_tr_b16 v[120:121], v206 offset:34816
	ds_read_b64_tr_b16 v[122:123], v206 offset:35328
	v_exp_f32_e32 v88, v88
	v_exp_f32_e32 v89, v89
	ds_read_b128 v[132:135], v128 offset:6144
	ds_read_b128 v[128:131], v128 offset:6656
	v_mfma_f32_32x32x16_bf16 v[32:47], v[148:151], v[198:201], v[32:47]
	ds_read_b64_tr_b16 v[124:125], v206 offset:38912
	ds_read_b64_tr_b16 v[126:127], v206 offset:39424
	v_exp_f32_e32 v90, v90
	v_exp_f32_e32 v91, v91
	s_waitcnt lgkmcnt(14)
	v_mfma_f32_32x32x16_bf16 v[48:63], v[144:147], v[202:205], v[48:63]
	ds_read_b64_tr_b16 v[198:199], v206 offset:35840
	ds_read_b64_tr_b16 v[200:201], v206 offset:36352
	v_exp_f32_e32 v92, v92
	v_exp_f32_e32 v93, v93
	v_mfma_f32_32x32x16_bf16 v[32:47], v[144:147], v[104:107], v[32:47]
	ds_read_b64_tr_b16 v[202:203], v206 offset:39936
	ds_read_b64_tr_b16 v[204:205], v206 offset:40448
	v_exp_f32_e32 v94, v94
	v_exp_f32_e32 v95, v95
	s_waitcnt lgkmcnt(14)
	v_mfma_f32_32x32x16_bf16 v[16:31], v[156:159], v[108:111], v[16:31]
	v_exp_f32_e32 v64, v64
	v_exp_f32_e32 v65, v65
	v_mfma_f32_32x32x16_bf16 v[0:15], v[156:159], v[194:197], v[0:15]
	v_exp_f32_e32 v66, v66
	v_exp_f32_e32 v67, v67
	v_mfma_f32_32x32x16_bf16 v[16:31], v[152:155], v[112:115], v[16:31]
	v_exp_f32_e32 v68, v68
	v_exp_f32_e32 v69, v69
	s_waitcnt lgkmcnt(12)
	v_mfma_f32_32x32x16_bf16 v[0:15], v[152:155], v[116:119], v[0:15]
	v_exp_f32_e32 v70, v70
	v_exp_f32_e32 v71, v71
	s_waitcnt lgkmcnt(8)
	v_mfma_f32_32x32x16_bf16 v[16:31], v[148:151], v[120:123], v[16:31]
	v_exp_f32_e32 v72, v72
	v_exp_f32_e32 v73, v73
	s_waitcnt lgkmcnt(4)
	v_mfma_f32_32x32x16_bf16 v[0:15], v[148:151], v[124:127], v[0:15]
	v_exp_f32_e32 v74, v74
	v_exp_f32_e32 v75, v75
	s_waitcnt lgkmcnt(2)
	v_mfma_f32_32x32x16_bf16 v[16:31], v[144:147], v[198:201], v[16:31]
	v_exp_f32_e32 v76, v76
	v_exp_f32_e32 v77, v77
	s_waitcnt lgkmcnt(0)
	v_mfma_f32_32x32x16_bf16 v[0:15], v[144:147], v[202:205], v[0:15]
	v_exp_f32_e32 v78, v78
	v_exp_f32_e32 v79, v79
	s_add_i32 s90, s88, 0x2000
	s_waitcnt vmcnt(3) lgkmcnt(0)
	s_barrier
; #define WAIT_BAR(N) asm volatile("s_waitcnt vmcnt(" #N ") lgkmcnt(0)\n\ts_barrier":::"memory")
;   #define RESC() do{ if(!NOMAX&&resc){ asm volatile("s_waitcnt lgkmcnt(0)":::"memory"); \
;       _Pragma("unroll") for(int d_=0;d_<2*VM;++d_) _Pragma("unroll") for(int r=0;r<16;++r)o[d_][r]*=wsf[crow(r,hi)]; } }while(0)
;   #define ROT() do{sl_prev=sl_cur;sl_cur=sl_next;sl_next=(sl_next==(NSLOT-1)*SLOTB)?0:sl_next+SLOTB;}while(0)
;   #define ENDW(tt) do{ if((tt)+3<NT){ if constexpr(VM==2){WAIT_BAR(3);}else{WAIT_BAR(2);} } else if((tt)+2<NT){ if constexpr(VM==2){WAIT_BAR(2);}else{WAIT_BAR(1);} } else {WAIT_BAR(0);} }while(0)
; template<int THRL,int VM,bool NOMAX> __device__ __forceinline__ void attn_unit(const bf16*Qb,const bf16*__restrict__ Kh,const bf16*__restrict__ Vh,bf16*Ob,const int NT,const int sp,float*wscr,char*shm){
;     ...
;   int t=1;
;   for(;t+5<NT;t+=2){
;     STEP(pB0,pB1,pA0,pA1,t,true,true,true);     if constexpr(VM==2){WAIT_BAR(3);}else{WAIT_BAR(2);} RESC(); ROT();
;     STEP(pA0,pA1,pB0,pB1,t+1,true,true,true);   if constexpr(VM==2){WAIT_BAR(3);}else{WAIT_BAR(2);} RESC(); ROT();
;   }
;     ...
;   for(;t+1<NT;t+=2){
;     STEP(pB0,pB1,pA0,pA1,t,(t+3<NT),(t+1<NT),(t+1<NT));       ENDW(t);   RESC(); ROT();
;     STEP(pA0,pA1,pB0,pB1,t+1,(t+4<NT),(t+2<NT),(t+2<NT));     ENDW(t+1); RESC(); ROT();
	s_cmpk_lg_i32 s88, 0x4000
	s_mov_b32 s89, s86
	s_cselect_b32 s86, s90, 0
	s_add_i32 s85, s85, 2
	v_lshl_add_u64 v[176:177], v[176:177], 0, s[56:57]
	v_lshl_add_u64 v[178:179], v[178:179], 0, s[56:57]
	v_lshl_add_u64 v[180:181], v[180:181], 0, s[56:57]
	s_mov_b32 s87, s88
	s_cmpk_lt_u32 s85, 0x79
	s_cbranch_scc1 .LBB0_863
	s_and_b32 s34, s34, 0x3fffffc0
	s_lshl_b32 s34, s34, 2
	s_add_i32 s34, s34, 0
	s_add_i32 s34, s34, 0x12000
	s_cmp_lg_u32 0, -1
	s_cselect_b32 s85, 0, 0
	s_add_i32 s86, s85, 0x6000
	v_add_u32_e32 v104, s86, v191
	v_add3_u32 v176, v104, v190, v192
	v_add_u32_e32 v177, 0x6000, v168
	ds_read_b64_tr_b16 v[178:179], v168 offset:57344
	ds_read_b64_tr_b16 v[180:181], v168 offset:57856
	v_add_f32_e32 v108, v80, v81
	ds_read_b128 v[104:107], v188
	v_add_f32_e32 v108, v82, v108
	v_add_f32_e32 v108, v83, v108
	v_add_f32_e32 v108, v84, v108
	v_add_f32_e32 v108, v85, v108
	v_cvt_pk_bf16_f32 v156, v80, v81
	v_cvt_pk_bf16_f32 v157, v82, v83
	s_waitcnt lgkmcnt(0)
	v_mfma_f32_32x32x16_bf16 v[112:127], v[100:103], v[104:107], 0
	ds_read_b64_tr_b16 v[80:81], v168 offset:61440
	ds_read_b64_tr_b16 v[82:83], v168 offset:61952
	ds_read_b128 v[100:103], v188
	v_add_f32_e32 v104, v86, v108
	v_add_f32_e32 v104, v87, v104
	v_add_f32_e32 v104, v88, v104
	v_add_f32_e32 v144, v89, v104
	v_cvt_pk_bf16_f32 v158, v84, v85
	v_cvt_pk_bf16_f32 v159, v86, v87
	s_waitcnt lgkmcnt(0)
	v_mfma_f32_32x32x16_bf16 v[96:111], v[96:99], v[100:103], 0
	ds_read_b64_tr_b16 v[84:85], v168 offset:58368
	ds_read_b64_tr_b16 v[86:87], v168 offset:58880
	ds_read_b128 v[194:197], v188 offset:1024
	v_add_f32_e32 v144, v90, v144
	v_add_f32_e32 v144, v91, v144
	v_add_f32_e32 v144, v92, v144
	v_add_f32_e32 v144, v93, v144
	v_cvt_pk_bf16_f32 v152, v88, v89
	v_cvt_pk_bf16_f32 v153, v90, v91
	s_waitcnt lgkmcnt(0)
	v_mfma_f32_32x32x16_bf16 v[112:127], v[164:167], v[194:197], v[112:127]
	ds_read_b64_tr_b16 v[88:89], v168 offset:62464
	ds_read_b64_tr_b16 v[90:91], v168 offset:62976
	ds_read_b128 v[164:167], v188 offset:1024
	v_add_f32_e32 v144, v94, v144
	v_add_f32_e32 v144, v95, v144
	v_add_f32_e32 v144, v64, v144
	v_add_f32_e32 v144, v65, v144
	v_cvt_pk_bf16_f32 v154, v92, v93
	v_cvt_pk_bf16_f32 v155, v94, v95
	s_waitcnt lgkmcnt(0)
	v_mfma_f32_32x32x16_bf16 v[96:111], v[160:163], v[164:167], v[96:111]
	ds_read_b64_tr_b16 v[194:195], v168 offset:59392
	ds_read_b64_tr_b16 v[196:197], v168 offset:59904
	ds_read_b128 v[92:95], v188 offset:2048
	v_add_f32_e32 v144, v66, v144
	v_add_f32_e32 v144, v67, v144
	v_add_f32_e32 v144, v68, v144
	v_add_f32_e32 v144, v69, v144
	v_cvt_pk_bf16_f32 v148, v64, v65
	v_cvt_pk_bf16_f32 v149, v66, v67
	s_waitcnt lgkmcnt(0)
	v_mfma_f32_32x32x16_bf16 v[112:127], v[140:143], v[92:95], v[112:127]
	ds_read_b64_tr_b16 v[140:141], v168 offset:63488
	ds_read_b64_tr_b16 v[142:143], v168 offset:64000
	ds_read_b128 v[64:67], v188 offset:2048
	v_add_f32_e32 v92, v70, v144
	v_add_f32_e32 v92, v71, v92
	v_add_f32_e32 v92, v72, v92
	v_add_f32_e32 v92, v73, v92
	v_cvt_pk_bf16_f32 v150, v68, v69
	v_cvt_pk_bf16_f32 v151, v70, v71
	s_waitcnt lgkmcnt(0)
	v_mfma_f32_32x32x16_bf16 v[96:111], v[136:139], v[64:67], v[96:111]
	ds_read_b64_tr_b16 v[136:137], v168 offset:60416
	ds_read_b64_tr_b16 v[138:139], v168 offset:60928
	ds_read_b128 v[64:67], v188 offset:3072
	v_add_f32_e32 v68, v74, v92
	v_add_f32_e32 v68, v75, v68
	v_add_f32_e32 v68, v76, v68
	v_add_f32_e32 v68, v77, v68
	v_cvt_pk_bf16_f32 v144, v72, v73
	v_cvt_pk_bf16_f32 v145, v74, v75
	s_waitcnt lgkmcnt(0)
	v_mfma_f32_32x32x16_bf16 v[112:127], v[132:135], v[64:67], v[112:127]
	ds_read_b64_tr_b16 v[72:73], v168 offset:64512
	ds_read_b64_tr_b16 v[74:75], v168 offset:65024
	ds_read_b128 v[64:67], v188 offset:3072
	v_add_f32_e32 v68, v78, v68
	v_add_f32_e32 v68, v79, v68
	v_add_f32_e32 v68, 0, v68
	v_cvt_pk_bf16_f32 v146, v76, v77
	v_cvt_pk_bf16_f32 v147, v78, v79
	s_waitcnt lgkmcnt(0)
	v_mfma_f32_32x32x16_bf16 v[96:111], v[128:131], v[64:67], v[96:111]
	v_lshl_add_u64 v[64:65], v[174:175], 0, s[58:59]
	s_mov_b32 s86, m0
	s_mov_b32 m0, s35
	s_nop 0
	global_load_lds_dwordx4 v[64:65], off
	s_mov_b32 m0, s86
	s_add_i32 s85, s85, s17
	v_lshl_add_u64 v[64:65], v[170:171], 0, s[60:61]
	s_add_i32 s17, s85, 0xa000
	s_mov_b32 s35, m0
	s_mov_b32 m0, s17
	s_nop 0
	global_load_lds_dwordx4 v[64:65], off
	s_mov_b32 m0, s35
	v_lshl_add_u64 v[64:65], v[172:173], 0, s[60:61]
	s_add_i32 s35, s17, 0x2000
	s_mov_b32 s86, m0
	s_mov_b32 m0, s35
	s_nop 0
	global_load_lds_dwordx4 v[64:65], off
	s_mov_b32 m0, s86
	v_add_f32_e32 v198, v193, v68
	v_mfma_f32_32x32x16_bf16 v[48:63], v[156:159], v[178:181], v[48:63]
	ds_read_b64_tr_b16 v[76:77], v177 offset:40960
	ds_read_b64_tr_b16 v[78:79], v177 offset:41472
	v_exp_f32_e32 v112, v112
	v_exp_f32_e32 v113, v113
	v_mfma_f32_32x32x16_bf16 v[32:47], v[156:159], v[80:83], v[32:47]
	ds_read_b64_tr_b16 v[128:129], v177 offset:45056
	ds_read_b64_tr_b16 v[130:131], v177 offset:45568
	v_exp_f32_e32 v114, v114
	v_exp_f32_e32 v115, v115
	ds_read_b128 v[68:71], v189 offset:8192
	ds_read_b128 v[64:67], v189 offset:8704
	v_mfma_f32_32x32x16_bf16 v[48:63], v[152:155], v[84:87], v[48:63]
	ds_read_b64_tr_b16 v[132:133], v177 offset:41984
	ds_read_b64_tr_b16 v[134:135], v177 offset:42496
	v_exp_f32_e32 v116, v116
	v_exp_f32_e32 v117, v117
	ds_read_b128 v[164:167], v189 offset:10240
	ds_read_b128 v[92:95], v189 offset:10752
	v_mfma_f32_32x32x16_bf16 v[32:47], v[152:155], v[88:91], v[32:47]
	ds_read_b64_tr_b16 v[178:179], v177 offset:46080
	ds_read_b64_tr_b16 v[180:181], v177 offset:46592
	v_exp_f32_e32 v118, v118
	v_exp_f32_e32 v119, v119
	ds_read_b128 v[160:163], v189 offset:12288
	ds_read_b128 v[84:87], v189 offset:12800
	v_mfma_f32_32x32x16_bf16 v[48:63], v[148:151], v[194:197], v[48:63]
	ds_read_b64_tr_b16 v[190:191], v177 offset:43008
	ds_read_b64_tr_b16 v[192:193], v177 offset:43520
	v_exp_f32_e32 v120, v120
	v_exp_f32_e32 v121, v121
	ds_read_b128 v[88:91], v189 offset:14336
	ds_read_b128 v[80:83], v189 offset:14848
	v_mfma_f32_32x32x16_bf16 v[32:47], v[148:151], v[140:143], v[32:47]
	ds_read_b64_tr_b16 v[194:195], v177 offset:47104
	ds_read_b64_tr_b16 v[196:197], v177 offset:47616
	v_exp_f32_e32 v122, v122
	v_exp_f32_e32 v123, v123
	v_mfma_f32_32x32x16_bf16 v[48:63], v[144:147], v[136:139], v[48:63]
	ds_read_b64_tr_b16 v[140:141], v177 offset:44032
	ds_read_b64_tr_b16 v[142:143], v177 offset:44544
	v_exp_f32_e32 v124, v124
	v_exp_f32_e32 v125, v125
	v_mfma_f32_32x32x16_bf16 v[32:47], v[144:147], v[72:75], v[32:47]
	ds_read_b64_tr_b16 v[136:137], v177 offset:48128
	ds_read_b64_tr_b16 v[138:139], v177 offset:48640
	v_exp_f32_e32 v126, v126
	v_exp_f32_e32 v127, v127
	s_waitcnt lgkmcnt(14)
; #define WAIT_BAR(N) asm volatile("s_waitcnt vmcnt(" #N ") lgkmcnt(0)\n\ts_barrier":::"memory")
;   #define RESC() do{ if(!NOMAX&&resc){ asm volatile("s_waitcnt lgkmcnt(0)":::"memory"); \
;       _Pragma("unroll") for(int d_=0;d_<2*VM;++d_) _Pragma("unroll") for(int r=0;r<16;++r)o[d_][r]*=wsf[crow(r,hi)]; } }while(0)
;   #define ROT() do{sl_prev=sl_cur;sl_cur=sl_next;sl_next=(sl_next==(NSLOT-1)*SLOTB)?0:sl_next+SLOTB;}while(0)
;   #define ENDW(tt) do{ if((tt)+3<NT){ if constexpr(VM==2){WAIT_BAR(3);}else{WAIT_BAR(2);} } else if((tt)+2<NT){ if constexpr(VM==2){WAIT_BAR(2);}else{WAIT_BAR(1);} } else {WAIT_BAR(0);} }while(0)
; template<int THRL,int VM,bool NOMAX> __device__ __forceinline__ void attn_unit(const bf16*Qb,const bf16*__restrict__ Kh,const bf16*__restrict__ Vh,bf16*Ob,const int NT,const int sp,float*wscr,char*shm){
;     ...
;   int t=1;
;   for(;t+5<NT;t+=2){
;     STEP(pB0,pB1,pA0,pA1,t,true,true,true);     if constexpr(VM==2){WAIT_BAR(3);}else{WAIT_BAR(2);} RESC(); ROT();
;     STEP(pA0,pA1,pB0,pB1,t+1,true,true,true);   if constexpr(VM==2){WAIT_BAR(3);}else{WAIT_BAR(2);} RESC(); ROT();
;   }
;     ...
;   for(;t+1<NT;t+=2){
;     STEP(pB0,pB1,pA0,pA1,t,(t+3<NT),(t+1<NT),(t+1<NT));       ENDW(t);   RESC(); ROT();
;     STEP(pA0,pA1,pB0,pB1,t+1,(t+4<NT),(t+2<NT),(t+2<NT));     ENDW(t+1); RESC(); ROT();
	v_mfma_f32_32x32x16_bf16 v[16:31], v[156:159], v[76:79], v[16:31]
	v_exp_f32_e32 v96, v96
	v_exp_f32_e32 v97, v97
	v_mfma_f32_32x32x16_bf16 v[0:15], v[156:159], v[128:131], v[0:15]
	v_exp_f32_e32 v98, v98
	v_exp_f32_e32 v99, v99
	v_mfma_f32_32x32x16_bf16 v[16:31], v[152:155], v[132:135], v[16:31]
	v_exp_f32_e32 v100, v100
	v_exp_f32_e32 v101, v101
	s_waitcnt lgkmcnt(12)
	v_mfma_f32_32x32x16_bf16 v[0:15], v[152:155], v[178:181], v[0:15]
	v_exp_f32_e32 v102, v102
	v_exp_f32_e32 v103, v103
	s_waitcnt lgkmcnt(8)
	v_mfma_f32_32x32x16_bf16 v[16:31], v[148:151], v[190:193], v[16:31]
	v_exp_f32_e32 v104, v104
	v_exp_f32_e32 v105, v105
	s_waitcnt lgkmcnt(4)
	v_mfma_f32_32x32x16_bf16 v[0:15], v[148:151], v[194:197], v[0:15]
	v_exp_f32_e32 v106, v106
	v_exp_f32_e32 v107, v107
	s_waitcnt lgkmcnt(2)
	v_mfma_f32_32x32x16_bf16 v[16:31], v[144:147], v[140:143], v[16:31]
	v_exp_f32_e32 v108, v108
	v_exp_f32_e32 v109, v109
	s_waitcnt lgkmcnt(0)
	v_mfma_f32_32x32x16_bf16 v[0:15], v[144:147], v[136:139], v[0:15]
	v_exp_f32_e32 v110, v110
	v_exp_f32_e32 v111, v111
	s_waitcnt vmcnt(3) lgkmcnt(0)
	s_barrier
	ds_read_b64_tr_b16 v[178:179], v168 offset:24576
	ds_read_b64_tr_b16 v[180:181], v168 offset:25088
	v_add_f32_e32 v76, v112, v113
	ds_read_b128 v[72:75], v188
	v_add_f32_e32 v76, v114, v76
	v_add_f32_e32 v76, v115, v76
	v_add_f32_e32 v76, v116, v76
	v_add_f32_e32 v76, v117, v76
	v_cvt_pk_bf16_f32 v156, v112, v113
	v_cvt_pk_bf16_f32 v157, v114, v115
	s_waitcnt lgkmcnt(0)
	v_mfma_f32_32x32x16_bf16 v[128:143], v[68:71], v[72:75], 0
	ds_read_b64_tr_b16 v[112:113], v168 offset:28672
	ds_read_b64_tr_b16 v[114:115], v168 offset:29184
	ds_read_b128 v[68:71], v188
	v_add_f32_e32 v72, v118, v76
	v_add_f32_e32 v72, v119, v72
	v_add_f32_e32 v72, v120, v72
	v_add_f32_e32 v144, v121, v72
	s_waitcnt lgkmcnt(0)
	v_mfma_f32_32x32x16_bf16 v[64:79], v[64:67], v[68:71], 0
	v_cvt_pk_bf16_f32 v158, v116, v117
	v_cvt_pk_bf16_f32 v159, v118, v119
	ds_read_b64_tr_b16 v[116:117], v168 offset:25600
	ds_read_b64_tr_b16 v[118:119], v168 offset:26112
	ds_read_b128 v[190:193], v188 offset:1024
	v_add_f32_e32 v144, v122, v144
	v_add_f32_e32 v144, v123, v144
	v_add_f32_e32 v144, v124, v144
	v_add_f32_e32 v144, v125, v144
	v_cvt_pk_bf16_f32 v152, v120, v121
	v_cvt_pk_bf16_f32 v153, v122, v123
	s_waitcnt lgkmcnt(0)
	v_mfma_f32_32x32x16_bf16 v[128:143], v[164:167], v[190:193], v[128:143]
	ds_read_b64_tr_b16 v[120:121], v168 offset:29696
	ds_read_b64_tr_b16 v[122:123], v168 offset:30208
	ds_read_b128 v[164:167], v188 offset:1024
	v_add_f32_e32 v144, v126, v144
	v_add_f32_e32 v144, v127, v144
	v_add_f32_e32 v144, v96, v144
	v_add_f32_e32 v144, v97, v144
	s_waitcnt lgkmcnt(0)
	v_mfma_f32_32x32x16_bf16 v[64:79], v[92:95], v[164:167], v[64:79]
	v_cvt_pk_bf16_f32 v154, v124, v125
	v_cvt_pk_bf16_f32 v155, v126, v127
	ds_read_b64_tr_b16 v[92:93], v168 offset:26624
	ds_read_b64_tr_b16 v[94:95], v168 offset:27136
	ds_read_b128 v[124:127], v188 offset:2048
	v_add_f32_e32 v144, v98, v144
	v_add_f32_e32 v144, v99, v144
	v_add_f32_e32 v144, v100, v144
	v_add_f32_e32 v144, v101, v144
	v_cvt_pk_bf16_f32 v148, v96, v97
	v_cvt_pk_bf16_f32 v149, v98, v99
	s_waitcnt lgkmcnt(0)
	v_mfma_f32_32x32x16_bf16 v[128:143], v[160:163], v[124:127], v[128:143]
	ds_read_b64_tr_b16 v[96:97], v168 offset:30720
	ds_read_b64_tr_b16 v[98:99], v168 offset:31232
	ds_read_b128 v[124:127], v188 offset:2048
	v_add_f32_e32 v144, v102, v144
	v_add_f32_e32 v144, v103, v144
	v_add_f32_e32 v144, v104, v144
	v_add_f32_e32 v144, v105, v144
	s_waitcnt lgkmcnt(0)
	v_mfma_f32_32x32x16_bf16 v[64:79], v[84:87], v[124:127], v[64:79]
	v_cvt_pk_bf16_f32 v150, v100, v101
	v_cvt_pk_bf16_f32 v151, v102, v103
	ds_read_b64_tr_b16 v[100:101], v168 offset:27648
	ds_read_b64_tr_b16 v[102:103], v168 offset:28160
	ds_read_b128 v[84:87], v188 offset:3072
	v_add_f32_e32 v124, v106, v144
	v_add_f32_e32 v124, v107, v124
	v_add_f32_e32 v124, v108, v124
	v_add_f32_e32 v124, v109, v124
	v_cvt_pk_bf16_f32 v144, v104, v105
	v_cvt_pk_bf16_f32 v145, v106, v107
	s_waitcnt lgkmcnt(0)
	v_mfma_f32_32x32x16_bf16 v[128:143], v[88:91], v[84:87], v[128:143]
	ds_read_b64_tr_b16 v[88:89], v168 offset:31744
	ds_read_b64_tr_b16 v[90:91], v168 offset:32256
	ds_read_b128 v[84:87], v188 offset:3072
	v_add_f32_e32 v104, v110, v124
	v_add_f32_e32 v104, v111, v104
	v_add_f32_e32 v104, 0, v104
	v_cvt_pk_bf16_f32 v146, v108, v109
	s_waitcnt lgkmcnt(0)
; #define WAIT_BAR(N) asm volatile("s_waitcnt vmcnt(" #N ") lgkmcnt(0)\n\ts_barrier":::"memory")
;   #define RESC() do{ if(!NOMAX&&resc){ asm volatile("s_waitcnt lgkmcnt(0)":::"memory"); \
;       _Pragma("unroll") for(int d_=0;d_<2*VM;++d_) _Pragma("unroll") for(int r=0;r<16;++r)o[d_][r]*=wsf[crow(r,hi)]; } }while(0)
;   #define ROT() do{sl_prev=sl_cur;sl_cur=sl_next;sl_next=(sl_next==(NSLOT-1)*SLOTB)?0:sl_next+SLOTB;}while(0)
;   #define ENDW(tt) do{ if((tt)+3<NT){ if constexpr(VM==2){WAIT_BAR(3);}else{WAIT_BAR(2);} } else if((tt)+2<NT){ if constexpr(VM==2){WAIT_BAR(2);}else{WAIT_BAR(1);} } else {WAIT_BAR(0);} }while(0)
; template<int THRL,int VM,bool NOMAX> __device__ __forceinline__ void attn_unit(const bf16*Qb,const bf16*__restrict__ Kh,const bf16*__restrict__ Vh,bf16*Ob,const int NT,const int sp,float*wscr,char*shm){
;     ...
;   int t=1;
;   for(;t+5<NT;t+=2){
;     STEP(pB0,pB1,pA0,pA1,t,true,true,true);     if constexpr(VM==2){WAIT_BAR(3);}else{WAIT_BAR(2);} RESC(); ROT();
;     STEP(pA0,pA1,pB0,pB1,t+1,true,true,true);   if constexpr(VM==2){WAIT_BAR(3);}else{WAIT_BAR(2);} RESC(); ROT();
;   }
;     ...
;   for(;t+1<NT;t+=2){
;     STEP(pB0,pB1,pA0,pA1,t,(t+3<NT),(t+1<NT),(t+1<NT));       ENDW(t);   RESC(); ROT();
;     STEP(pA0,pA1,pB0,pB1,t+1,(t+4<NT),(t+2<NT),(t+2<NT));     ENDW(t+1); RESC(); ROT();
	v_mfma_f32_32x32x16_bf16 v[64:79], v[80:83], v[84:87], v[64:79]
	v_cvt_pk_bf16_f32 v147, v110, v111
	v_lshl_add_u64 v[80:81], v[174:175], 0, s[62:63]
	s_add_i32 s86, s85, 0x2000
	s_mov_b32 s87, m0
	s_mov_b32 m0, s86
	s_nop 0
	global_load_lds_dwordx4 v[80:81], off
	s_mov_b32 m0, s87
	v_lshl_add_u64 v[80:81], v[170:171], 0, s[64:65]
	s_add_i32 s86, s85, 0xe000
	s_mov_b32 s87, m0
	s_mov_b32 m0, s86
	s_nop 0
	global_load_lds_dwordx4 v[80:81], off
	s_mov_b32 m0, s87
	v_lshl_add_u64 v[80:81], v[172:173], 0, s[64:65]
	s_add_i32 s85, s85, 0x10000
	s_mov_b32 s86, m0
	s_mov_b32 m0, s85
	s_nop 0
	global_load_lds_dwordx4 v[80:81], off
	s_mov_b32 m0, s86
	v_add_f32_e32 v198, v198, v104
	v_mfma_f32_32x32x16_bf16 v[48:63], v[156:159], v[178:181], v[48:63]
	ds_read_b64_tr_b16 v[104:105], v168 offset:32768
	ds_read_b64_tr_b16 v[106:107], v168 offset:33280
	v_exp_f32_e32 v128, v128
	v_exp_f32_e32 v129, v129
	v_mfma_f32_32x32x16_bf16 v[32:47], v[156:159], v[112:115], v[32:47]
	ds_read_b64_tr_b16 v[108:109], v168 offset:36864
	ds_read_b64_tr_b16 v[110:111], v168 offset:37376
	v_exp_f32_e32 v130, v130
	v_exp_f32_e32 v131, v131
	ds_read_b128 v[84:87], v189 offset:16384
	ds_read_b128 v[80:83], v189 offset:16896
	v_mfma_f32_32x32x16_bf16 v[48:63], v[152:155], v[116:119], v[48:63]
	ds_read_b64_tr_b16 v[178:179], v168 offset:33792
	ds_read_b64_tr_b16 v[180:181], v168 offset:34304
	v_exp_f32_e32 v132, v132
	v_exp_f32_e32 v133, v133
	ds_read_b128 v[164:167], v189 offset:18432
	ds_read_b128 v[124:127], v189 offset:18944
	v_mfma_f32_32x32x16_bf16 v[32:47], v[152:155], v[120:123], v[32:47]
	ds_read_b64_tr_b16 v[190:191], v168 offset:37888
	ds_read_b64_tr_b16 v[192:193], v168 offset:38400
	v_exp_f32_e32 v134, v134
	v_exp_f32_e32 v135, v135
	ds_read_b128 v[160:163], v189 offset:20480
	ds_read_b128 v[116:119], v189 offset:20992
	v_mfma_f32_32x32x16_bf16 v[48:63], v[148:151], v[92:95], v[48:63]
	ds_read_b64_tr_b16 v[194:195], v168 offset:34816
	ds_read_b64_tr_b16 v[196:197], v168 offset:35328
	v_exp_f32_e32 v136, v136
	v_exp_f32_e32 v137, v137
	ds_read_b128 v[120:123], v189 offset:22528
	ds_read_b128 v[112:115], v189 offset:23040
	v_mfma_f32_32x32x16_bf16 v[32:47], v[148:151], v[96:99], v[32:47]
	ds_read_b64_tr_b16 v[92:93], v168 offset:38912
	ds_read_b64_tr_b16 v[94:95], v168 offset:39424
	v_exp_f32_e32 v138, v138
	v_exp_f32_e32 v139, v139
	v_mfma_f32_32x32x16_bf16 v[48:63], v[144:147], v[100:103], v[48:63]
	ds_read_b64_tr_b16 v[96:97], v168 offset:35840
	ds_read_b64_tr_b16 v[98:99], v168 offset:36352
	v_exp_f32_e32 v140, v140
	v_exp_f32_e32 v141, v141
	v_mfma_f32_32x32x16_bf16 v[32:47], v[144:147], v[88:91], v[32:47]
	ds_read_b64_tr_b16 v[100:101], v168 offset:39936
	ds_read_b64_tr_b16 v[102:103], v168 offset:40448
	v_exp_f32_e32 v142, v142
	v_exp_f32_e32 v143, v143
	s_waitcnt lgkmcnt(14)
	v_mfma_f32_32x32x16_bf16 v[16:31], v[156:159], v[104:107], v[16:31]
	v_exp_f32_e32 v64, v64
	v_exp_f32_e32 v65, v65
	v_mfma_f32_32x32x16_bf16 v[0:15], v[156:159], v[108:111], v[0:15]
	v_exp_f32_e32 v66, v66
	v_exp_f32_e32 v67, v67
	v_mfma_f32_32x32x16_bf16 v[16:31], v[152:155], v[178:181], v[16:31]
	v_exp_f32_e32 v68, v68
	v_exp_f32_e32 v69, v69
	s_waitcnt lgkmcnt(12)
	v_mfma_f32_32x32x16_bf16 v[0:15], v[152:155], v[190:193], v[0:15]
	v_exp_f32_e32 v70, v70
	v_exp_f32_e32 v71, v71
	s_waitcnt lgkmcnt(8)
	v_mfma_f32_32x32x16_bf16 v[16:31], v[148:151], v[194:197], v[16:31]
	v_exp_f32_e32 v72, v72
	v_exp_f32_e32 v73, v73
	s_waitcnt lgkmcnt(4)
	v_mfma_f32_32x32x16_bf16 v[0:15], v[148:151], v[92:95], v[0:15]
	v_exp_f32_e32 v74, v74
	v_exp_f32_e32 v75, v75
	s_waitcnt lgkmcnt(2)
	v_mfma_f32_32x32x16_bf16 v[16:31], v[144:147], v[96:99], v[16:31]
	v_exp_f32_e32 v76, v76
	v_exp_f32_e32 v77, v77
	s_waitcnt lgkmcnt(0)
	v_mfma_f32_32x32x16_bf16 v[0:15], v[144:147], v[100:103], v[0:15]
	v_exp_f32_e32 v78, v78
	v_exp_f32_e32 v79, v79
	s_waitcnt vmcnt(3) lgkmcnt(0)
	s_barrier
	ds_read_b64_tr_b16 v[178:179], v168 offset:40960
	ds_read_b64_tr_b16 v[180:181], v168 offset:41472
	v_add_f32_e32 v92, v128, v129
	ds_read_b128 v[88:91], v188
	v_add_f32_e32 v92, v130, v92
	v_add_f32_e32 v92, v131, v92
	v_add_f32_e32 v92, v132, v92
	v_add_f32_e32 v92, v133, v92
	v_cvt_pk_bf16_f32 v156, v128, v129
	v_cvt_pk_bf16_f32 v157, v130, v131
	s_waitcnt lgkmcnt(0)
	v_mfma_f32_32x32x16_bf16 v[96:111], v[84:87], v[88:91], 0
	ds_read_b64_tr_b16 v[128:129], v168 offset:45056
	ds_read_b64_tr_b16 v[130:131], v168 offset:45568
	ds_read_b128 v[84:87], v188
	v_add_f32_e32 v88, v134, v92
	v_add_f32_e32 v88, v135, v88
	v_add_f32_e32 v88, v136, v88
	v_add_f32_e32 v144, v137, v88
	v_cvt_pk_bf16_f32 v158, v132, v133
	v_cvt_pk_bf16_f32 v159, v134, v135
	s_waitcnt lgkmcnt(0)
	v_mfma_f32_32x32x16_bf16 v[80:95], v[80:83], v[84:87], 0
	ds_read_b64_tr_b16 v[132:133], v168 offset:41984
	ds_read_b64_tr_b16 v[134:135], v168 offset:42496
	ds_read_b128 v[190:193], v188 offset:1024
	v_add_f32_e32 v144, v138, v144
	v_add_f32_e32 v144, v139, v144
	v_add_f32_e32 v144, v140, v144
	v_add_f32_e32 v144, v141, v144
	v_cvt_pk_bf16_f32 v152, v136, v137
	v_cvt_pk_bf16_f32 v153, v138, v139
	s_waitcnt lgkmcnt(0)
	v_mfma_f32_32x32x16_bf16 v[96:111], v[164:167], v[190:193], v[96:111]
	ds_read_b64_tr_b16 v[136:137], v168 offset:46080
	ds_read_b64_tr_b16 v[138:139], v168 offset:46592
	ds_read_b128 v[164:167], v188 offset:1024
	v_add_f32_e32 v144, v142, v144
	v_add_f32_e32 v144, v143, v144
	v_add_f32_e32 v144, v64, v144
	v_add_f32_e32 v144, v65, v144
	v_cvt_pk_bf16_f32 v154, v140, v141
	v_cvt_pk_bf16_f32 v155, v142, v143
	s_waitcnt lgkmcnt(0)
; #define WAIT_BAR(N) asm volatile("s_waitcnt vmcnt(" #N ") lgkmcnt(0)\n\ts_barrier":::"memory")
;   #define RESC() do{ if(!NOMAX&&resc){ asm volatile("s_waitcnt lgkmcnt(0)":::"memory"); \
;       _Pragma("unroll") for(int d_=0;d_<2*VM;++d_) _Pragma("unroll") for(int r=0;r<16;++r)o[d_][r]*=wsf[crow(r,hi)]; } }while(0)
;   #define ROT() do{sl_prev=sl_cur;sl_cur=sl_next;sl_next=(sl_next==(NSLOT-1)*SLOTB)?0:sl_next+SLOTB;}while(0)
;   #define ENDW(tt) do{ if((tt)+3<NT){ if constexpr(VM==2){WAIT_BAR(3);}else{WAIT_BAR(2);} } else if((tt)+2<NT){ if constexpr(VM==2){WAIT_BAR(2);}else{WAIT_BAR(1);} } else {WAIT_BAR(0);} }while(0)
; template<int THRL,int VM,bool NOMAX> __device__ __forceinline__ void attn_unit(const bf16*Qb,const bf16*__restrict__ Kh,const bf16*__restrict__ Vh,bf16*Ob,const int NT,const int sp,float*wscr,char*shm){
;     ...
;   int t=1;
;   for(;t+5<NT;t+=2){
;     STEP(pB0,pB1,pA0,pA1,t,true,true,true);     if constexpr(VM==2){WAIT_BAR(3);}else{WAIT_BAR(2);} RESC(); ROT();
;     STEP(pA0,pA1,pB0,pB1,t+1,true,true,true);   if constexpr(VM==2){WAIT_BAR(3);}else{WAIT_BAR(2);} RESC(); ROT();
;   }
;     ...
;   for(;t+1<NT;t+=2){
;     STEP(pB0,pB1,pA0,pA1,t,(t+3<NT),(t+1<NT),(t+1<NT));       ENDW(t);   RESC(); ROT();
;     STEP(pA0,pA1,pB0,pB1,t+1,(t+4<NT),(t+2<NT),(t+2<NT));     ENDW(t+1); RESC(); ROT();
	v_mfma_f32_32x32x16_bf16 v[80:95], v[124:127], v[164:167], v[80:95]
	ds_read_b64_tr_b16 v[124:125], v168 offset:43008
	ds_read_b64_tr_b16 v[126:127], v168 offset:43520
	ds_read_b128 v[140:143], v188 offset:2048
	v_add_f32_e32 v144, v66, v144
	v_add_f32_e32 v144, v67, v144
	v_add_f32_e32 v144, v68, v144
	v_add_f32_e32 v144, v69, v144
	v_cvt_pk_bf16_f32 v148, v64, v65
	v_cvt_pk_bf16_f32 v149, v66, v67
	s_waitcnt lgkmcnt(0)
	v_mfma_f32_32x32x16_bf16 v[96:111], v[160:163], v[140:143], v[96:111]
	ds_read_b64_tr_b16 v[190:191], v168 offset:47104
	ds_read_b64_tr_b16 v[192:193], v168 offset:47616
	ds_read_b128 v[64:67], v188 offset:2048
	v_add_f32_e32 v140, v70, v144
	v_add_f32_e32 v140, v71, v140
	v_add_f32_e32 v140, v72, v140
	v_add_f32_e32 v140, v73, v140
	v_cvt_pk_bf16_f32 v150, v68, v69
	v_cvt_pk_bf16_f32 v151, v70, v71
	s_waitcnt lgkmcnt(0)
	v_mfma_f32_32x32x16_bf16 v[80:95], v[116:119], v[64:67], v[80:95]
	ds_read_b64_tr_b16 v[116:117], v168 offset:44032
	ds_read_b64_tr_b16 v[118:119], v168 offset:44544
	ds_read_b128 v[64:67], v188 offset:3072
	v_add_f32_e32 v68, v74, v140
	v_add_f32_e32 v68, v75, v68
	v_add_f32_e32 v68, v76, v68
	v_add_f32_e32 v68, v77, v68
	v_cvt_pk_bf16_f32 v144, v72, v73
	v_cvt_pk_bf16_f32 v145, v74, v75
	s_waitcnt lgkmcnt(0)
	v_mfma_f32_32x32x16_bf16 v[96:111], v[120:123], v[64:67], v[96:111]
	ds_read_b64_tr_b16 v[72:73], v168 offset:48128
	ds_read_b64_tr_b16 v[74:75], v168 offset:48640
	ds_read_b128 v[64:67], v188 offset:3072
	v_add_f32_e32 v68, v78, v68
	v_add_f32_e32 v68, v79, v68
	v_add_f32_e32 v68, 0, v68
	v_cvt_pk_bf16_f32 v146, v76, v77
	v_cvt_pk_bf16_f32 v147, v78, v79
	s_waitcnt lgkmcnt(0)
	v_mfma_f32_32x32x16_bf16 v[80:95], v[112:115], v[64:67], v[80:95]
	v_lshl_add_u64 v[64:65], v[170:171], 0, s[58:59]
	s_mov_b32 s85, m0
	s_mov_b32 m0, s16
	s_nop 0
	global_load_lds_dwordx4 v[64:65], off
	s_mov_b32 m0, s85
	v_lshl_add_u64 v[64:65], v[172:173], 0, s[58:59]
	s_addk_i32 s16, 0x2000
	s_mov_b32 s85, m0
	s_mov_b32 m0, s16
	s_nop 0
	global_load_lds_dwordx4 v[64:65], off
	s_mov_b32 m0, s85
	v_add_f32_e32 v174, v198, v68
	v_mfma_f32_32x32x16_bf16 v[48:63], v[156:159], v[178:181], v[48:63]
	ds_read_b64_tr_b16 v[76:77], v168 offset:49152
	ds_read_b64_tr_b16 v[78:79], v168 offset:49664
	v_exp_f32_e32 v96, v96
	v_exp_f32_e32 v97, v97
	v_mfma_f32_32x32x16_bf16 v[32:47], v[156:159], v[128:131], v[32:47]
	ds_read_b64_tr_b16 v[112:113], v168 offset:53248
	ds_read_b64_tr_b16 v[114:115], v168 offset:53760
	v_exp_f32_e32 v98, v98
	v_exp_f32_e32 v99, v99
	ds_read_b128 v[68:71], v189
	ds_read_b128 v[64:67], v189 offset:512
	v_mfma_f32_32x32x16_bf16 v[48:63], v[152:155], v[132:135], v[48:63]
	ds_read_b64_tr_b16 v[120:121], v168 offset:50176
	ds_read_b64_tr_b16 v[122:123], v168 offset:50688
	v_exp_f32_e32 v100, v100
	v_exp_f32_e32 v101, v101
	ds_read_b128 v[164:167], v189 offset:2048
	ds_read_b128 v[140:143], v189 offset:2560
	v_mfma_f32_32x32x16_bf16 v[32:47], v[152:155], v[136:139], v[32:47]
	ds_read_b64_tr_b16 v[178:179], v168 offset:54272
	ds_read_b64_tr_b16 v[180:181], v168 offset:54784
	v_exp_f32_e32 v102, v102
	v_exp_f32_e32 v103, v103
	ds_read_b128 v[160:163], v189 offset:4096
	ds_read_b128 v[132:135], v189 offset:4608
	v_mfma_f32_32x32x16_bf16 v[48:63], v[148:151], v[124:127], v[48:63]
	ds_read_b64_tr_b16 v[194:195], v168 offset:51200
	ds_read_b64_tr_b16 v[196:197], v168 offset:51712
	v_exp_f32_e32 v104, v104
	v_exp_f32_e32 v105, v105
	ds_read_b128 v[136:139], v189 offset:6144
	ds_read_b128 v[128:131], v189 offset:6656
	v_mfma_f32_32x32x16_bf16 v[32:47], v[148:151], v[190:193], v[32:47]
	ds_read_b64_tr_b16 v[124:125], v168 offset:55296
	ds_read_b64_tr_b16 v[126:127], v168 offset:55808
	v_exp_f32_e32 v106, v106
	v_exp_f32_e32 v107, v107
	v_mfma_f32_32x32x16_bf16 v[48:63], v[144:147], v[116:119], v[48:63]
	ds_read_b64_tr_b16 v[190:191], v168 offset:52224
	ds_read_b64_tr_b16 v[192:193], v168 offset:52736
	v_exp_f32_e32 v108, v108
	v_exp_f32_e32 v109, v109
	v_mfma_f32_32x32x16_bf16 v[32:47], v[144:147], v[72:75], v[32:47]
	ds_read_b64_tr_b16 v[116:117], v168 offset:56320
	ds_read_b64_tr_b16 v[118:119], v168 offset:56832
	v_exp_f32_e32 v110, v110
	v_exp_f32_e32 v111, v111
	s_waitcnt lgkmcnt(14)
	v_mfma_f32_32x32x16_bf16 v[16:31], v[156:159], v[76:79], v[16:31]
	v_exp_f32_e32 v80, v80
	v_exp_f32_e32 v81, v81
	v_mfma_f32_32x32x16_bf16 v[0:15], v[156:159], v[112:115], v[0:15]
	v_exp_f32_e32 v82, v82
	v_exp_f32_e32 v83, v83
	v_mfma_f32_32x32x16_bf16 v[16:31], v[152:155], v[120:123], v[16:31]
	v_exp_f32_e32 v84, v84
	v_exp_f32_e32 v85, v85
	s_waitcnt lgkmcnt(12)
	v_mfma_f32_32x32x16_bf16 v[0:15], v[152:155], v[178:181], v[0:15]
	v_exp_f32_e32 v86, v86
	v_exp_f32_e32 v87, v87
	s_waitcnt lgkmcnt(8)
	v_mfma_f32_32x32x16_bf16 v[16:31], v[148:151], v[194:197], v[16:31]
	v_exp_f32_e32 v88, v88
	v_exp_f32_e32 v89, v89
	s_waitcnt lgkmcnt(4)
	v_mfma_f32_32x32x16_bf16 v[0:15], v[148:151], v[124:127], v[0:15]
	v_exp_f32_e32 v90, v90
	v_exp_f32_e32 v91, v91
	s_waitcnt lgkmcnt(2)
	v_mfma_f32_32x32x16_bf16 v[16:31], v[144:147], v[190:193], v[16:31]
	v_exp_f32_e32 v92, v92
	v_exp_f32_e32 v93, v93
	s_waitcnt lgkmcnt(0)
	v_mfma_f32_32x32x16_bf16 v[0:15], v[144:147], v[116:119], v[0:15]
	v_exp_f32_e32 v94, v94
	v_exp_f32_e32 v95, v95
	s_waitcnt vmcnt(2) lgkmcnt(0)
	s_barrier
; #define WAIT_BAR(N) asm volatile("s_waitcnt vmcnt(" #N ") lgkmcnt(0)\n\ts_barrier":::"memory")
;   #define RESC() do{ if(!NOMAX&&resc){ asm volatile("s_waitcnt lgkmcnt(0)":::"memory"); \
;       _Pragma("unroll") for(int d_=0;d_<2*VM;++d_) _Pragma("unroll") for(int r=0;r<16;++r)o[d_][r]*=wsf[crow(r,hi)]; } }while(0)
;   #define ROT() do{sl_prev=sl_cur;sl_cur=sl_next;sl_next=(sl_next==(NSLOT-1)*SLOTB)?0:sl_next+SLOTB;}while(0)
;   #define ENDW(tt) do{ if((tt)+3<NT){ if constexpr(VM==2){WAIT_BAR(3);}else{WAIT_BAR(2);} } else if((tt)+2<NT){ if constexpr(VM==2){WAIT_BAR(2);}else{WAIT_BAR(1);} } else {WAIT_BAR(0);} }while(0)
; template<int THRL,int VM,bool NOMAX> __device__ __forceinline__ void attn_unit(const bf16*Qb,const bf16*__restrict__ Kh,const bf16*__restrict__ Vh,bf16*Ob,const int NT,const int sp,float*wscr,char*shm){
;     ...
;   int t=1;
;   for(;t+5<NT;t+=2){
;     STEP(pB0,pB1,pA0,pA1,t,true,true,true);     if constexpr(VM==2){WAIT_BAR(3);}else{WAIT_BAR(2);} RESC(); ROT();
;     STEP(pA0,pA1,pB0,pB1,t+1,true,true,true);   if constexpr(VM==2){WAIT_BAR(3);}else{WAIT_BAR(2);} RESC(); ROT();
;   }
;     ...
;   for(;t+1<NT;t+=2){
;     STEP(pB0,pB1,pA0,pA1,t,(t+3<NT),(t+1<NT),(t+1<NT));       ENDW(t);   RESC(); ROT();
;     STEP(pA0,pA1,pB0,pB1,t+1,(t+4<NT),(t+2<NT),(t+2<NT));     ENDW(t+1); RESC(); ROT();
	ds_read_b64_tr_b16 v[178:179], v168 offset:57344
	ds_read_b64_tr_b16 v[180:181], v168 offset:57856
	v_add_f32_e32 v76, v96, v97
	ds_read_b128 v[72:75], v188
	v_add_f32_e32 v76, v98, v76
	v_add_f32_e32 v76, v99, v76
	v_add_f32_e32 v76, v100, v76
	v_add_f32_e32 v76, v101, v76
	v_cvt_pk_bf16_f32 v156, v96, v97
	v_cvt_pk_bf16_f32 v157, v98, v99
	s_waitcnt lgkmcnt(0)
	v_mfma_f32_32x32x16_bf16 v[112:127], v[68:71], v[72:75], 0
	ds_read_b64_tr_b16 v[96:97], v168 offset:61440
	ds_read_b64_tr_b16 v[98:99], v168 offset:61952
	ds_read_b128 v[68:71], v188
	v_add_f32_e32 v72, v102, v76
	v_add_f32_e32 v72, v103, v72
	v_add_f32_e32 v72, v104, v72
	v_add_f32_e32 v144, v105, v72
	s_waitcnt lgkmcnt(0)
	v_mfma_f32_32x32x16_bf16 v[64:79], v[64:67], v[68:71], 0
	v_cvt_pk_bf16_f32 v158, v100, v101
	v_cvt_pk_bf16_f32 v159, v102, v103
	ds_read_b64_tr_b16 v[100:101], v168 offset:58368
	ds_read_b64_tr_b16 v[102:103], v168 offset:58880
	ds_read_b128 v[190:193], v188 offset:1024
	v_add_f32_e32 v144, v106, v144
	v_add_f32_e32 v144, v107, v144
	v_add_f32_e32 v144, v108, v144
	v_add_f32_e32 v144, v109, v144
	v_cvt_pk_bf16_f32 v152, v104, v105
	v_cvt_pk_bf16_f32 v153, v106, v107
	s_waitcnt lgkmcnt(0)
	v_mfma_f32_32x32x16_bf16 v[112:127], v[164:167], v[190:193], v[112:127]
	ds_read_b64_tr_b16 v[104:105], v168 offset:62464
	ds_read_b64_tr_b16 v[106:107], v168 offset:62976
	ds_read_b128 v[164:167], v188 offset:1024
	v_add_f32_e32 v144, v110, v144
	v_add_f32_e32 v144, v111, v144
	v_add_f32_e32 v144, v80, v144
	v_add_f32_e32 v144, v81, v144
	s_waitcnt lgkmcnt(0)
	v_mfma_f32_32x32x16_bf16 v[64:79], v[140:143], v[164:167], v[64:79]
	v_cvt_pk_bf16_f32 v154, v108, v109
	v_cvt_pk_bf16_f32 v155, v110, v111
	ds_read_b64_tr_b16 v[108:109], v168 offset:59392
	ds_read_b64_tr_b16 v[110:111], v168 offset:59904
	ds_read_b128 v[140:143], v188 offset:2048
	v_add_f32_e32 v144, v82, v144
	v_add_f32_e32 v144, v83, v144
	v_add_f32_e32 v144, v84, v144
	v_add_f32_e32 v144, v85, v144
	v_cvt_pk_bf16_f32 v148, v80, v81
	v_cvt_pk_bf16_f32 v149, v82, v83
	s_waitcnt lgkmcnt(0)
	v_mfma_f32_32x32x16_bf16 v[112:127], v[160:163], v[140:143], v[112:127]
	ds_read_b64_tr_b16 v[190:191], v168 offset:63488
	ds_read_b64_tr_b16 v[192:193], v168 offset:64000
	ds_read_b128 v[80:83], v188 offset:2048
	v_add_f32_e32 v140, v86, v144
	v_add_f32_e32 v140, v87, v140
	v_add_f32_e32 v140, v88, v140
	v_add_f32_e32 v140, v89, v140
	s_waitcnt lgkmcnt(0)
	v_mfma_f32_32x32x16_bf16 v[64:79], v[132:135], v[80:83], v[64:79]
	v_cvt_pk_bf16_f32 v150, v84, v85
	v_cvt_pk_bf16_f32 v151, v86, v87
	ds_read_b64_tr_b16 v[84:85], v168 offset:60416
	ds_read_b64_tr_b16 v[86:87], v168 offset:60928
	ds_read_b128 v[80:83], v188 offset:3072
	v_add_f32_e32 v132, v90, v140
	v_add_f32_e32 v132, v91, v132
	v_add_f32_e32 v132, v92, v132
	v_add_f32_e32 v132, v93, v132
	v_cvt_pk_bf16_f32 v144, v88, v89
	v_cvt_pk_bf16_f32 v145, v90, v91
	s_waitcnt lgkmcnt(0)
	v_mfma_f32_32x32x16_bf16 v[112:127], v[136:139], v[80:83], v[112:127]
	ds_read_b64_tr_b16 v[88:89], v168 offset:64512
	ds_read_b64_tr_b16 v[90:91], v168 offset:65024
	ds_read_b128 v[80:83], v188 offset:3072
	v_add_f32_e32 v132, v94, v132
	v_add_f32_e32 v132, v95, v132
	v_add_f32_e32 v132, 0, v132
	v_cvt_pk_bf16_f32 v146, v92, v93
	s_waitcnt lgkmcnt(0)
	v_mfma_f32_32x32x16_bf16 v[64:79], v[128:131], v[80:83], v[64:79]
	v_cvt_pk_bf16_f32 v147, v94, v95
	v_lshl_add_u64 v[80:81], v[170:171], 0, s[62:63]
	s_mov_b32 s16, m0
	s_mov_b32 m0, s17
	s_nop 0
	global_load_lds_dwordx4 v[80:81], off
	s_mov_b32 m0, s16
	v_lshl_add_u64 v[80:81], v[172:173], 0, s[62:63]
	s_mov_b32 s16, m0
	s_mov_b32 m0, s35
	s_nop 0
	global_load_lds_dwordx4 v[80:81], off
	s_mov_b32 m0, s16
	v_add_f32_e32 v174, v174, v132
	v_mfma_f32_32x32x16_bf16 v[48:63], v[156:159], v[178:181], v[48:63]
	ds_read_b64_tr_b16 v[92:93], v177 offset:40960
	ds_read_b64_tr_b16 v[94:95], v177 offset:41472
	v_exp_f32_e32 v112, v112
	v_exp_f32_e32 v113, v113
	v_mfma_f32_32x32x16_bf16 v[32:47], v[156:159], v[96:99], v[32:47]
	ds_read_b64_tr_b16 v[170:171], v177 offset:45056
	ds_read_b64_tr_b16 v[172:173], v177 offset:45568
	v_exp_f32_e32 v114, v114
	v_exp_f32_e32 v115, v115
	ds_read_b128 v[80:83], v189 offset:8192
	ds_read_b128 v[96:99], v189 offset:8704
	v_mfma_f32_32x32x16_bf16 v[48:63], v[152:155], v[100:103], v[48:63]
	ds_read_b64_tr_b16 v[178:179], v177 offset:41984
	ds_read_b64_tr_b16 v[180:181], v177 offset:42496
	v_exp_f32_e32 v116, v116
	v_exp_f32_e32 v117, v117
	ds_read_b128 v[164:167], v189 offset:10240
	ds_read_b128 v[140:143], v189 offset:10752
	v_mfma_f32_32x32x16_bf16 v[32:47], v[152:155], v[104:107], v[32:47]
	ds_read_b64_tr_b16 v[100:101], v177 offset:46080
	ds_read_b64_tr_b16 v[102:103], v177 offset:46592
	v_exp_f32_e32 v118, v118
	v_exp_f32_e32 v119, v119
	ds_read_b128 v[160:163], v189 offset:12288
	ds_read_b128 v[132:135], v189 offset:12800
	v_mfma_f32_32x32x16_bf16 v[48:63], v[148:151], v[108:111], v[48:63]
	ds_read_b64_tr_b16 v[104:105], v177 offset:43008
	ds_read_b64_tr_b16 v[106:107], v177 offset:43520
	v_exp_f32_e32 v120, v120
	v_exp_f32_e32 v121, v121
	ds_read_b128 v[136:139], v189 offset:14336
	ds_read_b128 v[128:131], v189 offset:14848
	v_mfma_f32_32x32x16_bf16 v[32:47], v[148:151], v[190:193], v[32:47]
	ds_read_b64_tr_b16 v[108:109], v177 offset:47104
	ds_read_b64_tr_b16 v[110:111], v177 offset:47616
	v_exp_f32_e32 v122, v122
	v_exp_f32_e32 v123, v123
	v_mfma_f32_32x32x16_bf16 v[48:63], v[144:147], v[84:87], v[48:63]
	ds_read_b64_tr_b16 v[190:191], v177 offset:44032
	ds_read_b64_tr_b16 v[192:193], v177 offset:44544
	v_exp_f32_e32 v124, v124
	v_exp_f32_e32 v125, v125
	v_mfma_f32_32x32x16_bf16 v[32:47], v[144:147], v[88:91], v[32:47]
	ds_read_b64_tr_b16 v[84:85], v177 offset:48128
	ds_read_b64_tr_b16 v[86:87], v177 offset:48640
	v_exp_f32_e32 v126, v126
	v_exp_f32_e32 v127, v127
	s_waitcnt lgkmcnt(14)
	v_mfma_f32_32x32x16_bf16 v[16:31], v[156:159], v[92:95], v[16:31]
	v_exp_f32_e32 v64, v64
	v_exp_f32_e32 v65, v65
	v_mfma_f32_32x32x16_bf16 v[0:15], v[156:159], v[170:173], v[0:15]
	v_exp_f32_e32 v66, v66
	v_exp_f32_e32 v67, v67
	v_mfma_f32_32x32x16_bf16 v[16:31], v[152:155], v[178:181], v[16:31]
	v_exp_f32_e32 v68, v68
	v_exp_f32_e32 v69, v69
	s_waitcnt lgkmcnt(12)
	v_mfma_f32_32x32x16_bf16 v[0:15], v[152:155], v[100:103], v[0:15]
	v_exp_f32_e32 v70, v70
	v_exp_f32_e32 v71, v71
	s_waitcnt lgkmcnt(8)
	v_mfma_f32_32x32x16_bf16 v[16:31], v[148:151], v[104:107], v[16:31]
	v_exp_f32_e32 v72, v72
	v_exp_f32_e32 v73, v73
	s_waitcnt lgkmcnt(4)
	v_mfma_f32_32x32x16_bf16 v[0:15], v[148:151], v[108:111], v[0:15]
	v_exp_f32_e32 v74, v74
	v_exp_f32_e32 v75, v75
	s_waitcnt lgkmcnt(2)
	v_mfma_f32_32x32x16_bf16 v[16:31], v[144:147], v[190:193], v[16:31]
	v_exp_f32_e32 v76, v76
	v_exp_f32_e32 v77, v77
	s_waitcnt lgkmcnt(0)
	v_mfma_f32_32x32x16_bf16 v[0:15], v[144:147], v[84:87], v[0:15]
	v_exp_f32_e32 v78, v78
	v_exp_f32_e32 v79, v79
	s_waitcnt vmcnt(0) lgkmcnt(0)
	s_barrier
; #define WAIT_BAR(N) asm volatile("s_waitcnt vmcnt(" #N ") lgkmcnt(0)\n\ts_barrier":::"memory")
;   #define RESC() do{ if(!NOMAX&&resc){ asm volatile("s_waitcnt lgkmcnt(0)":::"memory"); \
;       _Pragma("unroll") for(int d_=0;d_<2*VM;++d_) _Pragma("unroll") for(int r=0;r<16;++r)o[d_][r]*=wsf[crow(r,hi)]; } }while(0)
;   #define ROT() do{sl_prev=sl_cur;sl_cur=sl_next;sl_next=(sl_next==(NSLOT-1)*SLOTB)?0:sl_next+SLOTB;}while(0)
;   #define ENDW(tt) do{ if((tt)+3<NT){ if constexpr(VM==2){WAIT_BAR(3);}else{WAIT_BAR(2);} } else if((tt)+2<NT){ if constexpr(VM==2){WAIT_BAR(2);}else{WAIT_BAR(1);} } else {WAIT_BAR(0);} }while(0)
; template<int THRL,int VM,bool NOMAX> __device__ __forceinline__ void attn_unit(const bf16*Qb,const bf16*__restrict__ Kh,const bf16*__restrict__ Vh,bf16*Ob,const int NT,const int sp,float*wscr,char*shm){
;     ...
;   int t=1;
;   for(;t+5<NT;t+=2){
;     STEP(pB0,pB1,pA0,pA1,t,true,true,true);     if constexpr(VM==2){WAIT_BAR(3);}else{WAIT_BAR(2);} RESC(); ROT();
;     STEP(pA0,pA1,pB0,pB1,t+1,true,true,true);   if constexpr(VM==2){WAIT_BAR(3);}else{WAIT_BAR(2);} RESC(); ROT();
;   }
;     ...
;   for(;t+1<NT;t+=2){
;     STEP(pB0,pB1,pA0,pA1,t,(t+3<NT),(t+1<NT),(t+1<NT));       ENDW(t);   RESC(); ROT();
;     STEP(pA0,pA1,pB0,pB1,t+1,(t+4<NT),(t+2<NT),(t+2<NT));     ENDW(t+1); RESC(); ROT();
;   }
;   STEP(pB0,pB1,pA0,pA1,NT-1,false,false,false); RESC();
	ds_read_b64_tr_b16 v[170:171], v168 offset:24576
	ds_read_b64_tr_b16 v[172:173], v168 offset:25088
	v_add_f32_e32 v88, v112, v113
	ds_read_b128 v[84:87], v188
	v_add_f32_e32 v88, v114, v88
	v_add_f32_e32 v88, v115, v88
	v_add_f32_e32 v88, v116, v88
	v_add_f32_e32 v104, v117, v88
	v_cvt_pk_bf16_f32 v156, v112, v113
	v_cvt_pk_bf16_f32 v157, v114, v115
	s_waitcnt lgkmcnt(0)
	v_mfma_f32_32x32x16_bf16 v[80:95], v[80:83], v[84:87], 0
	ds_read_b64_tr_b16 v[112:113], v168 offset:28672
	ds_read_b64_tr_b16 v[114:115], v168 offset:29184
	ds_read_b128 v[100:103], v188
	v_add_f32_e32 v104, v118, v104
	v_add_f32_e32 v104, v119, v104
	v_add_f32_e32 v104, v120, v104
	v_add_f32_e32 v144, v121, v104
	v_cvt_pk_bf16_f32 v158, v116, v117
	v_cvt_pk_bf16_f32 v159, v118, v119
	s_waitcnt lgkmcnt(0)
	v_mfma_f32_32x32x16_bf16 v[96:111], v[96:99], v[100:103], 0
	ds_read_b64_tr_b16 v[116:117], v168 offset:25600
	ds_read_b64_tr_b16 v[118:119], v168 offset:26112
	ds_read_b128 v[178:181], v188 offset:1024
	v_add_f32_e32 v144, v122, v144
	v_add_f32_e32 v144, v123, v144
	v_add_f32_e32 v144, v124, v144
	v_add_f32_e32 v144, v125, v144
	v_cvt_pk_bf16_f32 v152, v120, v121
	v_cvt_pk_bf16_f32 v153, v122, v123
	s_waitcnt lgkmcnt(0)
	v_mfma_f32_32x32x16_bf16 v[80:95], v[164:167], v[178:181], v[80:95]
	ds_read_b64_tr_b16 v[120:121], v168 offset:29696
	ds_read_b64_tr_b16 v[122:123], v168 offset:30208
	ds_read_b128 v[164:167], v188 offset:1024
	v_add_f32_e32 v144, v126, v144
	v_add_f32_e32 v144, v127, v144
	v_add_f32_e32 v144, v64, v144
	v_add_f32_e32 v144, v65, v144
	v_cvt_pk_bf16_f32 v154, v124, v125
	v_cvt_pk_bf16_f32 v155, v126, v127
	s_waitcnt lgkmcnt(0)
	v_mfma_f32_32x32x16_bf16 v[96:111], v[140:143], v[164:167], v[96:111]
	ds_read_b64_tr_b16 v[124:125], v168 offset:26624
	ds_read_b64_tr_b16 v[126:127], v168 offset:27136
	ds_read_b128 v[140:143], v188 offset:2048
	v_add_f32_e32 v144, v66, v144
	v_add_f32_e32 v144, v67, v144
	v_add_f32_e32 v144, v68, v144
	v_add_f32_e32 v144, v69, v144
	v_cvt_pk_bf16_f32 v148, v64, v65
	v_cvt_pk_bf16_f32 v149, v66, v67
	s_waitcnt lgkmcnt(0)
	v_mfma_f32_32x32x16_bf16 v[80:95], v[160:163], v[140:143], v[80:95]
	ds_read_b64_tr_b16 v[64:65], v168 offset:30720
	ds_read_b64_tr_b16 v[66:67], v168 offset:31232
	ds_read_b128 v[140:143], v188 offset:2048
	v_add_f32_e32 v144, v70, v144
	v_add_f32_e32 v144, v71, v144
	v_add_f32_e32 v144, v72, v144
	v_add_f32_e32 v144, v73, v144
	v_cvt_pk_bf16_f32 v150, v68, v69
	v_cvt_pk_bf16_f32 v151, v70, v71
	s_waitcnt lgkmcnt(0)
	v_mfma_f32_32x32x16_bf16 v[96:111], v[132:135], v[140:143], v[96:111]
	ds_read_b64_tr_b16 v[68:69], v168 offset:27648
	ds_read_b64_tr_b16 v[70:71], v168 offset:28160
	ds_read_b128 v[132:135], v188 offset:3072
	v_add_f32_e32 v140, v74, v144
	v_add_f32_e32 v140, v75, v140
	v_add_f32_e32 v140, v76, v140
	v_add_f32_e32 v140, v77, v140
	v_cvt_pk_bf16_f32 v144, v72, v73
	v_cvt_pk_bf16_f32 v145, v74, v75
	s_waitcnt lgkmcnt(0)
	v_mfma_f32_32x32x16_bf16 v[80:95], v[136:139], v[132:135], v[80:95]
	ds_read_b64_tr_b16 v[72:73], v168 offset:31744
	ds_read_b64_tr_b16 v[74:75], v168 offset:32256
	ds_read_b128 v[132:135], v188 offset:3072
	v_add_f32_e32 v136, v78, v140
	v_add_f32_e32 v136, v79, v136
	v_add_f32_e32 v136, 0, v136
	v_cvt_pk_bf16_f32 v146, v76, v77
	v_cvt_pk_bf16_f32 v147, v78, v79
	s_waitcnt lgkmcnt(0)
	v_mfma_f32_32x32x16_bf16 v[96:111], v[128:131], v[132:135], v[96:111]
	v_mfma_f32_32x32x16_bf16 v[48:63], v[156:159], v[170:173], v[48:63]
	ds_read_b64_tr_b16 v[76:77], v168 offset:32768
	ds_read_b64_tr_b16 v[78:79], v168 offset:33280
	v_exp_f32_e32 v80, v80
	v_exp_f32_e32 v81, v81
	v_mfma_f32_32x32x16_bf16 v[32:47], v[156:159], v[112:115], v[32:47]
	ds_read_b64_tr_b16 v[128:129], v168 offset:36864
	ds_read_b64_tr_b16 v[130:131], v168 offset:37376
	v_exp_f32_e32 v82, v82
	v_exp_f32_e32 v83, v83
	v_mfma_f32_32x32x16_bf16 v[48:63], v[152:155], v[116:119], v[48:63]
	ds_read_b64_tr_b16 v[112:113], v168 offset:33792
	ds_read_b64_tr_b16 v[114:115], v168 offset:34304
	v_exp_f32_e32 v84, v84
	v_exp_f32_e32 v85, v85
	v_mfma_f32_32x32x16_bf16 v[32:47], v[152:155], v[120:123], v[32:47]
	ds_read_b64_tr_b16 v[116:117], v168 offset:37888
	ds_read_b64_tr_b16 v[118:119], v168 offset:38400
	v_exp_f32_e32 v86, v86
	v_exp_f32_e32 v87, v87
	v_mfma_f32_32x32x16_bf16 v[48:63], v[148:151], v[124:127], v[48:63]
	ds_read_b64_tr_b16 v[120:121], v168 offset:34816
	ds_read_b64_tr_b16 v[122:123], v168 offset:35328
	v_exp_f32_e32 v88, v88
	v_exp_f32_e32 v89, v89
	v_mfma_f32_32x32x16_bf16 v[32:47], v[148:151], v[64:67], v[32:47]
	ds_read_b64_tr_b16 v[124:125], v168 offset:38912
	ds_read_b64_tr_b16 v[126:127], v168 offset:39424
	v_exp_f32_e32 v90, v90
	v_exp_f32_e32 v91, v91
	v_mfma_f32_32x32x16_bf16 v[48:63], v[144:147], v[68:71], v[48:63]
	ds_read_b64_tr_b16 v[64:65], v168 offset:35840
	ds_read_b64_tr_b16 v[66:67], v168 offset:36352
	v_exp_f32_e32 v92, v92
	v_exp_f32_e32 v93, v93
	v_mfma_f32_32x32x16_bf16 v[32:47], v[144:147], v[72:75], v[32:47]
	ds_read_b64_tr_b16 v[68:69], v168 offset:39936
	ds_read_b64_tr_b16 v[70:71], v168 offset:40448
	v_exp_f32_e32 v94, v94
	v_exp_f32_e32 v95, v95
	s_waitcnt lgkmcnt(14)
	v_mfma_f32_32x32x16_bf16 v[16:31], v[156:159], v[76:79], v[16:31]
	v_exp_f32_e32 v96, v96
	v_exp_f32_e32 v97, v97
	s_waitcnt lgkmcnt(12)
; #define SBAR() __builtin_amdgcn_sched_barrier(0)
; #define WAIT_BAR(N) asm volatile("s_waitcnt vmcnt(" #N ") lgkmcnt(0)\n\ts_barrier":::"memory")
;   #define RESC() do{ if(!NOMAX&&resc){ asm volatile("s_waitcnt lgkmcnt(0)":::"memory"); \
;       _Pragma("unroll") for(int d_=0;d_<2*VM;++d_) _Pragma("unroll") for(int r=0;r<16;++r)o[d_][r]*=wsf[crow(r,hi)]; } }while(0)
;   #define ROT() do{sl_prev=sl_cur;sl_cur=sl_next;sl_next=(sl_next==(NSLOT-1)*SLOTB)?0:sl_next+SLOTB;}while(0)
;   #define PKW(P,B) cvtpk_s(P[B],P[B+1])
;   #define ENDW(tt) do{ if((tt)+3<NT){ if constexpr(VM==2){WAIT_BAR(3);}else{WAIT_BAR(2);} } else if((tt)+2<NT){ if constexpr(VM==2){WAIT_BAR(2);}else{WAIT_BAR(1);} } else {WAIT_BAR(0);} }while(0)
; template<int THRL,int VM,bool NOMAX> __device__ __forceinline__ void attn_unit(const bf16*Qb,const bf16*__restrict__ Kh,const bf16*__restrict__ Vh,bf16*Ob,const int NT,const int sp,float*wscr,char*shm){
;     ...
;   int t=1;
;   for(;t+5<NT;t+=2){
;     STEP(pB0,pB1,pA0,pA1,t,true,true,true);     if constexpr(VM==2){WAIT_BAR(3);}else{WAIT_BAR(2);} RESC(); ROT();
;     STEP(pA0,pA1,pB0,pB1,t+1,true,true,true);   if constexpr(VM==2){WAIT_BAR(3);}else{WAIT_BAR(2);} RESC(); ROT();
;   }
;     ...
;   for(;t+1<NT;t+=2){
;     STEP(pB0,pB1,pA0,pA1,t,(t+3<NT),(t+1<NT),(t+1<NT));       ENDW(t);   RESC(); ROT();
;     STEP(pA0,pA1,pB0,pB1,t+1,(t+4<NT),(t+2<NT),(t+2<NT));     ENDW(t+1); RESC(); ROT();
;   }
;   STEP(pB0,pB1,pA0,pA1,NT-1,false,false,false); RESC();
;   { float sacc=pB0[0]+pB0[1]; _Pragma("unroll") for(int r=2;r<16;++r)sacc+=pB0[r]; _Pragma("unroll") for(int r=0;r<16;++r)sacc+=pB1[r]; l_reg+=sacc;
;     pw0=(u32x4){PKW(pB0,0),PKW(pB0,2),PKW(pB0,4),PKW(pB0,6)};pw1=(u32x4){PKW(pB0,8),PKW(pB0,10),PKW(pB0,12),PKW(pB0,14)};pw2=(u32x4){PKW(pB1,0),PKW(pB1,2),PKW(pB1,4),PKW(pB1,6)};pw3=(u32x4){PKW(pB1,8),PKW(pB1,10),PKW(pB1,12),PKW(pB1,14)};
;     SBAR(); pv(o,vb0+VM*sl_cur,PAF(0),PAF(1),PAF(2),PAF(3)); if constexpr(VM==2) pv(o+2,vb0+VM*sl_cur+8192,PAF(0),PAF(1),PAF(2),PAF(3)); }
;     ...
;   {auto rr=__builtin_amdgcn_permlane32_swap(__float_as_uint(l_reg),__float_as_uint(l_reg),false,false);l_reg=__uint_as_float(rr[0])+__uint_as_float(rr[1]);}
;   if(hi==0)wsf[32+r32]=l_reg;asm volatile("s_waitcnt lgkmcnt(0)":::"memory");
	v_mfma_f32_32x32x16_bf16 v[0:15], v[156:159], v[128:131], v[0:15]
	v_exp_f32_e32 v98, v98
	v_exp_f32_e32 v99, v99
	s_waitcnt lgkmcnt(10)
	v_mfma_f32_32x32x16_bf16 v[16:31], v[152:155], v[112:115], v[16:31]
	v_exp_f32_e32 v100, v100
	v_exp_f32_e32 v101, v101
	s_waitcnt lgkmcnt(8)
	v_mfma_f32_32x32x16_bf16 v[0:15], v[152:155], v[116:119], v[0:15]
	v_exp_f32_e32 v102, v102
	v_exp_f32_e32 v103, v103
	s_waitcnt lgkmcnt(6)
	v_mfma_f32_32x32x16_bf16 v[16:31], v[148:151], v[120:123], v[16:31]
	v_exp_f32_e32 v104, v104
	v_exp_f32_e32 v105, v105
	s_waitcnt lgkmcnt(4)
	v_mfma_f32_32x32x16_bf16 v[0:15], v[148:151], v[124:127], v[0:15]
	v_exp_f32_e32 v106, v106
	v_exp_f32_e32 v107, v107
	s_waitcnt lgkmcnt(2)
	v_mfma_f32_32x32x16_bf16 v[16:31], v[144:147], v[64:67], v[16:31]
	v_exp_f32_e32 v108, v108
	v_exp_f32_e32 v109, v109
	s_waitcnt lgkmcnt(0)
	v_mfma_f32_32x32x16_bf16 v[0:15], v[144:147], v[68:71], v[0:15]
	v_exp_f32_e32 v110, v110
	v_exp_f32_e32 v111, v111
	v_add_f32_e32 v64, v80, v81
	v_add_f32_e32 v64, v82, v64
	v_add_f32_e32 v64, v83, v64
	v_add_f32_e32 v64, v84, v64
	v_add_f32_e32 v64, v85, v64
	v_add_f32_e32 v64, v86, v64
	v_add_f32_e32 v64, v87, v64
	v_add_f32_e32 v64, v88, v64
	v_add_f32_e32 v64, v89, v64
	v_add_f32_e32 v64, v90, v64
	v_add_f32_e32 v64, v91, v64
	v_add_f32_e32 v64, v92, v64
	v_add_f32_e32 v64, v93, v64
	v_add_f32_e32 v64, v94, v64
	v_add_f32_e32 v64, v95, v64
	v_add_f32_e32 v64, v64, v96
	v_add_f32_e32 v64, v97, v64
	v_add_f32_e32 v64, v98, v64
	v_add_f32_e32 v64, v99, v64
	v_add_f32_e32 v64, v100, v64
	v_add_f32_e32 v64, v101, v64
	v_add_f32_e32 v64, v102, v64
	v_add_f32_e32 v64, v103, v64
	v_add_f32_e32 v64, v104, v64
	v_add_f32_e32 v64, v105, v64
	v_add_f32_e32 v64, v106, v64
	v_add_f32_e32 v64, v107, v64
	v_add_f32_e32 v64, v108, v64
	v_add_f32_e32 v64, v109, v64
	v_add_f32_e32 v64, v110, v64
	v_add_f32_e32 v64, v111, v64
	v_add_f32_e32 v65, v174, v136
	v_add_f32_e32 v64, v65, v64
	v_cvt_pk_bf16_f32 v66, v80, v81
	v_cvt_pk_bf16_f32 v67, v82, v83
	v_cvt_pk_bf16_f32 v68, v84, v85
	v_cvt_pk_bf16_f32 v69, v86, v87
	v_cvt_pk_bf16_f32 v70, v88, v89
	v_cvt_pk_bf16_f32 v71, v90, v91
	v_cvt_pk_bf16_f32 v72, v92, v93
	v_cvt_pk_bf16_f32 v73, v94, v95
	v_cvt_pk_bf16_f32 v74, v96, v97
	v_cvt_pk_bf16_f32 v75, v98, v99
	v_cvt_pk_bf16_f32 v76, v100, v101
	v_cvt_pk_bf16_f32 v77, v102, v103
	v_cvt_pk_bf16_f32 v78, v104, v105
	v_cvt_pk_bf16_f32 v79, v106, v107
	v_cvt_pk_bf16_f32 v80, v108, v109
	v_cvt_pk_bf16_f32 v81, v110, v111
	v_add_u32_e32 v65, 0x4000, v176
	ds_read_b64_tr_b16 v[82:83],v65 offset:0
	ds_read_b64_tr_b16 v[84:85],v65 offset:512
	ds_read_b64_tr_b16 v[86:87],v65 offset:1024
	ds_read_b64_tr_b16 v[88:89],v65 offset:1536
	ds_read_b64_tr_b16 v[90:91],v65 offset:2048
	ds_read_b64_tr_b16 v[92:93],v65 offset:2560
	ds_read_b64_tr_b16 v[94:95],v65 offset:3072
	ds_read_b64_tr_b16 v[96:97],v65 offset:3584
	s_waitcnt lgkmcnt(0)
	s_nop 0
	v_mfma_f32_32x32x16_bf16 v[48:63], v[66:69], v[82:85], v[48:63]
	ds_read_b64_tr_b16 v[82:83],v65 offset:4096
	ds_read_b64_tr_b16 v[84:85],v65 offset:4608
	v_mfma_f32_32x32x16_bf16 v[48:63], v[70:73], v[86:89], v[48:63]
	ds_read_b64_tr_b16 v[86:87],v65 offset:5120
	ds_read_b64_tr_b16 v[88:89],v65 offset:5632
	v_mfma_f32_32x32x16_bf16 v[48:63], v[74:77], v[90:93], v[48:63]
	ds_read_b64_tr_b16 v[90:91],v65 offset:6144
	ds_read_b64_tr_b16 v[92:93],v65 offset:6656
	ds_read_b64_tr_b16 v[98:99],v65 offset:7168
	ds_read_b64_tr_b16 v[100:101],v65 offset:7680
	s_waitcnt lgkmcnt(0)
	v_mfma_f32_32x32x16_bf16 v[48:63], v[78:81], v[94:97], v[48:63]
	v_mfma_f32_32x32x16_bf16 v[32:47], v[66:69], v[82:85], v[32:47]
	v_add_u32_e32 v65, 0x6000, v176
	ds_read_b64_tr_b16 v[82:83],v65 offset:0
	ds_read_b64_tr_b16 v[84:85],v65 offset:512
	v_mfma_f32_32x32x16_bf16 v[32:47], v[70:73], v[86:89], v[32:47]
	ds_read_b64_tr_b16 v[86:87],v65 offset:1024
	ds_read_b64_tr_b16 v[88:89],v65 offset:1536
	v_mfma_f32_32x32x16_bf16 v[32:47], v[74:77], v[90:93], v[32:47]
	ds_read_b64_tr_b16 v[90:91],v65 offset:2048
	ds_read_b64_tr_b16 v[92:93],v65 offset:2560
	ds_read_b64_tr_b16 v[94:95],v65 offset:3072
	ds_read_b64_tr_b16 v[96:97],v65 offset:3584
	s_waitcnt lgkmcnt(0)
	v_mfma_f32_32x32x16_bf16 v[32:47], v[78:81], v[98:101], v[32:47]
	v_mfma_f32_32x32x16_bf16 v[16:31], v[66:69], v[82:85], v[16:31]
	ds_read_b64_tr_b16 v[82:83],v65 offset:4096
	ds_read_b64_tr_b16 v[84:85],v65 offset:4608
	v_mfma_f32_32x32x16_bf16 v[16:31], v[70:73], v[86:89], v[16:31]
	ds_read_b64_tr_b16 v[86:87],v65 offset:5120
	ds_read_b64_tr_b16 v[88:89],v65 offset:5632
	v_mfma_f32_32x32x16_bf16 v[16:31], v[74:77], v[90:93], v[16:31]
	ds_read_b64_tr_b16 v[90:91],v65 offset:6144
	ds_read_b64_tr_b16 v[92:93],v65 offset:6656
	ds_read_b64_tr_b16 v[98:99],v65 offset:7168
	ds_read_b64_tr_b16 v[100:101],v65 offset:7680
	s_waitcnt lgkmcnt(0)
	v_mfma_f32_32x32x16_bf16 v[16:31], v[78:81], v[94:97], v[16:31]
	v_mfma_f32_32x32x16_bf16 v[0:15], v[66:69], v[82:85], v[0:15]
	v_mov_b32_e32 v65, v64
	s_nop 1
	v_permlane32_swap_b32_e32 v64, v65
	v_cmp_gt_u32_e32 vcc, 32, v187
	v_mfma_f32_32x32x16_bf16 v[0:15], v[70:73], v[86:89], v[0:15]
	v_mfma_f32_32x32x16_bf16 v[0:15], v[74:77], v[90:93], v[0:15]
	v_mfma_f32_32x32x16_bf16 v[0:15], v[78:81], v[98:101], v[0:15]
	s_and_saveexec_b64 s[16:17], vcc
	s_cbranch_execz .LBB0_859
	v_add_f32_e32 v64, v64, v65
	v_lshl_add_u32 v65, v186, 2, s34
	ds_write_b32 v65, v64 offset:128
	s_branch .LBB0_859

; #define WAIT_BAR(N) asm volatile("s_waitcnt vmcnt(" #N ") lgkmcnt(0)\n\ts_barrier":::"memory")
;   #define RESC() do{ if(!NOMAX&&resc){ asm volatile("s_waitcnt lgkmcnt(0)":::"memory"); \
;       _Pragma("unroll") for(int d_=0;d_<2*VM;++d_) _Pragma("unroll") for(int r=0;r<16;++r)o[d_][r]*=wsf[crow(r,hi)]; } }while(0)
;   #define ROT() do{sl_prev=sl_cur;sl_cur=sl_next;sl_next=(sl_next==(NSLOT-1)*SLOTB)?0:sl_next+SLOTB;}while(0)
; template<int THRL,int VM,bool NOMAX> __device__ __forceinline__ void attn_unit(const bf16*Qb,const bf16*__restrict__ Kh,const bf16*__restrict__ Vh,bf16*Ob,const int NT,const int sp,float*wscr,char*shm){
;     ...
;   int t=1;
;   for(;t+5<NT;t+=2){
;     STEP(pB0,pB1,pA0,pA1,t,true,true,true);     if constexpr(VM==2){WAIT_BAR(3);}else{WAIT_BAR(2);} RESC(); ROT();
;     STEP(pA0,pA1,pB0,pB1,t+1,true,true,true);   if constexpr(VM==2){WAIT_BAR(3);}else{WAIT_BAR(2);} RESC(); ROT();
;   }
.LBB0_874:
	v_mfma_f32_32x32x16_bf16 v[112:127], v[100:103], v[218:221], 0
	v_lshl_add_u32 v206, s89, 1, v188
	ds_read_b64_tr_b16 v[194:195], v206 offset:24576
	ds_read_b64_tr_b16 v[196:197], v206 offset:25088
	v_add_f32_e32 v108, v80, v81
	v_add_f32_e32 v108, v82, v108
	v_add_f32_e32 v108, v83, v108
	v_add_f32_e32 v108, v84, v108
	v_add_f32_e32 v108, v85, v108
	v_cvt_pk_bf16_f32 v156, v80, v81
	v_cvt_pk_bf16_f32 v157, v82, v83
	ds_read_b64_tr_b16 v[80:81], v206 offset:28672
	ds_read_b64_tr_b16 v[82:83], v206 offset:29184
	v_add_f32_e32 v104, v86, v108
	v_add_f32_e32 v104, v87, v104
	v_add_f32_e32 v104, v88, v104
	v_add_f32_e32 v144, v89, v104
	v_mfma_f32_32x32x16_bf16 v[96:111], v[96:99], v[218:221], 0
	v_cvt_pk_bf16_f32 v158, v84, v85
	v_cvt_pk_bf16_f32 v159, v86, v87
	ds_read_b64_tr_b16 v[84:85], v206 offset:25600
	ds_read_b64_tr_b16 v[86:87], v206 offset:26112
	v_add_f32_e32 v144, v90, v144
	v_add_f32_e32 v144, v91, v144
	v_add_f32_e32 v144, v92, v144
	v_add_f32_e32 v144, v93, v144
	v_cvt_pk_bf16_f32 v152, v88, v89
	v_cvt_pk_bf16_f32 v153, v90, v91
	v_mfma_f32_32x32x16_bf16 v[112:127], v[164:167], v[222:225], v[112:127]
	ds_read_b64_tr_b16 v[88:89], v206 offset:29696
	ds_read_b64_tr_b16 v[90:91], v206 offset:30208
	v_add_f32_e32 v144, v94, v144
	v_add_f32_e32 v144, v95, v144
	v_add_f32_e32 v144, v64, v144
	v_add_f32_e32 v144, v65, v144
	v_mfma_f32_32x32x16_bf16 v[96:111], v[160:163], v[222:225], v[96:111]
	v_cvt_pk_bf16_f32 v154, v92, v93
	v_cvt_pk_bf16_f32 v155, v94, v95
	ds_read_b64_tr_b16 v[92:93], v206 offset:26624
	ds_read_b64_tr_b16 v[94:95], v206 offset:27136
	v_add_f32_e32 v144, v66, v144
	v_add_f32_e32 v144, v67, v144
	v_add_f32_e32 v144, v68, v144
	v_add_f32_e32 v144, v69, v144
	v_cvt_pk_bf16_f32 v148, v64, v65
	v_cvt_pk_bf16_f32 v149, v66, v67
	v_mfma_f32_32x32x16_bf16 v[112:127], v[140:143], v[226:229], v[112:127]
	ds_read_b64_tr_b16 v[198:199], v206 offset:30720
	ds_read_b64_tr_b16 v[200:201], v206 offset:31232
	v_add_f32_e32 v140, v70, v144
	v_add_f32_e32 v140, v71, v140
	v_add_f32_e32 v140, v72, v140
	v_add_f32_e32 v140, v73, v140
	v_mfma_f32_32x32x16_bf16 v[96:111], v[136:139], v[226:229], v[96:111]
	v_cvt_pk_bf16_f32 v150, v68, v69
	v_cvt_pk_bf16_f32 v151, v70, v71
	ds_read_b64_tr_b16 v[202:203], v206 offset:27648
	ds_read_b64_tr_b16 v[204:205], v206 offset:28160
	v_add_f32_e32 v68, v74, v140
	v_add_f32_e32 v68, v75, v68
	v_add_f32_e32 v68, v76, v68
	v_add_f32_e32 v68, v77, v68
	v_cvt_pk_bf16_f32 v144, v72, v73
	v_cvt_pk_bf16_f32 v145, v74, v75
	v_mfma_f32_32x32x16_bf16 v[112:127], v[132:135], v[230:233], v[112:127]
	ds_read_b64_tr_b16 v[72:73], v206 offset:31744
	ds_read_b64_tr_b16 v[74:75], v206 offset:32256
	v_add_f32_e32 v68, v78, v68
	v_add_f32_e32 v68, v79, v68
	v_add_f32_e32 v68, 0, v68
	v_cvt_pk_bf16_f32 v146, v76, v77
	v_mfma_f32_32x32x16_bf16 v[96:111], v[128:131], v[230:233], v[96:111]
	v_cvt_pk_bf16_f32 v147, v78, v79
	s_add_i32 s88, s87, s17
	v_lshl_add_u64 v[64:65], v[180:181], 0, s[56:57]
	s_mov_b32 s89, m0
	s_mov_b32 m0, s88
	s_nop 0
	global_load_lds_dwordx4 v[64:65], off
	s_mov_b32 m0, s89
	s_lshl_b32 s88, s86, 1
	v_lshl_add_u64 v[64:65], v[178:179], 0, s[56:57]
	s_add_i32 s88, s88, s16
	s_mov_b32 s89, m0
	s_mov_b32 m0, s88
	s_nop 0
	global_load_lds_dwordx4 v[64:65], off
	s_mov_b32 m0, s89
	v_lshl_add_u64 v[64:65], v[176:177], 0, s[56:57]
	s_addk_i32 s88, 0x2000
	s_mov_b32 s89, m0
	s_mov_b32 m0, s88
	s_nop 0
	global_load_lds_dwordx4 v[64:65], off
	s_mov_b32 m0, s89
	v_add_f32_e32 v193, v193, v68
	s_waitcnt lgkmcnt(12)
	v_mfma_f32_32x32x16_bf16 v[48:63], v[156:159], v[194:197], v[48:63]
	ds_read_b64_tr_b16 v[76:77], v206 offset:32768
	ds_read_b64_tr_b16 v[78:79], v206 offset:33280
	v_exp_f32_e32 v112, v112
	v_exp_f32_e32 v113, v113
	v_mfma_f32_32x32x16_bf16 v[32:47], v[156:159], v[80:83], v[32:47]
	ds_read_b64_tr_b16 v[194:195], v206 offset:36864
	ds_read_b64_tr_b16 v[196:197], v206 offset:37376
	v_exp_f32_e32 v114, v114
	v_exp_f32_e32 v115, v115
	v_add_u32_e32 v128, s86, v189
	ds_read_b128 v[68:71], v128
	ds_read_b128 v[64:67], v128 offset:512
	s_waitcnt lgkmcnt(14)
	v_mfma_f32_32x32x16_bf16 v[48:63], v[152:155], v[84:87], v[48:63]
	ds_read_b64_tr_b16 v[80:81], v206 offset:33792
	ds_read_b64_tr_b16 v[82:83], v206 offset:34304
	v_exp_f32_e32 v116, v116
	v_exp_f32_e32 v117, v117
	ds_read_b128 v[164:167], v128 offset:2048
	ds_read_b128 v[140:143], v128 offset:2560
	v_mfma_f32_32x32x16_bf16 v[32:47], v[152:155], v[88:91], v[32:47]
	ds_read_b64_tr_b16 v[84:85], v206 offset:37888
	ds_read_b64_tr_b16 v[86:87], v206 offset:38400
	v_exp_f32_e32 v118, v118
	v_exp_f32_e32 v119, v119
	ds_read_b128 v[160:163], v128 offset:4096
	ds_read_b128 v[132:135], v128 offset:4608
	s_waitcnt lgkmcnt(14)
	v_mfma_f32_32x32x16_bf16 v[48:63], v[148:151], v[92:95], v[48:63]
	ds_read_b64_tr_b16 v[88:89], v206 offset:34816
	ds_read_b64_tr_b16 v[90:91], v206 offset:35328
	v_exp_f32_e32 v120, v120
	v_exp_f32_e32 v121, v121
	ds_read_b128 v[136:139], v128 offset:6144
	ds_read_b128 v[128:131], v128 offset:6656
	v_mfma_f32_32x32x16_bf16 v[32:47], v[148:151], v[198:201], v[32:47]
	ds_read_b64_tr_b16 v[92:93], v206 offset:38912
	ds_read_b64_tr_b16 v[94:95], v206 offset:39424
	v_exp_f32_e32 v122, v122
	v_exp_f32_e32 v123, v123
	s_waitcnt lgkmcnt(14)
	v_mfma_f32_32x32x16_bf16 v[48:63], v[144:147], v[202:205], v[48:63]
	ds_read_b64_tr_b16 v[198:199], v206 offset:35840
	ds_read_b64_tr_b16 v[200:201], v206 offset:36352
	v_exp_f32_e32 v124, v124
	v_exp_f32_e32 v125, v125
	v_mfma_f32_32x32x16_bf16 v[32:47], v[144:147], v[72:75], v[32:47]
	ds_read_b64_tr_b16 v[202:203], v206 offset:39936
	ds_read_b64_tr_b16 v[204:205], v206 offset:40448
	v_exp_f32_e32 v126, v126
	v_exp_f32_e32 v127, v127
	s_waitcnt lgkmcnt(14)
	v_mfma_f32_32x32x16_bf16 v[16:31], v[156:159], v[76:79], v[16:31]
	v_exp_f32_e32 v96, v96
	v_exp_f32_e32 v97, v97
	v_mfma_f32_32x32x16_bf16 v[0:15], v[156:159], v[194:197], v[0:15]
	v_exp_f32_e32 v98, v98
	v_exp_f32_e32 v99, v99
	v_mfma_f32_32x32x16_bf16 v[16:31], v[152:155], v[80:83], v[16:31]
	v_exp_f32_e32 v100, v100
	v_exp_f32_e32 v101, v101
	s_waitcnt lgkmcnt(12)
	v_mfma_f32_32x32x16_bf16 v[0:15], v[152:155], v[84:87], v[0:15]
	v_exp_f32_e32 v102, v102
	v_exp_f32_e32 v103, v103
	s_waitcnt lgkmcnt(8)
	v_mfma_f32_32x32x16_bf16 v[16:31], v[148:151], v[88:91], v[16:31]
	v_exp_f32_e32 v104, v104
	v_exp_f32_e32 v105, v105
	s_waitcnt lgkmcnt(4)
	v_mfma_f32_32x32x16_bf16 v[0:15], v[148:151], v[92:95], v[0:15]
	v_exp_f32_e32 v106, v106
	v_exp_f32_e32 v107, v107
	s_waitcnt lgkmcnt(2)
	v_mfma_f32_32x32x16_bf16 v[16:31], v[144:147], v[198:201], v[16:31]
	v_exp_f32_e32 v108, v108
	v_exp_f32_e32 v109, v109
	s_waitcnt lgkmcnt(0)
	v_mfma_f32_32x32x16_bf16 v[0:15], v[144:147], v[202:205], v[0:15]
	v_exp_f32_e32 v110, v110
	v_exp_f32_e32 v111, v111
	s_waitcnt vmcnt(3) lgkmcnt(0)
	s_barrier
; #define WAIT_BAR(N) asm volatile("s_waitcnt vmcnt(" #N ") lgkmcnt(0)\n\ts_barrier":::"memory")
;   #define RESC() do{ if(!NOMAX&&resc){ asm volatile("s_waitcnt lgkmcnt(0)":::"memory"); \
;       _Pragma("unroll") for(int d_=0;d_<2*VM;++d_) _Pragma("unroll") for(int r=0;r<16;++r)o[d_][r]*=wsf[crow(r,hi)]; } }while(0)
;   #define ROT() do{sl_prev=sl_cur;sl_cur=sl_next;sl_next=(sl_next==(NSLOT-1)*SLOTB)?0:sl_next+SLOTB;}while(0)
; template<int THRL,int VM,bool NOMAX> __device__ __forceinline__ void attn_unit(const bf16*Qb,const bf16*__restrict__ Kh,const bf16*__restrict__ Vh,bf16*Ob,const int NT,const int sp,float*wscr,char*shm){
;     ...
;   int t=1;
;   for(;t+5<NT;t+=2){
;     STEP(pB0,pB1,pA0,pA1,t,true,true,true);     if constexpr(VM==2){WAIT_BAR(3);}else{WAIT_BAR(2);} RESC(); ROT();
;     STEP(pA0,pA1,pB0,pB1,t+1,true,true,true);   if constexpr(VM==2){WAIT_BAR(3);}else{WAIT_BAR(2);} RESC(); ROT();
;   }
	v_mfma_f32_32x32x16_bf16 v[80:95], v[68:71], v[218:221], 0
	s_add_i32 s88, s86, 0x2000
	s_cmpk_lg_i32 s86, 0x4000
	s_cselect_b32 s88, s88, 0
	v_lshl_add_u32 v206, s87, 1, v188
	ds_read_b64_tr_b16 v[194:195], v206 offset:24576
	ds_read_b64_tr_b16 v[196:197], v206 offset:25088
	v_add_f32_e32 v76, v112, v113
	v_add_f32_e32 v76, v114, v76
	v_add_f32_e32 v76, v115, v76
	v_add_f32_e32 v76, v116, v76
	v_add_f32_e32 v76, v117, v76
	v_cvt_pk_bf16_f32 v156, v112, v113
	v_cvt_pk_bf16_f32 v157, v114, v115
	ds_read_b64_tr_b16 v[112:113], v206 offset:28672
	ds_read_b64_tr_b16 v[114:115], v206 offset:29184
	v_add_f32_e32 v72, v118, v76
	v_add_f32_e32 v72, v119, v72
	v_add_f32_e32 v72, v120, v72
	v_add_f32_e32 v144, v121, v72
	v_mfma_f32_32x32x16_bf16 v[64:79], v[64:67], v[218:221], 0
	v_cvt_pk_bf16_f32 v158, v116, v117
	v_cvt_pk_bf16_f32 v159, v118, v119
	ds_read_b64_tr_b16 v[116:117], v206 offset:25600
	ds_read_b64_tr_b16 v[118:119], v206 offset:26112
	v_add_f32_e32 v144, v122, v144
	v_add_f32_e32 v144, v123, v144
	v_add_f32_e32 v144, v124, v144
	v_add_f32_e32 v144, v125, v144
	v_mfma_f32_32x32x16_bf16 v[80:95], v[164:167], v[222:225], v[80:95]
	v_cvt_pk_bf16_f32 v152, v120, v121
	v_cvt_pk_bf16_f32 v153, v122, v123
	ds_read_b64_tr_b16 v[120:121], v206 offset:29696
	ds_read_b64_tr_b16 v[122:123], v206 offset:30208
	v_add_f32_e32 v144, v126, v144
	v_add_f32_e32 v144, v127, v144
	v_add_f32_e32 v144, v96, v144
	v_add_f32_e32 v144, v97, v144
	v_mfma_f32_32x32x16_bf16 v[64:79], v[140:143], v[222:225], v[64:79]
	v_cvt_pk_bf16_f32 v154, v124, v125
	v_cvt_pk_bf16_f32 v155, v126, v127
	ds_read_b64_tr_b16 v[124:125], v206 offset:26624
	ds_read_b64_tr_b16 v[126:127], v206 offset:27136
	v_add_f32_e32 v144, v98, v144
	v_add_f32_e32 v144, v99, v144
	v_add_f32_e32 v144, v100, v144
	v_add_f32_e32 v144, v101, v144
	v_mfma_f32_32x32x16_bf16 v[80:95], v[160:163], v[226:229], v[80:95]
	v_cvt_pk_bf16_f32 v148, v96, v97
	v_cvt_pk_bf16_f32 v149, v98, v99
	ds_read_b64_tr_b16 v[198:199], v206 offset:30720
	ds_read_b64_tr_b16 v[200:201], v206 offset:31232
	v_add_f32_e32 v140, v102, v144
	v_add_f32_e32 v140, v103, v140
	v_add_f32_e32 v140, v104, v140
	v_add_f32_e32 v140, v105, v140
	v_mfma_f32_32x32x16_bf16 v[64:79], v[132:135], v[226:229], v[64:79]
	v_cvt_pk_bf16_f32 v150, v100, v101
	v_cvt_pk_bf16_f32 v151, v102, v103
	ds_read_b64_tr_b16 v[202:203], v206 offset:27648
	ds_read_b64_tr_b16 v[204:205], v206 offset:28160
	v_add_f32_e32 v100, v106, v140
	v_add_f32_e32 v100, v107, v100
	v_add_f32_e32 v100, v108, v100
	v_add_f32_e32 v100, v109, v100
	v_mfma_f32_32x32x16_bf16 v[80:95], v[136:139], v[230:233], v[80:95]
	v_cvt_pk_bf16_f32 v144, v104, v105
	v_cvt_pk_bf16_f32 v145, v106, v107
	ds_read_b64_tr_b16 v[104:105], v206 offset:31744
	ds_read_b64_tr_b16 v[106:107], v206 offset:32256
	v_add_f32_e32 v100, v110, v100
	v_add_f32_e32 v100, v111, v100
	v_add_f32_e32 v100, 0, v100
	v_cvt_pk_bf16_f32 v146, v108, v109
	v_mfma_f32_32x32x16_bf16 v[64:79], v[128:131], v[230:233], v[64:79]
	v_cvt_pk_bf16_f32 v147, v110, v111
	s_add_i32 s87, s86, s17
	s_mov_b32 s89, m0
	s_mov_b32 m0, s87
	s_nop 0
	global_load_lds_dwordx4 v[180:181], off
	s_mov_b32 m0, s89
	s_lshl_b32 s87, s88, 1
	s_add_i32 s87, s87, s16
	s_mov_b32 s89, m0
	s_mov_b32 m0, s87
	s_nop 0
	global_load_lds_dwordx4 v[178:179], off
	s_mov_b32 m0, s89
	s_addk_i32 s87, 0x2000
	s_mov_b32 s89, m0
	s_mov_b32 m0, s87
	s_nop 0
	global_load_lds_dwordx4 v[176:177], off
	s_mov_b32 m0, s89
	v_add_f32_e32 v193, v193, v100
	s_waitcnt lgkmcnt(12)
	v_mfma_f32_32x32x16_bf16 v[48:63], v[156:159], v[194:197], v[48:63]
	ds_read_b64_tr_b16 v[108:109], v206 offset:32768
	ds_read_b64_tr_b16 v[110:111], v206 offset:33280
	v_exp_f32_e32 v80, v80
	v_exp_f32_e32 v81, v81
	v_mfma_f32_32x32x16_bf16 v[32:47], v[156:159], v[112:115], v[32:47]
	ds_read_b64_tr_b16 v[194:195], v206 offset:36864
	ds_read_b64_tr_b16 v[196:197], v206 offset:37376
	v_exp_f32_e32 v82, v82
	v_exp_f32_e32 v83, v83
	v_add_u32_e32 v128, s88, v189
	ds_read_b128 v[100:103], v128
	ds_read_b128 v[96:99], v128 offset:512
	s_waitcnt lgkmcnt(14)
	v_mfma_f32_32x32x16_bf16 v[48:63], v[152:155], v[116:119], v[48:63]
	ds_read_b64_tr_b16 v[112:113], v206 offset:33792
	ds_read_b64_tr_b16 v[114:115], v206 offset:34304
	v_exp_f32_e32 v84, v84
	v_exp_f32_e32 v85, v85
	ds_read_b128 v[164:167], v128 offset:2048
	ds_read_b128 v[160:163], v128 offset:2560
	v_mfma_f32_32x32x16_bf16 v[32:47], v[152:155], v[120:123], v[32:47]
	ds_read_b64_tr_b16 v[116:117], v206 offset:37888
	ds_read_b64_tr_b16 v[118:119], v206 offset:38400
	v_exp_f32_e32 v86, v86
	v_exp_f32_e32 v87, v87
	ds_read_b128 v[140:143], v128 offset:4096
	ds_read_b128 v[136:139], v128 offset:4608
	s_waitcnt lgkmcnt(14)
	v_mfma_f32_32x32x16_bf16 v[48:63], v[148:151], v[124:127], v[48:63]
	ds_read_b64_tr_b16 v[120:121], v206 offset:34816
	ds_read_b64_tr_b16 v[122:123], v206 offset:35328
	v_exp_f32_e32 v88, v88
	v_exp_f32_e32 v89, v89
	ds_read_b128 v[132:135], v128 offset:6144
	ds_read_b128 v[128:131], v128 offset:6656
	v_mfma_f32_32x32x16_bf16 v[32:47], v[148:151], v[198:201], v[32:47]
	ds_read_b64_tr_b16 v[124:125], v206 offset:38912
	ds_read_b64_tr_b16 v[126:127], v206 offset:39424
	v_exp_f32_e32 v90, v90
	v_exp_f32_e32 v91, v91
	s_waitcnt lgkmcnt(14)
	v_mfma_f32_32x32x16_bf16 v[48:63], v[144:147], v[202:205], v[48:63]
	ds_read_b64_tr_b16 v[198:199], v206 offset:35840
	ds_read_b64_tr_b16 v[200:201], v206 offset:36352
	v_exp_f32_e32 v92, v92
	v_exp_f32_e32 v93, v93
	v_mfma_f32_32x32x16_bf16 v[32:47], v[144:147], v[104:107], v[32:47]
	ds_read_b64_tr_b16 v[202:203], v206 offset:39936
	ds_read_b64_tr_b16 v[204:205], v206 offset:40448
	v_exp_f32_e32 v94, v94
	v_exp_f32_e32 v95, v95
	s_waitcnt lgkmcnt(14)
	v_mfma_f32_32x32x16_bf16 v[16:31], v[156:159], v[108:111], v[16:31]
	v_exp_f32_e32 v64, v64
	v_exp_f32_e32 v65, v65
	v_mfma_f32_32x32x16_bf16 v[0:15], v[156:159], v[194:197], v[0:15]
	v_exp_f32_e32 v66, v66
	v_exp_f32_e32 v67, v67
	v_mfma_f32_32x32x16_bf16 v[16:31], v[152:155], v[112:115], v[16:31]
	v_exp_f32_e32 v68, v68
	v_exp_f32_e32 v69, v69
	s_waitcnt lgkmcnt(12)
	v_mfma_f32_32x32x16_bf16 v[0:15], v[152:155], v[116:119], v[0:15]
	v_exp_f32_e32 v70, v70
	v_exp_f32_e32 v71, v71
	s_waitcnt lgkmcnt(8)
	v_mfma_f32_32x32x16_bf16 v[16:31], v[148:151], v[120:123], v[16:31]
	v_exp_f32_e32 v72, v72
	v_exp_f32_e32 v73, v73
	s_waitcnt lgkmcnt(4)
	v_mfma_f32_32x32x16_bf16 v[0:15], v[148:151], v[124:127], v[0:15]
	v_exp_f32_e32 v74, v74
	v_exp_f32_e32 v75, v75
	s_waitcnt lgkmcnt(2)
	v_mfma_f32_32x32x16_bf16 v[16:31], v[144:147], v[198:201], v[16:31]
	v_exp_f32_e32 v76, v76
	v_exp_f32_e32 v77, v77
	s_waitcnt lgkmcnt(0)
	v_mfma_f32_32x32x16_bf16 v[0:15], v[144:147], v[202:205], v[0:15]
	v_exp_f32_e32 v78, v78
	v_exp_f32_e32 v79, v79
	s_add_i32 s90, s88, 0x2000
	s_waitcnt vmcnt(3) lgkmcnt(0)
	s_barrier
; #define WAIT_BAR(N) asm volatile("s_waitcnt vmcnt(" #N ") lgkmcnt(0)\n\ts_barrier":::"memory")
;   #define RESC() do{ if(!NOMAX&&resc){ asm volatile("s_waitcnt lgkmcnt(0)":::"memory"); \
;       _Pragma("unroll") for(int d_=0;d_<2*VM;++d_) _Pragma("unroll") for(int r=0;r<16;++r)o[d_][r]*=wsf[crow(r,hi)]; } }while(0)
;   #define ROT() do{sl_prev=sl_cur;sl_cur=sl_next;sl_next=(sl_next==(NSLOT-1)*SLOTB)?0:sl_next+SLOTB;}while(0)
;   #define ENDW(tt) do{ if((tt)+3<NT){ if constexpr(VM==2){WAIT_BAR(3);}else{WAIT_BAR(2);} } else if((tt)+2<NT){ if constexpr(VM==2){WAIT_BAR(2);}else{WAIT_BAR(1);} } else {WAIT_BAR(0);} }while(0)
; template<int THRL,int VM,bool NOMAX> __device__ __forceinline__ void attn_unit(const bf16*Qb,const bf16*__restrict__ Kh,const bf16*__restrict__ Vh,bf16*Ob,const int NT,const int sp,float*wscr,char*shm){
;     ...
;   int t=1;
;   for(;t+5<NT;t+=2){
;     STEP(pB0,pB1,pA0,pA1,t,true,true,true);     if constexpr(VM==2){WAIT_BAR(3);}else{WAIT_BAR(2);} RESC(); ROT();
;     STEP(pA0,pA1,pB0,pB1,t+1,true,true,true);   if constexpr(VM==2){WAIT_BAR(3);}else{WAIT_BAR(2);} RESC(); ROT();
;   }
;     ...
;   for(;t+1<NT;t+=2){
;     STEP(pB0,pB1,pA0,pA1,t,(t+3<NT),(t+1<NT),(t+1<NT));       ENDW(t);   RESC(); ROT();
;     STEP(pA0,pA1,pB0,pB1,t+1,(t+4<NT),(t+2<NT),(t+2<NT));     ENDW(t+1); RESC(); ROT();
	s_cmpk_lg_i32 s88, 0x4000
	s_mov_b32 s89, s86
	s_cselect_b32 s86, s90, 0
	s_add_i32 s85, s85, 2
	v_lshl_add_u64 v[176:177], v[176:177], 0, s[58:59]
	v_lshl_add_u64 v[178:179], v[178:179], 0, s[58:59]
	v_lshl_add_u64 v[180:181], v[180:181], 0, s[58:59]
	s_mov_b32 s87, s88
	s_cmp_lt_u32 s85, 57
	s_cbranch_scc1 .LBB0_874
	s_and_b32 s34, s34, 0x3fffffc0
	s_lshl_b32 s34, s34, 2
	s_add_i32 s34, s34, 0
	s_add_i32 s34, s34, 0x12000
	s_cmp_lg_u32 0, -1
	s_cselect_b32 s85, 0, 0
	s_add_i32 s86, s85, 0x6000
	v_add_u32_e32 v104, s86, v191
	v_add3_u32 v176, v104, v190, v192
	v_add_u32_e32 v177, 0x6000, v188
	ds_read_b64_tr_b16 v[178:179], v188 offset:40960
	ds_read_b64_tr_b16 v[180:181], v188 offset:41472
	v_add_f32_e32 v108, v80, v81
	ds_read_b128 v[104:107], v168
	v_add_f32_e32 v108, v82, v108
	v_add_f32_e32 v108, v83, v108
	v_add_f32_e32 v108, v84, v108
	v_add_f32_e32 v108, v85, v108
	v_cvt_pk_bf16_f32 v156, v80, v81
	v_cvt_pk_bf16_f32 v157, v82, v83
	s_waitcnt lgkmcnt(0)
	v_mfma_f32_32x32x16_bf16 v[112:127], v[100:103], v[104:107], 0
	ds_read_b64_tr_b16 v[80:81], v188 offset:45056
	ds_read_b64_tr_b16 v[82:83], v188 offset:45568
	ds_read_b128 v[100:103], v168
	v_add_f32_e32 v104, v86, v108
	v_add_f32_e32 v104, v87, v104
	v_add_f32_e32 v104, v88, v104
	v_add_f32_e32 v144, v89, v104
	v_cvt_pk_bf16_f32 v158, v84, v85
	v_cvt_pk_bf16_f32 v159, v86, v87
	s_waitcnt lgkmcnt(0)
	v_mfma_f32_32x32x16_bf16 v[96:111], v[96:99], v[100:103], 0
	ds_read_b64_tr_b16 v[84:85], v188 offset:41984
	ds_read_b64_tr_b16 v[86:87], v188 offset:42496
	ds_read_b128 v[194:197], v168 offset:1024
	v_add_f32_e32 v144, v90, v144
	v_add_f32_e32 v144, v91, v144
	v_add_f32_e32 v144, v92, v144
	v_add_f32_e32 v144, v93, v144
	v_cvt_pk_bf16_f32 v152, v88, v89
	v_cvt_pk_bf16_f32 v153, v90, v91
	s_waitcnt lgkmcnt(0)
	v_mfma_f32_32x32x16_bf16 v[112:127], v[164:167], v[194:197], v[112:127]
	ds_read_b64_tr_b16 v[88:89], v188 offset:46080
	ds_read_b64_tr_b16 v[90:91], v188 offset:46592
	ds_read_b128 v[164:167], v168 offset:1024
	v_add_f32_e32 v144, v94, v144
	v_add_f32_e32 v144, v95, v144
	v_add_f32_e32 v144, v64, v144
	v_add_f32_e32 v144, v65, v144
	v_cvt_pk_bf16_f32 v154, v92, v93
	v_cvt_pk_bf16_f32 v155, v94, v95
	s_waitcnt lgkmcnt(0)
	v_mfma_f32_32x32x16_bf16 v[96:111], v[160:163], v[164:167], v[96:111]
	ds_read_b64_tr_b16 v[194:195], v188 offset:43008
	ds_read_b64_tr_b16 v[196:197], v188 offset:43520
	ds_read_b128 v[92:95], v168 offset:2048
	v_add_f32_e32 v144, v66, v144
	v_add_f32_e32 v144, v67, v144
	v_add_f32_e32 v144, v68, v144
	v_add_f32_e32 v144, v69, v144
	v_cvt_pk_bf16_f32 v148, v64, v65
	v_cvt_pk_bf16_f32 v149, v66, v67
	s_waitcnt lgkmcnt(0)
	v_mfma_f32_32x32x16_bf16 v[112:127], v[140:143], v[92:95], v[112:127]
	ds_read_b64_tr_b16 v[140:141], v188 offset:47104
	ds_read_b64_tr_b16 v[142:143], v188 offset:47616
	ds_read_b128 v[64:67], v168 offset:2048
	v_add_f32_e32 v92, v70, v144
	v_add_f32_e32 v92, v71, v92
	v_add_f32_e32 v92, v72, v92
	v_add_f32_e32 v92, v73, v92
	v_cvt_pk_bf16_f32 v150, v68, v69
	v_cvt_pk_bf16_f32 v151, v70, v71
	s_waitcnt lgkmcnt(0)
	v_mfma_f32_32x32x16_bf16 v[96:111], v[136:139], v[64:67], v[96:111]
	ds_read_b64_tr_b16 v[136:137], v188 offset:44032
	ds_read_b64_tr_b16 v[138:139], v188 offset:44544
	ds_read_b128 v[64:67], v168 offset:3072
	v_add_f32_e32 v68, v74, v92
	v_add_f32_e32 v68, v75, v68
	v_add_f32_e32 v68, v76, v68
	v_add_f32_e32 v68, v77, v68
	v_cvt_pk_bf16_f32 v144, v72, v73
	v_cvt_pk_bf16_f32 v145, v74, v75
	s_waitcnt lgkmcnt(0)
	v_mfma_f32_32x32x16_bf16 v[112:127], v[132:135], v[64:67], v[112:127]
	ds_read_b64_tr_b16 v[72:73], v188 offset:48128
	ds_read_b64_tr_b16 v[74:75], v188 offset:48640
	ds_read_b128 v[64:67], v168 offset:3072
	v_add_f32_e32 v68, v78, v68
	v_add_f32_e32 v68, v79, v68
	v_add_f32_e32 v68, 0, v68
	v_cvt_pk_bf16_f32 v146, v76, v77
	v_cvt_pk_bf16_f32 v147, v78, v79
	s_waitcnt lgkmcnt(0)
	v_mfma_f32_32x32x16_bf16 v[96:111], v[128:131], v[64:67], v[96:111]
	s_add_i32 s85, s85, s35
	v_lshl_add_u64 v[64:65], v[174:175], 0, s[60:61]
	s_add_i32 s35, s85, 0x4000
	s_mov_b32 s86, m0
	s_mov_b32 m0, s35
	s_nop 0
	global_load_lds_dwordx4 v[64:65], off
	s_mov_b32 m0, s86
	v_lshl_add_u64 v[64:65], v[170:171], 0, s[62:63]
	s_mov_b32 s35, m0
	s_mov_b32 m0, s16
	s_nop 0
	global_load_lds_dwordx4 v[64:65], off
	s_mov_b32 m0, s35
	v_lshl_add_u64 v[64:65], v[172:173], 0, s[62:63]
	s_add_i32 s35, s16, 0x2000
	s_mov_b32 s86, m0
	s_mov_b32 m0, s35
	s_nop 0
	global_load_lds_dwordx4 v[64:65], off
	s_mov_b32 m0, s86
	v_add_f32_e32 v198, v193, v68
	v_mfma_f32_32x32x16_bf16 v[48:63], v[156:159], v[178:181], v[48:63]
	ds_read_b64_tr_b16 v[76:77], v188 offset:49152
	ds_read_b64_tr_b16 v[78:79], v188 offset:49664
	v_exp_f32_e32 v112, v112
	v_exp_f32_e32 v113, v113
	v_mfma_f32_32x32x16_bf16 v[32:47], v[156:159], v[80:83], v[32:47]
	ds_read_b64_tr_b16 v[128:129], v188 offset:53248
	ds_read_b64_tr_b16 v[130:131], v188 offset:53760
	v_exp_f32_e32 v114, v114
	v_exp_f32_e32 v115, v115
	ds_read_b128 v[68:71], v189
	ds_read_b128 v[64:67], v189 offset:512
	v_mfma_f32_32x32x16_bf16 v[48:63], v[152:155], v[84:87], v[48:63]
	ds_read_b64_tr_b16 v[132:133], v188 offset:50176
	ds_read_b64_tr_b16 v[134:135], v188 offset:50688
	v_exp_f32_e32 v116, v116
	v_exp_f32_e32 v117, v117
	ds_read_b128 v[164:167], v189 offset:2048
	ds_read_b128 v[92:95], v189 offset:2560
	v_mfma_f32_32x32x16_bf16 v[32:47], v[152:155], v[88:91], v[32:47]
	ds_read_b64_tr_b16 v[178:179], v188 offset:54272
	ds_read_b64_tr_b16 v[180:181], v188 offset:54784
	v_exp_f32_e32 v118, v118
	v_exp_f32_e32 v119, v119
	ds_read_b128 v[160:163], v189 offset:4096
	ds_read_b128 v[84:87], v189 offset:4608
	v_mfma_f32_32x32x16_bf16 v[48:63], v[148:151], v[194:197], v[48:63]
	ds_read_b64_tr_b16 v[190:191], v188 offset:51200
	ds_read_b64_tr_b16 v[192:193], v188 offset:51712
	v_exp_f32_e32 v120, v120
	v_exp_f32_e32 v121, v121
	ds_read_b128 v[88:91], v189 offset:6144
	ds_read_b128 v[80:83], v189 offset:6656
	v_mfma_f32_32x32x16_bf16 v[32:47], v[148:151], v[140:143], v[32:47]
	ds_read_b64_tr_b16 v[194:195], v188 offset:55296
	ds_read_b64_tr_b16 v[196:197], v188 offset:55808
	v_exp_f32_e32 v122, v122
	v_exp_f32_e32 v123, v123
	v_mfma_f32_32x32x16_bf16 v[48:63], v[144:147], v[136:139], v[48:63]
	ds_read_b64_tr_b16 v[140:141], v188 offset:52224
	ds_read_b64_tr_b16 v[142:143], v188 offset:52736
	v_exp_f32_e32 v124, v124
	v_exp_f32_e32 v125, v125
	v_mfma_f32_32x32x16_bf16 v[32:47], v[144:147], v[72:75], v[32:47]
	ds_read_b64_tr_b16 v[136:137], v188 offset:56320
	ds_read_b64_tr_b16 v[138:139], v188 offset:56832
	v_exp_f32_e32 v126, v126
	v_exp_f32_e32 v127, v127
	s_waitcnt lgkmcnt(14)
; #define WAIT_BAR(N) asm volatile("s_waitcnt vmcnt(" #N ") lgkmcnt(0)\n\ts_barrier":::"memory")
;   #define RESC() do{ if(!NOMAX&&resc){ asm volatile("s_waitcnt lgkmcnt(0)":::"memory"); \
;       _Pragma("unroll") for(int d_=0;d_<2*VM;++d_) _Pragma("unroll") for(int r=0;r<16;++r)o[d_][r]*=wsf[crow(r,hi)]; } }while(0)
;   #define ROT() do{sl_prev=sl_cur;sl_cur=sl_next;sl_next=(sl_next==(NSLOT-1)*SLOTB)?0:sl_next+SLOTB;}while(0)
;   #define ENDW(tt) do{ if((tt)+3<NT){ if constexpr(VM==2){WAIT_BAR(3);}else{WAIT_BAR(2);} } else if((tt)+2<NT){ if constexpr(VM==2){WAIT_BAR(2);}else{WAIT_BAR(1);} } else {WAIT_BAR(0);} }while(0)
; template<int THRL,int VM,bool NOMAX> __device__ __forceinline__ void attn_unit(const bf16*Qb,const bf16*__restrict__ Kh,const bf16*__restrict__ Vh,bf16*Ob,const int NT,const int sp,float*wscr,char*shm){
;     ...
;   int t=1;
;   for(;t+5<NT;t+=2){
;     STEP(pB0,pB1,pA0,pA1,t,true,true,true);     if constexpr(VM==2){WAIT_BAR(3);}else{WAIT_BAR(2);} RESC(); ROT();
;     STEP(pA0,pA1,pB0,pB1,t+1,true,true,true);   if constexpr(VM==2){WAIT_BAR(3);}else{WAIT_BAR(2);} RESC(); ROT();
;   }
;     ...
;   for(;t+1<NT;t+=2){
;     STEP(pB0,pB1,pA0,pA1,t,(t+3<NT),(t+1<NT),(t+1<NT));       ENDW(t);   RESC(); ROT();
;     STEP(pA0,pA1,pB0,pB1,t+1,(t+4<NT),(t+2<NT),(t+2<NT));     ENDW(t+1); RESC(); ROT();
	v_mfma_f32_32x32x16_bf16 v[16:31], v[156:159], v[76:79], v[16:31]
	v_exp_f32_e32 v96, v96
	v_exp_f32_e32 v97, v97
	v_mfma_f32_32x32x16_bf16 v[0:15], v[156:159], v[128:131], v[0:15]
	v_exp_f32_e32 v98, v98
	v_exp_f32_e32 v99, v99
	v_mfma_f32_32x32x16_bf16 v[16:31], v[152:155], v[132:135], v[16:31]
	v_exp_f32_e32 v100, v100
	v_exp_f32_e32 v101, v101
	s_waitcnt lgkmcnt(12)
	v_mfma_f32_32x32x16_bf16 v[0:15], v[152:155], v[178:181], v[0:15]
	v_exp_f32_e32 v102, v102
	v_exp_f32_e32 v103, v103
	s_waitcnt lgkmcnt(8)
	v_mfma_f32_32x32x16_bf16 v[16:31], v[148:151], v[190:193], v[16:31]
	v_exp_f32_e32 v104, v104
	v_exp_f32_e32 v105, v105
	s_waitcnt lgkmcnt(4)
	v_mfma_f32_32x32x16_bf16 v[0:15], v[148:151], v[194:197], v[0:15]
	v_exp_f32_e32 v106, v106
	v_exp_f32_e32 v107, v107
	s_waitcnt lgkmcnt(2)
	v_mfma_f32_32x32x16_bf16 v[16:31], v[144:147], v[140:143], v[16:31]
	v_exp_f32_e32 v108, v108
	v_exp_f32_e32 v109, v109
	s_waitcnt lgkmcnt(0)
	v_mfma_f32_32x32x16_bf16 v[0:15], v[144:147], v[136:139], v[0:15]
	v_exp_f32_e32 v110, v110
	v_exp_f32_e32 v111, v111
	s_waitcnt vmcnt(3) lgkmcnt(0)
	s_barrier
	ds_read_b64_tr_b16 v[178:179], v188 offset:57344
	ds_read_b64_tr_b16 v[180:181], v188 offset:57856
	v_add_f32_e32 v76, v112, v113
	ds_read_b128 v[72:75], v168
	v_add_f32_e32 v76, v114, v76
	v_add_f32_e32 v76, v115, v76
	v_add_f32_e32 v76, v116, v76
	v_add_f32_e32 v76, v117, v76
	v_cvt_pk_bf16_f32 v156, v112, v113
	v_cvt_pk_bf16_f32 v157, v114, v115
	s_waitcnt lgkmcnt(0)
	v_mfma_f32_32x32x16_bf16 v[128:143], v[68:71], v[72:75], 0
	ds_read_b64_tr_b16 v[112:113], v188 offset:61440
	ds_read_b64_tr_b16 v[114:115], v188 offset:61952
	ds_read_b128 v[68:71], v168
	v_add_f32_e32 v72, v118, v76
	v_add_f32_e32 v72, v119, v72
	v_add_f32_e32 v72, v120, v72
	v_add_f32_e32 v144, v121, v72
	s_waitcnt lgkmcnt(0)
	v_mfma_f32_32x32x16_bf16 v[64:79], v[64:67], v[68:71], 0
	v_cvt_pk_bf16_f32 v158, v116, v117
	v_cvt_pk_bf16_f32 v159, v118, v119
	ds_read_b64_tr_b16 v[116:117], v188 offset:58368
	ds_read_b64_tr_b16 v[118:119], v188 offset:58880
	ds_read_b128 v[190:193], v168 offset:1024
	v_add_f32_e32 v144, v122, v144
	v_add_f32_e32 v144, v123, v144
	v_add_f32_e32 v144, v124, v144
	v_add_f32_e32 v144, v125, v144
	v_cvt_pk_bf16_f32 v152, v120, v121
	v_cvt_pk_bf16_f32 v153, v122, v123
	s_waitcnt lgkmcnt(0)
	v_mfma_f32_32x32x16_bf16 v[128:143], v[164:167], v[190:193], v[128:143]
	ds_read_b64_tr_b16 v[120:121], v188 offset:62464
	ds_read_b64_tr_b16 v[122:123], v188 offset:62976
	ds_read_b128 v[164:167], v168 offset:1024
	v_add_f32_e32 v144, v126, v144
	v_add_f32_e32 v144, v127, v144
	v_add_f32_e32 v144, v96, v144
	v_add_f32_e32 v144, v97, v144
	s_waitcnt lgkmcnt(0)
	v_mfma_f32_32x32x16_bf16 v[64:79], v[92:95], v[164:167], v[64:79]
	v_cvt_pk_bf16_f32 v154, v124, v125
	v_cvt_pk_bf16_f32 v155, v126, v127
	ds_read_b64_tr_b16 v[92:93], v188 offset:59392
	ds_read_b64_tr_b16 v[94:95], v188 offset:59904
	ds_read_b128 v[124:127], v168 offset:2048
	v_add_f32_e32 v144, v98, v144
	v_add_f32_e32 v144, v99, v144
	v_add_f32_e32 v144, v100, v144
	v_add_f32_e32 v144, v101, v144
	v_cvt_pk_bf16_f32 v148, v96, v97
	v_cvt_pk_bf16_f32 v149, v98, v99
	s_waitcnt lgkmcnt(0)
	v_mfma_f32_32x32x16_bf16 v[128:143], v[160:163], v[124:127], v[128:143]
	ds_read_b64_tr_b16 v[96:97], v188 offset:63488
	ds_read_b64_tr_b16 v[98:99], v188 offset:64000
	ds_read_b128 v[124:127], v168 offset:2048
	v_add_f32_e32 v144, v102, v144
	v_add_f32_e32 v144, v103, v144
	v_add_f32_e32 v144, v104, v144
	v_add_f32_e32 v144, v105, v144
	s_waitcnt lgkmcnt(0)
	v_mfma_f32_32x32x16_bf16 v[64:79], v[84:87], v[124:127], v[64:79]
	v_cvt_pk_bf16_f32 v150, v100, v101
	v_cvt_pk_bf16_f32 v151, v102, v103
	ds_read_b64_tr_b16 v[100:101], v188 offset:60416
	ds_read_b64_tr_b16 v[102:103], v188 offset:60928
	ds_read_b128 v[84:87], v168 offset:3072
	v_add_f32_e32 v124, v106, v144
	v_add_f32_e32 v124, v107, v124
	v_add_f32_e32 v124, v108, v124
	v_add_f32_e32 v124, v109, v124
	v_cvt_pk_bf16_f32 v144, v104, v105
	v_cvt_pk_bf16_f32 v145, v106, v107
	s_waitcnt lgkmcnt(0)
	v_mfma_f32_32x32x16_bf16 v[128:143], v[88:91], v[84:87], v[128:143]
	ds_read_b64_tr_b16 v[88:89], v188 offset:64512
	ds_read_b64_tr_b16 v[90:91], v188 offset:65024
	ds_read_b128 v[84:87], v168 offset:3072
	v_add_f32_e32 v104, v110, v124
	v_add_f32_e32 v104, v111, v104
	v_add_f32_e32 v104, 0, v104
	v_cvt_pk_bf16_f32 v146, v108, v109
	s_waitcnt lgkmcnt(0)
; #define WAIT_BAR(N) asm volatile("s_waitcnt vmcnt(" #N ") lgkmcnt(0)\n\ts_barrier":::"memory")
;   #define RESC() do{ if(!NOMAX&&resc){ asm volatile("s_waitcnt lgkmcnt(0)":::"memory"); \
;       _Pragma("unroll") for(int d_=0;d_<2*VM;++d_) _Pragma("unroll") for(int r=0;r<16;++r)o[d_][r]*=wsf[crow(r,hi)]; } }while(0)
;   #define ROT() do{sl_prev=sl_cur;sl_cur=sl_next;sl_next=(sl_next==(NSLOT-1)*SLOTB)?0:sl_next+SLOTB;}while(0)
;   #define ENDW(tt) do{ if((tt)+3<NT){ if constexpr(VM==2){WAIT_BAR(3);}else{WAIT_BAR(2);} } else if((tt)+2<NT){ if constexpr(VM==2){WAIT_BAR(2);}else{WAIT_BAR(1);} } else {WAIT_BAR(0);} }while(0)
; template<int THRL,int VM,bool NOMAX> __device__ __forceinline__ void attn_unit(const bf16*Qb,const bf16*__restrict__ Kh,const bf16*__restrict__ Vh,bf16*Ob,const int NT,const int sp,float*wscr,char*shm){
;     ...
;   int t=1;
;   for(;t+5<NT;t+=2){
;     STEP(pB0,pB1,pA0,pA1,t,true,true,true);     if constexpr(VM==2){WAIT_BAR(3);}else{WAIT_BAR(2);} RESC(); ROT();
;     STEP(pA0,pA1,pB0,pB1,t+1,true,true,true);   if constexpr(VM==2){WAIT_BAR(3);}else{WAIT_BAR(2);} RESC(); ROT();
;   }
;     ...
;   for(;t+1<NT;t+=2){
;     STEP(pB0,pB1,pA0,pA1,t,(t+3<NT),(t+1<NT),(t+1<NT));       ENDW(t);   RESC(); ROT();
;     STEP(pA0,pA1,pB0,pB1,t+1,(t+4<NT),(t+2<NT),(t+2<NT));     ENDW(t+1); RESC(); ROT();
	v_mfma_f32_32x32x16_bf16 v[64:79], v[80:83], v[84:87], v[64:79]
	v_cvt_pk_bf16_f32 v147, v110, v111
	v_lshl_add_u64 v[80:81], v[174:175], 0, s[64:65]
	s_mov_b32 s86, m0
	s_mov_b32 m0, s17
	s_nop 0
	global_load_lds_dwordx4 v[80:81], off
	s_mov_b32 m0, s86
	v_lshl_add_u64 v[80:81], v[170:171], 0, s[66:67]
	s_add_i32 s17, s85, 0xa000
	s_mov_b32 s86, m0
	s_mov_b32 m0, s17
	s_nop 0
	global_load_lds_dwordx4 v[80:81], off
	s_mov_b32 m0, s86
	v_lshl_add_u64 v[80:81], v[172:173], 0, s[66:67]
	s_add_i32 s17, s85, 0xc000
	s_mov_b32 s86, m0
	s_mov_b32 m0, s17
	s_nop 0
	global_load_lds_dwordx4 v[80:81], off
	s_mov_b32 m0, s86
	v_add_f32_e32 v198, v198, v104
	v_mfma_f32_32x32x16_bf16 v[48:63], v[156:159], v[178:181], v[48:63]
	ds_read_b64_tr_b16 v[104:105], v177 offset:40960
	ds_read_b64_tr_b16 v[106:107], v177 offset:41472
	v_exp_f32_e32 v128, v128
	v_exp_f32_e32 v129, v129
	v_mfma_f32_32x32x16_bf16 v[32:47], v[156:159], v[112:115], v[32:47]
	ds_read_b64_tr_b16 v[108:109], v177 offset:45056
	ds_read_b64_tr_b16 v[110:111], v177 offset:45568
	v_exp_f32_e32 v130, v130
	v_exp_f32_e32 v131, v131
	ds_read_b128 v[84:87], v189 offset:8192
	ds_read_b128 v[80:83], v189 offset:8704
	v_mfma_f32_32x32x16_bf16 v[48:63], v[152:155], v[116:119], v[48:63]
	ds_read_b64_tr_b16 v[178:179], v177 offset:41984
	ds_read_b64_tr_b16 v[180:181], v177 offset:42496
	v_exp_f32_e32 v132, v132
	v_exp_f32_e32 v133, v133
	ds_read_b128 v[164:167], v189 offset:10240
	ds_read_b128 v[124:127], v189 offset:10752
	v_mfma_f32_32x32x16_bf16 v[32:47], v[152:155], v[120:123], v[32:47]
	ds_read_b64_tr_b16 v[190:191], v177 offset:46080
	ds_read_b64_tr_b16 v[192:193], v177 offset:46592
	v_exp_f32_e32 v134, v134
	v_exp_f32_e32 v135, v135
	ds_read_b128 v[160:163], v189 offset:12288
	ds_read_b128 v[116:119], v189 offset:12800
	v_mfma_f32_32x32x16_bf16 v[48:63], v[148:151], v[92:95], v[48:63]
	ds_read_b64_tr_b16 v[194:195], v177 offset:43008
	ds_read_b64_tr_b16 v[196:197], v177 offset:43520
	v_exp_f32_e32 v136, v136
	v_exp_f32_e32 v137, v137
	ds_read_b128 v[120:123], v189 offset:14336
	ds_read_b128 v[112:115], v189 offset:14848
	v_mfma_f32_32x32x16_bf16 v[32:47], v[148:151], v[96:99], v[32:47]
	ds_read_b64_tr_b16 v[92:93], v177 offset:47104
	ds_read_b64_tr_b16 v[94:95], v177 offset:47616
	v_exp_f32_e32 v138, v138
	v_exp_f32_e32 v139, v139
	v_mfma_f32_32x32x16_bf16 v[48:63], v[144:147], v[100:103], v[48:63]
	ds_read_b64_tr_b16 v[96:97], v177 offset:44032
	ds_read_b64_tr_b16 v[98:99], v177 offset:44544
	v_exp_f32_e32 v140, v140
	v_exp_f32_e32 v141, v141
	v_mfma_f32_32x32x16_bf16 v[32:47], v[144:147], v[88:91], v[32:47]
	ds_read_b64_tr_b16 v[100:101], v177 offset:48128
	ds_read_b64_tr_b16 v[102:103], v177 offset:48640
	v_exp_f32_e32 v142, v142
	v_exp_f32_e32 v143, v143
	s_waitcnt lgkmcnt(14)
	v_mfma_f32_32x32x16_bf16 v[16:31], v[156:159], v[104:107], v[16:31]
	v_exp_f32_e32 v64, v64
	v_exp_f32_e32 v65, v65
	v_mfma_f32_32x32x16_bf16 v[0:15], v[156:159], v[108:111], v[0:15]
	v_exp_f32_e32 v66, v66
	v_exp_f32_e32 v67, v67
	v_mfma_f32_32x32x16_bf16 v[16:31], v[152:155], v[178:181], v[16:31]
	v_exp_f32_e32 v68, v68
	v_exp_f32_e32 v69, v69
	s_waitcnt lgkmcnt(12)
	v_mfma_f32_32x32x16_bf16 v[0:15], v[152:155], v[190:193], v[0:15]
	v_exp_f32_e32 v70, v70
	v_exp_f32_e32 v71, v71
	s_waitcnt lgkmcnt(8)
	v_mfma_f32_32x32x16_bf16 v[16:31], v[148:151], v[194:197], v[16:31]
	v_exp_f32_e32 v72, v72
	v_exp_f32_e32 v73, v73
	s_waitcnt lgkmcnt(4)
	v_mfma_f32_32x32x16_bf16 v[0:15], v[148:151], v[92:95], v[0:15]
	v_exp_f32_e32 v74, v74
	v_exp_f32_e32 v75, v75
	s_waitcnt lgkmcnt(2)
	v_mfma_f32_32x32x16_bf16 v[16:31], v[144:147], v[96:99], v[16:31]
	v_exp_f32_e32 v76, v76
	v_exp_f32_e32 v77, v77
	s_waitcnt lgkmcnt(0)
	v_mfma_f32_32x32x16_bf16 v[0:15], v[144:147], v[100:103], v[0:15]
	v_exp_f32_e32 v78, v78
	v_exp_f32_e32 v79, v79
	s_waitcnt vmcnt(3) lgkmcnt(0)
	s_barrier
	ds_read_b64_tr_b16 v[178:179], v188 offset:24576
	ds_read_b64_tr_b16 v[180:181], v188 offset:25088
	v_add_f32_e32 v92, v128, v129
	ds_read_b128 v[88:91], v168
	v_add_f32_e32 v92, v130, v92
	v_add_f32_e32 v92, v131, v92
	v_add_f32_e32 v92, v132, v92
	v_add_f32_e32 v92, v133, v92
	v_cvt_pk_bf16_f32 v156, v128, v129
	v_cvt_pk_bf16_f32 v157, v130, v131
	s_waitcnt lgkmcnt(0)
	v_mfma_f32_32x32x16_bf16 v[96:111], v[84:87], v[88:91], 0
	ds_read_b64_tr_b16 v[128:129], v188 offset:28672
	ds_read_b64_tr_b16 v[130:131], v188 offset:29184
	ds_read_b128 v[84:87], v168
	v_add_f32_e32 v88, v134, v92
	v_add_f32_e32 v88, v135, v88
	v_add_f32_e32 v88, v136, v88
	v_add_f32_e32 v144, v137, v88
	v_cvt_pk_bf16_f32 v158, v132, v133
	v_cvt_pk_bf16_f32 v159, v134, v135
	s_waitcnt lgkmcnt(0)
	v_mfma_f32_32x32x16_bf16 v[80:95], v[80:83], v[84:87], 0
	ds_read_b64_tr_b16 v[132:133], v188 offset:25600
	ds_read_b64_tr_b16 v[134:135], v188 offset:26112
	ds_read_b128 v[190:193], v168 offset:1024
	v_add_f32_e32 v144, v138, v144
	v_add_f32_e32 v144, v139, v144
	v_add_f32_e32 v144, v140, v144
	v_add_f32_e32 v144, v141, v144
	v_cvt_pk_bf16_f32 v152, v136, v137
	v_cvt_pk_bf16_f32 v153, v138, v139
	s_waitcnt lgkmcnt(0)
	v_mfma_f32_32x32x16_bf16 v[96:111], v[164:167], v[190:193], v[96:111]
	ds_read_b64_tr_b16 v[136:137], v188 offset:29696
	ds_read_b64_tr_b16 v[138:139], v188 offset:30208
	ds_read_b128 v[164:167], v168 offset:1024
	v_add_f32_e32 v144, v142, v144
	v_add_f32_e32 v144, v143, v144
	v_add_f32_e32 v144, v64, v144
	v_add_f32_e32 v144, v65, v144
	v_cvt_pk_bf16_f32 v154, v140, v141
	v_cvt_pk_bf16_f32 v155, v142, v143
	s_waitcnt lgkmcnt(0)
; #define WAIT_BAR(N) asm volatile("s_waitcnt vmcnt(" #N ") lgkmcnt(0)\n\ts_barrier":::"memory")
;   #define RESC() do{ if(!NOMAX&&resc){ asm volatile("s_waitcnt lgkmcnt(0)":::"memory"); \
;       _Pragma("unroll") for(int d_=0;d_<2*VM;++d_) _Pragma("unroll") for(int r=0;r<16;++r)o[d_][r]*=wsf[crow(r,hi)]; } }while(0)
;   #define ROT() do{sl_prev=sl_cur;sl_cur=sl_next;sl_next=(sl_next==(NSLOT-1)*SLOTB)?0:sl_next+SLOTB;}while(0)
;   #define ENDW(tt) do{ if((tt)+3<NT){ if constexpr(VM==2){WAIT_BAR(3);}else{WAIT_BAR(2);} } else if((tt)+2<NT){ if constexpr(VM==2){WAIT_BAR(2);}else{WAIT_BAR(1);} } else {WAIT_BAR(0);} }while(0)
; template<int THRL,int VM,bool NOMAX> __device__ __forceinline__ void attn_unit(const bf16*Qb,const bf16*__restrict__ Kh,const bf16*__restrict__ Vh,bf16*Ob,const int NT,const int sp,float*wscr,char*shm){
;     ...
;   int t=1;
;   for(;t+5<NT;t+=2){
;     STEP(pB0,pB1,pA0,pA1,t,true,true,true);     if constexpr(VM==2){WAIT_BAR(3);}else{WAIT_BAR(2);} RESC(); ROT();
;     STEP(pA0,pA1,pB0,pB1,t+1,true,true,true);   if constexpr(VM==2){WAIT_BAR(3);}else{WAIT_BAR(2);} RESC(); ROT();
;   }
;     ...
;   for(;t+1<NT;t+=2){
;     STEP(pB0,pB1,pA0,pA1,t,(t+3<NT),(t+1<NT),(t+1<NT));       ENDW(t);   RESC(); ROT();
;     STEP(pA0,pA1,pB0,pB1,t+1,(t+4<NT),(t+2<NT),(t+2<NT));     ENDW(t+1); RESC(); ROT();
	v_mfma_f32_32x32x16_bf16 v[80:95], v[124:127], v[164:167], v[80:95]
	ds_read_b64_tr_b16 v[124:125], v188 offset:26624
	ds_read_b64_tr_b16 v[126:127], v188 offset:27136
	ds_read_b128 v[140:143], v168 offset:2048
	v_add_f32_e32 v144, v66, v144
	v_add_f32_e32 v144, v67, v144
	v_add_f32_e32 v144, v68, v144
	v_add_f32_e32 v144, v69, v144
	v_cvt_pk_bf16_f32 v148, v64, v65
	v_cvt_pk_bf16_f32 v149, v66, v67
	s_waitcnt lgkmcnt(0)
	v_mfma_f32_32x32x16_bf16 v[96:111], v[160:163], v[140:143], v[96:111]
	ds_read_b64_tr_b16 v[190:191], v188 offset:30720
	ds_read_b64_tr_b16 v[192:193], v188 offset:31232
	ds_read_b128 v[64:67], v168 offset:2048
	v_add_f32_e32 v140, v70, v144
	v_add_f32_e32 v140, v71, v140
	v_add_f32_e32 v140, v72, v140
	v_add_f32_e32 v140, v73, v140
	v_cvt_pk_bf16_f32 v150, v68, v69
	v_cvt_pk_bf16_f32 v151, v70, v71
	s_waitcnt lgkmcnt(0)
	v_mfma_f32_32x32x16_bf16 v[80:95], v[116:119], v[64:67], v[80:95]
	ds_read_b64_tr_b16 v[116:117], v188 offset:27648
	ds_read_b64_tr_b16 v[118:119], v188 offset:28160
	ds_read_b128 v[64:67], v168 offset:3072
	v_add_f32_e32 v68, v74, v140
	v_add_f32_e32 v68, v75, v68
	v_add_f32_e32 v68, v76, v68
	v_add_f32_e32 v68, v77, v68
	v_cvt_pk_bf16_f32 v144, v72, v73
	v_cvt_pk_bf16_f32 v145, v74, v75
	s_waitcnt lgkmcnt(0)
	v_mfma_f32_32x32x16_bf16 v[96:111], v[120:123], v[64:67], v[96:111]
	ds_read_b64_tr_b16 v[72:73], v188 offset:31744
	ds_read_b64_tr_b16 v[74:75], v188 offset:32256
	ds_read_b128 v[64:67], v168 offset:3072
	v_add_f32_e32 v68, v78, v68
	v_add_f32_e32 v68, v79, v68
	v_add_f32_e32 v68, 0, v68
	v_cvt_pk_bf16_f32 v146, v76, v77
	v_cvt_pk_bf16_f32 v147, v78, v79
	s_waitcnt lgkmcnt(0)
	v_mfma_f32_32x32x16_bf16 v[80:95], v[112:115], v[64:67], v[80:95]
	v_lshl_add_u64 v[64:65], v[170:171], 0, s[60:61]
	s_add_i32 s17, s85, 0xe000
	s_mov_b32 s86, m0
	s_mov_b32 m0, s17
	s_nop 0
	global_load_lds_dwordx4 v[64:65], off
	s_mov_b32 m0, s86
	v_lshl_add_u64 v[64:65], v[172:173], 0, s[60:61]
	s_add_i32 s85, s85, 0x10000
	s_mov_b32 s17, m0
	s_mov_b32 m0, s85
	s_nop 0
	global_load_lds_dwordx4 v[64:65], off
	s_mov_b32 m0, s17
	v_add_f32_e32 v174, v198, v68
	v_mfma_f32_32x32x16_bf16 v[48:63], v[156:159], v[178:181], v[48:63]
	ds_read_b64_tr_b16 v[76:77], v188 offset:32768
	ds_read_b64_tr_b16 v[78:79], v188 offset:33280
	v_exp_f32_e32 v96, v96
	v_exp_f32_e32 v97, v97
	v_mfma_f32_32x32x16_bf16 v[32:47], v[156:159], v[128:131], v[32:47]
	ds_read_b64_tr_b16 v[112:113], v188 offset:36864
	ds_read_b64_tr_b16 v[114:115], v188 offset:37376
	v_exp_f32_e32 v98, v98
	v_exp_f32_e32 v99, v99
	ds_read_b128 v[68:71], v189 offset:16384
	ds_read_b128 v[64:67], v189 offset:16896
	v_mfma_f32_32x32x16_bf16 v[48:63], v[152:155], v[132:135], v[48:63]
	ds_read_b64_tr_b16 v[120:121], v188 offset:33792
	ds_read_b64_tr_b16 v[122:123], v188 offset:34304
	v_exp_f32_e32 v100, v100
	v_exp_f32_e32 v101, v101
	ds_read_b128 v[164:167], v189 offset:18432
	ds_read_b128 v[140:143], v189 offset:18944
	v_mfma_f32_32x32x16_bf16 v[32:47], v[152:155], v[136:139], v[32:47]
	ds_read_b64_tr_b16 v[178:179], v188 offset:37888
	ds_read_b64_tr_b16 v[180:181], v188 offset:38400
	v_exp_f32_e32 v102, v102
	v_exp_f32_e32 v103, v103
	ds_read_b128 v[160:163], v189 offset:20480
	ds_read_b128 v[132:135], v189 offset:20992
	v_mfma_f32_32x32x16_bf16 v[48:63], v[148:151], v[124:127], v[48:63]
	ds_read_b64_tr_b16 v[194:195], v188 offset:34816
	ds_read_b64_tr_b16 v[196:197], v188 offset:35328
	v_exp_f32_e32 v104, v104
	v_exp_f32_e32 v105, v105
	ds_read_b128 v[136:139], v189 offset:22528
	ds_read_b128 v[128:131], v189 offset:23040
	v_mfma_f32_32x32x16_bf16 v[32:47], v[148:151], v[190:193], v[32:47]
	ds_read_b64_tr_b16 v[124:125], v188 offset:38912
	ds_read_b64_tr_b16 v[126:127], v188 offset:39424
	v_exp_f32_e32 v106, v106
	v_exp_f32_e32 v107, v107
	v_mfma_f32_32x32x16_bf16 v[48:63], v[144:147], v[116:119], v[48:63]
	ds_read_b64_tr_b16 v[190:191], v188 offset:35840
	ds_read_b64_tr_b16 v[192:193], v188 offset:36352
	v_exp_f32_e32 v108, v108
	v_exp_f32_e32 v109, v109
	v_mfma_f32_32x32x16_bf16 v[32:47], v[144:147], v[72:75], v[32:47]
	ds_read_b64_tr_b16 v[116:117], v188 offset:39936
	ds_read_b64_tr_b16 v[118:119], v188 offset:40448
	v_exp_f32_e32 v110, v110
	v_exp_f32_e32 v111, v111
	s_waitcnt lgkmcnt(14)
	v_mfma_f32_32x32x16_bf16 v[16:31], v[156:159], v[76:79], v[16:31]
	v_exp_f32_e32 v80, v80
	v_exp_f32_e32 v81, v81
	v_mfma_f32_32x32x16_bf16 v[0:15], v[156:159], v[112:115], v[0:15]
	v_exp_f32_e32 v82, v82
	v_exp_f32_e32 v83, v83
	v_mfma_f32_32x32x16_bf16 v[16:31], v[152:155], v[120:123], v[16:31]
	v_exp_f32_e32 v84, v84
	v_exp_f32_e32 v85, v85
	s_waitcnt lgkmcnt(12)
	v_mfma_f32_32x32x16_bf16 v[0:15], v[152:155], v[178:181], v[0:15]
	v_exp_f32_e32 v86, v86
	v_exp_f32_e32 v87, v87
	s_waitcnt lgkmcnt(8)
	v_mfma_f32_32x32x16_bf16 v[16:31], v[148:151], v[194:197], v[16:31]
	v_exp_f32_e32 v88, v88
	v_exp_f32_e32 v89, v89
	s_waitcnt lgkmcnt(4)
	v_mfma_f32_32x32x16_bf16 v[0:15], v[148:151], v[124:127], v[0:15]
	v_exp_f32_e32 v90, v90
	v_exp_f32_e32 v91, v91
	s_waitcnt lgkmcnt(2)
	v_mfma_f32_32x32x16_bf16 v[16:31], v[144:147], v[190:193], v[16:31]
	v_exp_f32_e32 v92, v92
	v_exp_f32_e32 v93, v93
	s_waitcnt lgkmcnt(0)
	v_mfma_f32_32x32x16_bf16 v[0:15], v[144:147], v[116:119], v[0:15]
	v_exp_f32_e32 v94, v94
	v_exp_f32_e32 v95, v95
	s_waitcnt vmcnt(2) lgkmcnt(0)
	s_barrier
;   #define RESC() do{ if(!NOMAX&&resc){ asm volatile("s_waitcnt lgkmcnt(0)":::"memory"); \
;       _Pragma("unroll") for(int d_=0;d_<2*VM;++d_) _Pragma("unroll") for(int r=0;r<16;++r)o[d_][r]*=wsf[crow(r,hi)]; } }while(0)
;   #define ROT() do{sl_prev=sl_cur;sl_cur=sl_next;sl_next=(sl_next==(NSLOT-1)*SLOTB)?0:sl_next+SLOTB;}while(0)
;   #define ENDW(tt) do{ if((tt)+3<NT){ if constexpr(VM==2){WAIT_BAR(3);}else{WAIT_BAR(2);} } else if((tt)+2<NT){ if constexpr(VM==2){WAIT_BAR(2);}else{WAIT_BAR(1);} } else {WAIT_BAR(0);} }while(0)
; template<int THRL,int VM,bool NOMAX> __device__ __forceinline__ void attn_unit(const bf16*Qb,const bf16*__restrict__ Kh,const bf16*__restrict__ Vh,bf16*Ob,const int NT,const int sp,float*wscr,char*shm){
;     ...
;   for(;t+1<NT;t+=2){
;     STEP(pB0,pB1,pA0,pA1,t,(t+3<NT),(t+1<NT),(t+1<NT));       ENDW(t);   RESC(); ROT();
;     STEP(pA0,pA1,pB0,pB1,t+1,(t+4<NT),(t+2<NT),(t+2<NT));     ENDW(t+1); RESC(); ROT();
	ds_read_b64_tr_b16 v[178:179], v188 offset:40960
	ds_read_b64_tr_b16 v[180:181], v188 offset:41472
	v_add_f32_e32 v76, v96, v97
	ds_read_b128 v[72:75], v168
	v_add_f32_e32 v76, v98, v76
	v_add_f32_e32 v76, v99, v76
	v_add_f32_e32 v76, v100, v76
	v_add_f32_e32 v76, v101, v76
	v_cvt_pk_bf16_f32 v156, v96, v97
	v_cvt_pk_bf16_f32 v157, v98, v99
	s_waitcnt lgkmcnt(0)
	v_mfma_f32_32x32x16_bf16 v[112:127], v[68:71], v[72:75], 0
	ds_read_b64_tr_b16 v[96:97], v188 offset:45056
	ds_read_b64_tr_b16 v[98:99], v188 offset:45568
	ds_read_b128 v[68:71], v168
	v_add_f32_e32 v72, v102, v76
	v_add_f32_e32 v72, v103, v72
	v_add_f32_e32 v72, v104, v72
	v_add_f32_e32 v144, v105, v72
	s_waitcnt lgkmcnt(0)
	v_mfma_f32_32x32x16_bf16 v[64:79], v[64:67], v[68:71], 0
	v_cvt_pk_bf16_f32 v158, v100, v101
	v_cvt_pk_bf16_f32 v159, v102, v103
	ds_read_b64_tr_b16 v[100:101], v188 offset:41984
	ds_read_b64_tr_b16 v[102:103], v188 offset:42496
	ds_read_b128 v[190:193], v168 offset:1024
	v_add_f32_e32 v144, v106, v144
	v_add_f32_e32 v144, v107, v144
	v_add_f32_e32 v144, v108, v144
	v_add_f32_e32 v144, v109, v144
	v_cvt_pk_bf16_f32 v152, v104, v105
	v_cvt_pk_bf16_f32 v153, v106, v107
	s_waitcnt lgkmcnt(0)
	v_mfma_f32_32x32x16_bf16 v[112:127], v[164:167], v[190:193], v[112:127]
	ds_read_b64_tr_b16 v[104:105], v188 offset:46080
	ds_read_b64_tr_b16 v[106:107], v188 offset:46592
	ds_read_b128 v[164:167], v168 offset:1024
	v_add_f32_e32 v144, v110, v144
	v_add_f32_e32 v144, v111, v144
	v_add_f32_e32 v144, v80, v144
	v_add_f32_e32 v144, v81, v144
	s_waitcnt lgkmcnt(0)
	v_mfma_f32_32x32x16_bf16 v[64:79], v[140:143], v[164:167], v[64:79]
	v_cvt_pk_bf16_f32 v154, v108, v109
	v_cvt_pk_bf16_f32 v155, v110, v111
	ds_read_b64_tr_b16 v[108:109], v188 offset:43008
	ds_read_b64_tr_b16 v[110:111], v188 offset:43520
	ds_read_b128 v[140:143], v168 offset:2048
	v_add_f32_e32 v144, v82, v144
	v_add_f32_e32 v144, v83, v144
	v_add_f32_e32 v144, v84, v144
	v_add_f32_e32 v144, v85, v144
	v_cvt_pk_bf16_f32 v148, v80, v81
	v_cvt_pk_bf16_f32 v149, v82, v83
	s_waitcnt lgkmcnt(0)
	v_mfma_f32_32x32x16_bf16 v[112:127], v[160:163], v[140:143], v[112:127]
	ds_read_b64_tr_b16 v[190:191], v188 offset:47104
	ds_read_b64_tr_b16 v[192:193], v188 offset:47616
	ds_read_b128 v[80:83], v168 offset:2048
	v_add_f32_e32 v140, v86, v144
	v_add_f32_e32 v140, v87, v140
	v_add_f32_e32 v140, v88, v140
	v_add_f32_e32 v140, v89, v140
	s_waitcnt lgkmcnt(0)
	v_mfma_f32_32x32x16_bf16 v[64:79], v[132:135], v[80:83], v[64:79]
	v_cvt_pk_bf16_f32 v150, v84, v85
	v_cvt_pk_bf16_f32 v151, v86, v87
	ds_read_b64_tr_b16 v[84:85], v188 offset:44032
	ds_read_b64_tr_b16 v[86:87], v188 offset:44544
	ds_read_b128 v[80:83], v168 offset:3072
	v_add_f32_e32 v132, v90, v140
	v_add_f32_e32 v132, v91, v132
	v_add_f32_e32 v132, v92, v132
	v_add_f32_e32 v132, v93, v132
	v_cvt_pk_bf16_f32 v144, v88, v89
	v_cvt_pk_bf16_f32 v145, v90, v91
	s_waitcnt lgkmcnt(0)
	v_mfma_f32_32x32x16_bf16 v[112:127], v[136:139], v[80:83], v[112:127]
	ds_read_b64_tr_b16 v[88:89], v188 offset:48128
	ds_read_b64_tr_b16 v[90:91], v188 offset:48640
	ds_read_b128 v[80:83], v168 offset:3072
	v_add_f32_e32 v132, v94, v132
	v_add_f32_e32 v132, v95, v132
	v_add_f32_e32 v132, 0, v132
	v_cvt_pk_bf16_f32 v146, v92, v93
	s_waitcnt lgkmcnt(0)
	v_mfma_f32_32x32x16_bf16 v[64:79], v[128:131], v[80:83], v[64:79]
	v_cvt_pk_bf16_f32 v147, v94, v95
	v_lshl_add_u64 v[80:81], v[170:171], 0, s[64:65]
	s_mov_b32 s17, m0
	s_mov_b32 m0, s16
	s_nop 0
	global_load_lds_dwordx4 v[80:81], off
	s_mov_b32 m0, s17
	v_lshl_add_u64 v[80:81], v[172:173], 0, s[64:65]
	s_mov_b32 s16, m0
	s_mov_b32 m0, s35
	s_nop 0
	global_load_lds_dwordx4 v[80:81], off
	s_mov_b32 m0, s16
	v_add_f32_e32 v174, v174, v132
	v_mfma_f32_32x32x16_bf16 v[48:63], v[156:159], v[178:181], v[48:63]
	ds_read_b64_tr_b16 v[92:93], v188 offset:49152
	ds_read_b64_tr_b16 v[94:95], v188 offset:49664
	v_exp_f32_e32 v112, v112
	v_exp_f32_e32 v113, v113
	v_mfma_f32_32x32x16_bf16 v[32:47], v[156:159], v[96:99], v[32:47]
	ds_read_b64_tr_b16 v[170:171], v188 offset:53248
	ds_read_b64_tr_b16 v[172:173], v188 offset:53760
	v_exp_f32_e32 v114, v114
	v_exp_f32_e32 v115, v115
	ds_read_b128 v[80:83], v189
	ds_read_b128 v[96:99], v189 offset:512
	v_mfma_f32_32x32x16_bf16 v[48:63], v[152:155], v[100:103], v[48:63]
	ds_read_b64_tr_b16 v[178:179], v188 offset:50176
	ds_read_b64_tr_b16 v[180:181], v188 offset:50688
	v_exp_f32_e32 v116, v116
	v_exp_f32_e32 v117, v117
	ds_read_b128 v[164:167], v189 offset:2048
	ds_read_b128 v[140:143], v189 offset:2560
	v_mfma_f32_32x32x16_bf16 v[32:47], v[152:155], v[104:107], v[32:47]
	ds_read_b64_tr_b16 v[100:101], v188 offset:54272
	ds_read_b64_tr_b16 v[102:103], v188 offset:54784
	v_exp_f32_e32 v118, v118
	v_exp_f32_e32 v119, v119
	ds_read_b128 v[160:163], v189 offset:4096
	ds_read_b128 v[132:135], v189 offset:4608
	v_mfma_f32_32x32x16_bf16 v[48:63], v[148:151], v[108:111], v[48:63]
	ds_read_b64_tr_b16 v[104:105], v188 offset:51200
	ds_read_b64_tr_b16 v[106:107], v188 offset:51712
	v_exp_f32_e32 v120, v120
	v_exp_f32_e32 v121, v121
	ds_read_b128 v[136:139], v189 offset:6144
	ds_read_b128 v[128:131], v189 offset:6656
	v_mfma_f32_32x32x16_bf16 v[32:47], v[148:151], v[190:193], v[32:47]
	ds_read_b64_tr_b16 v[108:109], v188 offset:55296
	ds_read_b64_tr_b16 v[110:111], v188 offset:55808
	v_exp_f32_e32 v122, v122
	v_exp_f32_e32 v123, v123
	v_mfma_f32_32x32x16_bf16 v[48:63], v[144:147], v[84:87], v[48:63]
	ds_read_b64_tr_b16 v[190:191], v188 offset:52224
	ds_read_b64_tr_b16 v[192:193], v188 offset:52736
	v_exp_f32_e32 v124, v124
	v_exp_f32_e32 v125, v125
	v_mfma_f32_32x32x16_bf16 v[32:47], v[144:147], v[88:91], v[32:47]
	ds_read_b64_tr_b16 v[84:85], v188 offset:56320
	ds_read_b64_tr_b16 v[86:87], v188 offset:56832
	v_exp_f32_e32 v126, v126
	v_exp_f32_e32 v127, v127
	s_waitcnt lgkmcnt(14)
	v_mfma_f32_32x32x16_bf16 v[16:31], v[156:159], v[92:95], v[16:31]
	v_exp_f32_e32 v64, v64
	v_exp_f32_e32 v65, v65
	v_mfma_f32_32x32x16_bf16 v[0:15], v[156:159], v[170:173], v[0:15]
	v_exp_f32_e32 v66, v66
	v_exp_f32_e32 v67, v67
	v_mfma_f32_32x32x16_bf16 v[16:31], v[152:155], v[178:181], v[16:31]
	v_exp_f32_e32 v68, v68
	v_exp_f32_e32 v69, v69
	s_waitcnt lgkmcnt(12)
	v_mfma_f32_32x32x16_bf16 v[0:15], v[152:155], v[100:103], v[0:15]
	v_exp_f32_e32 v70, v70
	v_exp_f32_e32 v71, v71
	s_waitcnt lgkmcnt(8)
	v_mfma_f32_32x32x16_bf16 v[16:31], v[148:151], v[104:107], v[16:31]
	v_exp_f32_e32 v72, v72
	v_exp_f32_e32 v73, v73
	s_waitcnt lgkmcnt(4)
	v_mfma_f32_32x32x16_bf16 v[0:15], v[148:151], v[108:111], v[0:15]
	v_exp_f32_e32 v74, v74
	v_exp_f32_e32 v75, v75
	s_waitcnt lgkmcnt(2)
	v_mfma_f32_32x32x16_bf16 v[16:31], v[144:147], v[190:193], v[16:31]
	v_exp_f32_e32 v76, v76
	v_exp_f32_e32 v77, v77
	s_waitcnt lgkmcnt(0)
	v_mfma_f32_32x32x16_bf16 v[0:15], v[144:147], v[84:87], v[0:15]
	v_exp_f32_e32 v78, v78
	v_exp_f32_e32 v79, v79
	s_waitcnt vmcnt(0) lgkmcnt(0)
	s_barrier
	ds_read_b64_tr_b16 v[170:171], v188 offset:57344
	ds_read_b64_tr_b16 v[172:173], v188 offset:57856
	v_add_f32_e32 v88, v112, v113
	ds_read_b128 v[84:87], v168
	v_add_f32_e32 v88, v114, v88
	v_add_f32_e32 v88, v115, v88
	v_add_f32_e32 v88, v116, v88
	v_add_f32_e32 v104, v117, v88
	v_cvt_pk_bf16_f32 v156, v112, v113
	v_cvt_pk_bf16_f32 v157, v114, v115
	s_waitcnt lgkmcnt(0)
	v_mfma_f32_32x32x16_bf16 v[80:95], v[80:83], v[84:87], 0
	ds_read_b64_tr_b16 v[112:113], v188 offset:61440
	ds_read_b64_tr_b16 v[114:115], v188 offset:61952
	ds_read_b128 v[100:103], v168
	v_add_f32_e32 v104, v118, v104
	v_add_f32_e32 v104, v119, v104
	v_add_f32_e32 v104, v120, v104
	v_add_f32_e32 v144, v121, v104
	v_cvt_pk_bf16_f32 v158, v116, v117
	v_cvt_pk_bf16_f32 v159, v118, v119
	s_waitcnt lgkmcnt(0)
	v_mfma_f32_32x32x16_bf16 v[96:111], v[96:99], v[100:103], 0
	ds_read_b64_tr_b16 v[116:117], v188 offset:58368
	ds_read_b64_tr_b16 v[118:119], v188 offset:58880
	ds_read_b128 v[178:181], v168 offset:1024
	v_add_f32_e32 v144, v122, v144
	v_add_f32_e32 v144, v123, v144
	v_add_f32_e32 v144, v124, v144
	v_add_f32_e32 v144, v125, v144
	v_cvt_pk_bf16_f32 v152, v120, v121
	v_cvt_pk_bf16_f32 v153, v122, v123
	s_waitcnt lgkmcnt(0)
	v_mfma_f32_32x32x16_bf16 v[80:95], v[164:167], v[178:181], v[80:95]
	ds_read_b64_tr_b16 v[120:121], v188 offset:62464
	ds_read_b64_tr_b16 v[122:123], v188 offset:62976
	ds_read_b128 v[164:167], v168 offset:1024
	v_add_f32_e32 v144, v126, v144
	v_add_f32_e32 v144, v127, v144
	v_add_f32_e32 v144, v64, v144
	v_add_f32_e32 v144, v65, v144
	v_cvt_pk_bf16_f32 v154, v124, v125
	v_cvt_pk_bf16_f32 v155, v126, v127
	s_waitcnt lgkmcnt(0)
	v_mfma_f32_32x32x16_bf16 v[96:111], v[140:143], v[164:167], v[96:111]
	ds_read_b64_tr_b16 v[124:125], v188 offset:59392
	ds_read_b64_tr_b16 v[126:127], v188 offset:59904
	ds_read_b128 v[140:143], v168 offset:2048
	v_add_f32_e32 v144, v66, v144
	v_add_f32_e32 v144, v67, v144
	v_add_f32_e32 v144, v68, v144
	v_add_f32_e32 v144, v69, v144
	v_cvt_pk_bf16_f32 v148, v64, v65
	v_cvt_pk_bf16_f32 v149, v66, v67
	s_waitcnt lgkmcnt(0)
	v_mfma_f32_32x32x16_bf16 v[80:95], v[160:163], v[140:143], v[80:95]
	ds_read_b64_tr_b16 v[64:65], v188 offset:63488
	ds_read_b64_tr_b16 v[66:67], v188 offset:64000
	ds_read_b128 v[140:143], v168 offset:2048
	v_add_f32_e32 v144, v70, v144
	v_add_f32_e32 v144, v71, v144
	v_add_f32_e32 v144, v72, v144
	v_add_f32_e32 v144, v73, v144
	v_cvt_pk_bf16_f32 v150, v68, v69
	v_cvt_pk_bf16_f32 v151, v70, v71
	s_waitcnt lgkmcnt(0)
	v_mfma_f32_32x32x16_bf16 v[96:111], v[132:135], v[140:143], v[96:111]
	ds_read_b64_tr_b16 v[68:69], v188 offset:60416
	ds_read_b64_tr_b16 v[70:71], v188 offset:60928
	ds_read_b128 v[132:135], v168 offset:3072
	v_add_f32_e32 v140, v74, v144
	v_add_f32_e32 v140, v75, v140
	v_add_f32_e32 v140, v76, v140
	v_add_f32_e32 v140, v77, v140
	v_cvt_pk_bf16_f32 v144, v72, v73
	v_cvt_pk_bf16_f32 v145, v74, v75
	s_waitcnt lgkmcnt(0)
	v_mfma_f32_32x32x16_bf16 v[80:95], v[136:139], v[132:135], v[80:95]
	ds_read_b64_tr_b16 v[72:73], v188 offset:64512
	ds_read_b64_tr_b16 v[74:75], v188 offset:65024
	ds_read_b128 v[132:135], v168 offset:3072
	v_add_f32_e32 v136, v78, v140
	v_add_f32_e32 v136, v79, v136
	v_add_f32_e32 v136, 0, v136
	v_cvt_pk_bf16_f32 v146, v76, v77
	v_cvt_pk_bf16_f32 v147, v78, v79
	s_waitcnt lgkmcnt(0)
	v_mfma_f32_32x32x16_bf16 v[96:111], v[128:131], v[132:135], v[96:111]
	v_mfma_f32_32x32x16_bf16 v[48:63], v[156:159], v[170:173], v[48:63]
	ds_read_b64_tr_b16 v[76:77], v177 offset:40960
	ds_read_b64_tr_b16 v[78:79], v177 offset:41472
	v_exp_f32_e32 v80, v80
	v_exp_f32_e32 v81, v81
	v_mfma_f32_32x32x16_bf16 v[32:47], v[156:159], v[112:115], v[32:47]
	ds_read_b64_tr_b16 v[128:129], v177 offset:45056
	ds_read_b64_tr_b16 v[130:131], v177 offset:45568
	v_exp_f32_e32 v82, v82
	v_exp_f32_e32 v83, v83
	v_mfma_f32_32x32x16_bf16 v[48:63], v[152:155], v[116:119], v[48:63]
	ds_read_b64_tr_b16 v[112:113], v177 offset:41984
	ds_read_b64_tr_b16 v[114:115], v177 offset:42496
	v_exp_f32_e32 v84, v84
	v_exp_f32_e32 v85, v85
	v_mfma_f32_32x32x16_bf16 v[32:47], v[152:155], v[120:123], v[32:47]
	ds_read_b64_tr_b16 v[116:117], v177 offset:46080
	ds_read_b64_tr_b16 v[118:119], v177 offset:46592
	v_exp_f32_e32 v86, v86
	v_exp_f32_e32 v87, v87
	v_mfma_f32_32x32x16_bf16 v[48:63], v[148:151], v[124:127], v[48:63]
	ds_read_b64_tr_b16 v[120:121], v177 offset:43008
	ds_read_b64_tr_b16 v[122:123], v177 offset:43520
	v_exp_f32_e32 v88, v88
	v_exp_f32_e32 v89, v89
	v_mfma_f32_32x32x16_bf16 v[32:47], v[148:151], v[64:67], v[32:47]
	ds_read_b64_tr_b16 v[124:125], v177 offset:47104
	ds_read_b64_tr_b16 v[126:127], v177 offset:47616
	v_exp_f32_e32 v90, v90
	v_exp_f32_e32 v91, v91
	v_mfma_f32_32x32x16_bf16 v[48:63], v[144:147], v[68:71], v[48:63]
	ds_read_b64_tr_b16 v[64:65], v177 offset:44032
	ds_read_b64_tr_b16 v[66:67], v177 offset:44544
	v_exp_f32_e32 v92, v92
	v_exp_f32_e32 v93, v93
	v_mfma_f32_32x32x16_bf16 v[32:47], v[144:147], v[72:75], v[32:47]
	ds_read_b64_tr_b16 v[68:69], v177 offset:48128
	ds_read_b64_tr_b16 v[70:71], v177 offset:48640
	v_exp_f32_e32 v94, v94
	v_exp_f32_e32 v95, v95
	s_waitcnt lgkmcnt(14)
	v_mfma_f32_32x32x16_bf16 v[16:31], v[156:159], v[76:79], v[16:31]
	v_exp_f32_e32 v96, v96
	v_exp_f32_e32 v97, v97
	s_waitcnt lgkmcnt(12)
; #define SBAR() __builtin_amdgcn_sched_barrier(0)
;   #define RESC() do{ if(!NOMAX&&resc){ asm volatile("s_waitcnt lgkmcnt(0)":::"memory"); \
;       _Pragma("unroll") for(int d_=0;d_<2*VM;++d_) _Pragma("unroll") for(int r=0;r<16;++r)o[d_][r]*=wsf[crow(r,hi)]; } }while(0)
;   #define PKW(P,B) cvtpk_s(P[B],P[B+1])
; template<int THRL,int VM,bool NOMAX> __device__ __forceinline__ void attn_unit(const bf16*Qb,const bf16*__restrict__ Kh,const bf16*__restrict__ Vh,bf16*Ob,const int NT,const int sp,float*wscr,char*shm){
;     ...
;   STEP(pB0,pB1,pA0,pA1,NT-1,false,false,false); RESC();
;   { float sacc=pB0[0]+pB0[1]; _Pragma("unroll") for(int r=2;r<16;++r)sacc+=pB0[r]; _Pragma("unroll") for(int r=0;r<16;++r)sacc+=pB1[r]; l_reg+=sacc;
;     pw0=(u32x4){PKW(pB0,0),PKW(pB0,2),PKW(pB0,4),PKW(pB0,6)};pw1=(u32x4){PKW(pB0,8),PKW(pB0,10),PKW(pB0,12),PKW(pB0,14)};pw2=(u32x4){PKW(pB1,0),PKW(pB1,2),PKW(pB1,4),PKW(pB1,6)};pw3=(u32x4){PKW(pB1,8),PKW(pB1,10),PKW(pB1,12),PKW(pB1,14)};
;     SBAR(); pv(o,vb0+VM*sl_cur,PAF(0),PAF(1),PAF(2),PAF(3)); if constexpr(VM==2) pv(o+2,vb0+VM*sl_cur+8192,PAF(0),PAF(1),PAF(2),PAF(3)); }
;     ...
;   {auto rr=__builtin_amdgcn_permlane32_swap(__float_as_uint(l_reg),__float_as_uint(l_reg),false,false);l_reg=__uint_as_float(rr[0])+__uint_as_float(rr[1]);}
;   if(hi==0)wsf[32+r32]=l_reg;asm volatile("s_waitcnt lgkmcnt(0)":::"memory");
	v_mfma_f32_32x32x16_bf16 v[0:15], v[156:159], v[128:131], v[0:15]
	v_exp_f32_e32 v98, v98
	v_exp_f32_e32 v99, v99
	s_waitcnt lgkmcnt(10)
	v_mfma_f32_32x32x16_bf16 v[16:31], v[152:155], v[112:115], v[16:31]
	v_exp_f32_e32 v100, v100
	v_exp_f32_e32 v101, v101
	s_waitcnt lgkmcnt(8)
	v_mfma_f32_32x32x16_bf16 v[0:15], v[152:155], v[116:119], v[0:15]
	v_exp_f32_e32 v102, v102
	v_exp_f32_e32 v103, v103
	s_waitcnt lgkmcnt(6)
	v_mfma_f32_32x32x16_bf16 v[16:31], v[148:151], v[120:123], v[16:31]
	v_exp_f32_e32 v104, v104
	v_exp_f32_e32 v105, v105
	s_waitcnt lgkmcnt(4)
	v_mfma_f32_32x32x16_bf16 v[0:15], v[148:151], v[124:127], v[0:15]
	v_exp_f32_e32 v106, v106
	v_exp_f32_e32 v107, v107
	s_waitcnt lgkmcnt(2)
	v_mfma_f32_32x32x16_bf16 v[16:31], v[144:147], v[64:67], v[16:31]
	v_exp_f32_e32 v108, v108
	v_exp_f32_e32 v109, v109
	s_waitcnt lgkmcnt(0)
	v_mfma_f32_32x32x16_bf16 v[0:15], v[144:147], v[68:71], v[0:15]
	v_exp_f32_e32 v110, v110
	v_exp_f32_e32 v111, v111
	v_add_f32_e32 v64, v80, v81
	v_add_f32_e32 v64, v82, v64
	v_add_f32_e32 v64, v83, v64
	v_add_f32_e32 v64, v84, v64
	v_add_f32_e32 v64, v85, v64
	v_add_f32_e32 v64, v86, v64
	v_add_f32_e32 v64, v87, v64
	v_add_f32_e32 v64, v88, v64
	v_add_f32_e32 v64, v89, v64
	v_add_f32_e32 v64, v90, v64
	v_add_f32_e32 v64, v91, v64
	v_add_f32_e32 v64, v92, v64
	v_add_f32_e32 v64, v93, v64
	v_add_f32_e32 v64, v94, v64
	v_add_f32_e32 v64, v95, v64
	v_add_f32_e32 v64, v64, v96
	v_add_f32_e32 v64, v97, v64
	v_add_f32_e32 v64, v98, v64
	v_add_f32_e32 v64, v99, v64
	v_add_f32_e32 v64, v100, v64
	v_add_f32_e32 v64, v101, v64
	v_add_f32_e32 v64, v102, v64
	v_add_f32_e32 v64, v103, v64
	v_add_f32_e32 v64, v104, v64
	v_add_f32_e32 v64, v105, v64
	v_add_f32_e32 v64, v106, v64
	v_add_f32_e32 v64, v107, v64
	v_add_f32_e32 v64, v108, v64
	v_add_f32_e32 v64, v109, v64
	v_add_f32_e32 v64, v110, v64
	v_add_f32_e32 v64, v111, v64
	v_add_f32_e32 v65, v174, v136
	v_add_f32_e32 v64, v65, v64
	v_cvt_pk_bf16_f32 v66, v80, v81
	v_cvt_pk_bf16_f32 v67, v82, v83
	v_cvt_pk_bf16_f32 v68, v84, v85
	v_cvt_pk_bf16_f32 v69, v86, v87
	v_cvt_pk_bf16_f32 v70, v88, v89
	v_cvt_pk_bf16_f32 v71, v90, v91
	v_cvt_pk_bf16_f32 v72, v92, v93
	v_cvt_pk_bf16_f32 v73, v94, v95
	v_cvt_pk_bf16_f32 v74, v96, v97
	v_cvt_pk_bf16_f32 v75, v98, v99
	v_cvt_pk_bf16_f32 v76, v100, v101
	v_cvt_pk_bf16_f32 v77, v102, v103
	v_cvt_pk_bf16_f32 v78, v104, v105
	v_cvt_pk_bf16_f32 v79, v106, v107
	v_cvt_pk_bf16_f32 v80, v108, v109
	v_cvt_pk_bf16_f32 v81, v110, v111
	ds_read_b64_tr_b16 v[82:83],v176 offset:0
	ds_read_b64_tr_b16 v[84:85],v176 offset:512
	ds_read_b64_tr_b16 v[86:87],v176 offset:1024
	ds_read_b64_tr_b16 v[88:89],v176 offset:1536
	ds_read_b64_tr_b16 v[90:91],v176 offset:2048
	ds_read_b64_tr_b16 v[92:93],v176 offset:2560
	ds_read_b64_tr_b16 v[94:95],v176 offset:3072
	ds_read_b64_tr_b16 v[96:97],v176 offset:3584
	s_waitcnt lgkmcnt(0)
	s_nop 0
	v_mfma_f32_32x32x16_bf16 v[48:63], v[66:69], v[82:85], v[48:63]
	ds_read_b64_tr_b16 v[82:83],v176 offset:4096
	ds_read_b64_tr_b16 v[84:85],v176 offset:4608
	v_mfma_f32_32x32x16_bf16 v[48:63], v[70:73], v[86:89], v[48:63]
	ds_read_b64_tr_b16 v[86:87],v176 offset:5120
	ds_read_b64_tr_b16 v[88:89],v176 offset:5632
	v_mfma_f32_32x32x16_bf16 v[48:63], v[74:77], v[90:93], v[48:63]
	ds_read_b64_tr_b16 v[90:91],v176 offset:6144
	ds_read_b64_tr_b16 v[92:93],v176 offset:6656
	ds_read_b64_tr_b16 v[98:99],v176 offset:7168
	ds_read_b64_tr_b16 v[100:101],v176 offset:7680
	s_waitcnt lgkmcnt(0)
	v_mfma_f32_32x32x16_bf16 v[48:63], v[78:81], v[94:97], v[48:63]
	v_mfma_f32_32x32x16_bf16 v[32:47], v[66:69], v[82:85], v[32:47]
	v_add_u32_e32 v65, 0x2000, v176
	ds_read_b64_tr_b16 v[82:83],v65 offset:0
	ds_read_b64_tr_b16 v[84:85],v65 offset:512
	v_mfma_f32_32x32x16_bf16 v[32:47], v[70:73], v[86:89], v[32:47]
	ds_read_b64_tr_b16 v[86:87],v65 offset:1024
	ds_read_b64_tr_b16 v[88:89],v65 offset:1536
	v_mfma_f32_32x32x16_bf16 v[32:47], v[74:77], v[90:93], v[32:47]
	ds_read_b64_tr_b16 v[90:91],v65 offset:2048
	ds_read_b64_tr_b16 v[92:93],v65 offset:2560
	ds_read_b64_tr_b16 v[94:95],v65 offset:3072
	ds_read_b64_tr_b16 v[96:97],v65 offset:3584
	s_waitcnt lgkmcnt(0)
	v_mfma_f32_32x32x16_bf16 v[32:47], v[78:81], v[98:101], v[32:47]
	v_mfma_f32_32x32x16_bf16 v[16:31], v[66:69], v[82:85], v[16:31]
	ds_read_b64_tr_b16 v[82:83],v65 offset:4096
	ds_read_b64_tr_b16 v[84:85],v65 offset:4608
	v_mfma_f32_32x32x16_bf16 v[16:31], v[70:73], v[86:89], v[16:31]
	ds_read_b64_tr_b16 v[86:87],v65 offset:5120
	ds_read_b64_tr_b16 v[88:89],v65 offset:5632
	v_mfma_f32_32x32x16_bf16 v[16:31], v[74:77], v[90:93], v[16:31]
	ds_read_b64_tr_b16 v[90:91],v65 offset:6144
	ds_read_b64_tr_b16 v[92:93],v65 offset:6656
	ds_read_b64_tr_b16 v[98:99],v65 offset:7168
	ds_read_b64_tr_b16 v[100:101],v65 offset:7680
	s_waitcnt lgkmcnt(0)
	v_mfma_f32_32x32x16_bf16 v[16:31], v[78:81], v[94:97], v[16:31]
	v_mfma_f32_32x32x16_bf16 v[0:15], v[66:69], v[82:85], v[0:15]
	v_mov_b32_e32 v65, v64
	s_nop 1
	v_permlane32_swap_b32_e32 v64, v65
	v_cmp_gt_u32_e32 vcc, 32, v187
	v_mfma_f32_32x32x16_bf16 v[0:15], v[70:73], v[86:89], v[0:15]
	v_mfma_f32_32x32x16_bf16 v[0:15], v[74:77], v[90:93], v[0:15]
	v_mfma_f32_32x32x16_bf16 v[0:15], v[78:81], v[98:101], v[0:15]
	s_and_saveexec_b64 s[16:17], vcc
	s_cbranch_execz .LBB0_870
	v_add_f32_e32 v64, v64, v65
	v_lshl_add_u32 v65, v186, 2, s34
	ds_write_b32 v65, v64 offset:128
	s_branch .LBB0_870

; #define WAIT_BAR(N) asm volatile("s_waitcnt vmcnt(" #N ") lgkmcnt(0)\n\ts_barrier":::"memory")
;   #define RESC() do{ if(!NOMAX&&resc){ asm volatile("s_waitcnt lgkmcnt(0)":::"memory"); \
;       _Pragma("unroll") for(int d_=0;d_<2*VM;++d_) _Pragma("unroll") for(int r=0;r<16;++r)o[d_][r]*=wsf[crow(r,hi)]; } }while(0)
;   #define ROT() do{sl_prev=sl_cur;sl_cur=sl_next;sl_next=(sl_next==(NSLOT-1)*SLOTB)?0:sl_next+SLOTB;}while(0)
; template<int THRL,int VM,bool NOMAX> __device__ __forceinline__ void attn_unit(const bf16*Qb,const bf16*__restrict__ Kh,const bf16*__restrict__ Vh,bf16*Ob,const int NT,const int sp,float*wscr,char*shm){
;     ...
;   for(;t+5<NT;t+=2){
;     STEP(pB0,pB1,pA0,pA1,t,true,true,true);     if constexpr(VM==2){WAIT_BAR(3);}else{WAIT_BAR(2);} RESC(); ROT();
;     STEP(pA0,pA1,pB0,pB1,t+1,true,true,true);   if constexpr(VM==2){WAIT_BAR(3);}else{WAIT_BAR(2);} RESC(); ROT();
.LBB0_882:
	v_mfma_f32_32x32x16_bf16 v[96:111], v[84:87], v[156:159], 0
	v_add_u32_e32 v187, s54, v182
	ds_read_b64_tr_b16 v[188:189], v187 offset:24576
	ds_read_b64_tr_b16 v[190:191], v187 offset:25088
	v_add_f32_e32 v88, v64, v65
	v_add_f32_e32 v88, v66, v88
	v_add_f32_e32 v88, v67, v88
	v_add_f32_e32 v88, v68, v88
	v_add_f32_e32 v88, v69, v88
	v_cvt_pk_bf16_f32 v140, v64, v65
	v_cvt_pk_bf16_f32 v141, v66, v67
	ds_read_b64_tr_b16 v[64:65], v187 offset:28672
	ds_read_b64_tr_b16 v[66:67], v187 offset:29184
	v_add_f32_e32 v84, v70, v88
	v_add_f32_e32 v84, v71, v84
	v_add_f32_e32 v84, v72, v84
	v_add_f32_e32 v128, v73, v84
	s_waitcnt lgkmcnt(10)
	v_mfma_f32_32x32x16_bf16 v[80:95], v[80:83], v[156:159], 0
	v_cvt_pk_bf16_f32 v142, v68, v69
	v_cvt_pk_bf16_f32 v143, v70, v71
	ds_read_b64_tr_b16 v[68:69], v187 offset:25600
	ds_read_b64_tr_b16 v[70:71], v187 offset:26112
	v_add_f32_e32 v128, v74, v128
	v_add_f32_e32 v128, v75, v128
	v_add_f32_e32 v128, v76, v128
	v_add_f32_e32 v128, v77, v128
	v_cvt_pk_bf16_f32 v136, v72, v73
	v_cvt_pk_bf16_f32 v137, v74, v75
	s_waitcnt lgkmcnt(11)
	v_mfma_f32_32x32x16_bf16 v[96:111], v[164:167], v[152:155], v[96:111]
	ds_read_b64_tr_b16 v[72:73], v187 offset:29696
	ds_read_b64_tr_b16 v[74:75], v187 offset:30208
	s_waitcnt lgkmcnt(12)
	v_mfma_f32_32x32x16_bf16 v[80:95], v[160:163], v[152:155], v[80:95]
	v_add_f32_e32 v128, v78, v128
	v_add_f32_e32 v128, v79, v128
	v_add_f32_e32 v128, v48, v128
	v_add_f32_e32 v128, v49, v128
	v_cvt_pk_bf16_f32 v138, v76, v77
	v_cvt_pk_bf16_f32 v139, v78, v79
	ds_read_b64_tr_b16 v[76:77], v187 offset:26624
	ds_read_b64_tr_b16 v[78:79], v187 offset:27136
	v_add_f32_e32 v128, v50, v128
	v_add_f32_e32 v128, v51, v128
	v_add_f32_e32 v128, v52, v128
	v_add_f32_e32 v128, v53, v128
	v_cvt_pk_bf16_f32 v132, v48, v49
	v_cvt_pk_bf16_f32 v133, v50, v51
	s_waitcnt lgkmcnt(13)
	v_mfma_f32_32x32x16_bf16 v[96:111], v[124:127], v[148:151], v[96:111]
	ds_read_b64_tr_b16 v[48:49], v187 offset:30720
	ds_read_b64_tr_b16 v[50:51], v187 offset:31232
	s_waitcnt lgkmcnt(14)
	v_mfma_f32_32x32x16_bf16 v[80:95], v[120:123], v[148:151], v[80:95]
	v_add_f32_e32 v124, v54, v128
	v_add_f32_e32 v124, v55, v124
	v_add_f32_e32 v124, v56, v124
	v_add_f32_e32 v124, v57, v124
	v_cvt_pk_bf16_f32 v134, v52, v53
	v_cvt_pk_bf16_f32 v135, v54, v55
	ds_read_b64_tr_b16 v[52:53], v187 offset:27648
	ds_read_b64_tr_b16 v[54:55], v187 offset:28160
	v_add_f32_e32 v120, v58, v124
	v_add_f32_e32 v120, v59, v120
	v_add_f32_e32 v120, v60, v120
	v_add_f32_e32 v120, v61, v120
	v_cvt_pk_bf16_f32 v128, v56, v57
	v_cvt_pk_bf16_f32 v129, v58, v59
	s_waitcnt lgkmcnt(14)
	v_mfma_f32_32x32x16_bf16 v[96:111], v[116:119], v[144:147], v[96:111]
	ds_read_b64_tr_b16 v[56:57], v187 offset:31744
	ds_read_b64_tr_b16 v[58:59], v187 offset:32256
	v_mfma_f32_32x32x16_bf16 v[80:95], v[112:115], v[144:147], v[80:95]
	v_add_f32_e32 v116, v62, v120
	v_add_f32_e32 v116, v63, v116
	v_add_f32_e32 v116, 0, v116
	v_cvt_pk_bf16_f32 v130, v60, v61
	v_cvt_pk_bf16_f32 v131, v62, v63
	v_lshl_add_u64 v[60:61], v[176:177], 0, s[38:39]
	s_add_i32 s53, s52, s33
	s_mov_b32 s54, m0
	s_mov_b32 m0, s53
	s_nop 0
	global_load_lds_dwordx4 v[60:61], off
	s_mov_b32 m0, s54
	v_lshl_add_u64 v[60:61], v[174:175], 0, s[38:39]
	s_add_i32 s53, s35, s16
	s_mov_b32 s54, m0
	s_mov_b32 m0, s53
	s_nop 0
	global_load_lds_dwordx4 v[60:61], off
	s_mov_b32 m0, s54
	v_add_f32_e32 v202, v186, v116
	s_waitcnt lgkmcnt(14)
	v_mfma_f32_32x32x16_bf16 v[16:31], v[140:143], v[188:191], v[16:31]
	v_exp_f32_e32 v96, v96
	v_exp_f32_e32 v97, v97
	v_exp_f32_e32 v98, v98
	v_exp_f32_e32 v99, v99
	s_waitcnt lgkmcnt(12)
	v_mfma_f32_32x32x16_bf16 v[32:47], v[140:143], v[64:67], v[32:47]
	v_exp_f32_e32 v100, v100
	v_exp_f32_e32 v101, v101
	v_exp_f32_e32 v102, v102
	v_exp_f32_e32 v103, v103
	v_add_u32_e32 v64, s35, v183
	ds_read_b128 v[60:63], v64
	ds_read_b128 v[112:115], v64 offset:512
	s_waitcnt lgkmcnt(12)
	v_mfma_f32_32x32x16_bf16 v[16:31], v[136:139], v[68:71], v[16:31]
	v_exp_f32_e32 v104, v104
	v_exp_f32_e32 v105, v105
	v_exp_f32_e32 v106, v106
	v_exp_f32_e32 v107, v107
	ds_read_b128 v[116:119], v64 offset:2048
	ds_read_b128 v[120:123], v64 offset:2560
	s_waitcnt lgkmcnt(12)
	v_mfma_f32_32x32x16_bf16 v[32:47], v[136:139], v[72:75], v[32:47]
	v_exp_f32_e32 v108, v108
	v_exp_f32_e32 v109, v109
	v_exp_f32_e32 v110, v110
	v_exp_f32_e32 v111, v111
	ds_read_b128 v[124:127], v64 offset:4096
	ds_read_b128 v[160:163], v64 offset:4608
	s_waitcnt lgkmcnt(12)
	v_mfma_f32_32x32x16_bf16 v[16:31], v[132:135], v[76:79], v[16:31]
	v_exp_f32_e32 v80, v80
	v_exp_f32_e32 v81, v81
	v_exp_f32_e32 v82, v82
	v_exp_f32_e32 v83, v83
	ds_read_b128 v[164:167], v64 offset:6144
	ds_read_b128 v[186:189], v64 offset:6656
	s_waitcnt lgkmcnt(12)
	v_mfma_f32_32x32x16_bf16 v[32:47], v[132:135], v[48:51], v[32:47]
	v_exp_f32_e32 v84, v84
	v_exp_f32_e32 v85, v85
	v_exp_f32_e32 v86, v86
	v_exp_f32_e32 v87, v87
	s_waitcnt lgkmcnt(10)
	v_mfma_f32_32x32x16_bf16 v[16:31], v[128:131], v[52:55], v[16:31]
	v_exp_f32_e32 v88, v88
	v_exp_f32_e32 v89, v89
	v_exp_f32_e32 v90, v90
	v_exp_f32_e32 v91, v91
	s_waitcnt lgkmcnt(8)
	v_mfma_f32_32x32x16_bf16 v[32:47], v[128:131], v[56:59], v[32:47]
	v_exp_f32_e32 v92, v92
	v_exp_f32_e32 v93, v93
	v_exp_f32_e32 v94, v94
	v_exp_f32_e32 v95, v95
	s_waitcnt vmcnt(2) lgkmcnt(0)
	s_barrier
; #define WAIT_BAR(N) asm volatile("s_waitcnt vmcnt(" #N ") lgkmcnt(0)\n\ts_barrier":::"memory")
;   #define RESC() do{ if(!NOMAX&&resc){ asm volatile("s_waitcnt lgkmcnt(0)":::"memory"); \
;       _Pragma("unroll") for(int d_=0;d_<2*VM;++d_) _Pragma("unroll") for(int r=0;r<16;++r)o[d_][r]*=wsf[crow(r,hi)]; } }while(0)
;   #define ROT() do{sl_prev=sl_cur;sl_cur=sl_next;sl_next=(sl_next==(NSLOT-1)*SLOTB)?0:sl_next+SLOTB;}while(0)
; template<int THRL,int VM,bool NOMAX> __device__ __forceinline__ void attn_unit(const bf16*Qb,const bf16*__restrict__ Kh,const bf16*__restrict__ Vh,bf16*Ob,const int NT,const int sp,float*wscr,char*shm){
;     ...
;   for(;t+5<NT;t+=2){
;     STEP(pB0,pB1,pA0,pA1,t,true,true,true);     if constexpr(VM==2){WAIT_BAR(3);}else{WAIT_BAR(2);} RESC(); ROT();
;     STEP(pA0,pA1,pB0,pB1,t+1,true,true,true);   if constexpr(VM==2){WAIT_BAR(3);}else{WAIT_BAR(2);} RESC(); ROT();
	v_mfma_f32_32x32x16_bf16 v[64:79], v[60:63], v[156:159], 0
	s_add_i32 s53, s35, 0x2000
	s_cmpk_lg_i32 s35, 0x4000
	s_cselect_b32 s53, s53, 0
	v_add_u32_e32 v203, s52, v182
	ds_read_b64_tr_b16 v[190:191], v203 offset:24576
	ds_read_b64_tr_b16 v[192:193], v203 offset:25088
	v_add_f32_e32 v48, v96, v97
	v_add_f32_e32 v48, v98, v48
	v_add_f32_e32 v48, v99, v48
	v_add_f32_e32 v48, v100, v48
	v_add_f32_e32 v48, v101, v48
	v_cvt_pk_bf16_f32 v140, v96, v97
	v_cvt_pk_bf16_f32 v141, v98, v99
	ds_read_b64_tr_b16 v[96:97], v203 offset:28672
	ds_read_b64_tr_b16 v[98:99], v203 offset:29184
	v_add_f32_e32 v48, v102, v48
	v_add_f32_e32 v48, v103, v48
	v_add_f32_e32 v48, v104, v48
	v_add_f32_e32 v128, v105, v48
	s_waitcnt lgkmcnt(10)
	v_mfma_f32_32x32x16_bf16 v[48:63], v[112:115], v[156:159], 0
	v_cvt_pk_bf16_f32 v142, v100, v101
	v_cvt_pk_bf16_f32 v143, v102, v103
	ds_read_b64_tr_b16 v[100:101], v203 offset:25600
	ds_read_b64_tr_b16 v[102:103], v203 offset:26112
	s_waitcnt lgkmcnt(11)
	v_mfma_f32_32x32x16_bf16 v[64:79], v[116:119], v[152:155], v[64:79]
	v_add_f32_e32 v112, v106, v128
	v_add_f32_e32 v112, v107, v112
	v_add_f32_e32 v112, v108, v112
	v_add_f32_e32 v112, v109, v112
	v_cvt_pk_bf16_f32 v136, v104, v105
	v_cvt_pk_bf16_f32 v137, v106, v107
	ds_read_b64_tr_b16 v[104:105], v203 offset:29696
	ds_read_b64_tr_b16 v[106:107], v203 offset:30208
	s_waitcnt lgkmcnt(12)
	v_mfma_f32_32x32x16_bf16 v[48:63], v[120:123], v[152:155], v[48:63]
	v_add_f32_e32 v112, v110, v112
	v_add_f32_e32 v112, v111, v112
	v_add_f32_e32 v112, v80, v112
	v_add_f32_e32 v112, v81, v112
	v_cvt_pk_bf16_f32 v138, v108, v109
	v_cvt_pk_bf16_f32 v139, v110, v111
	ds_read_b64_tr_b16 v[108:109], v203 offset:26624
	ds_read_b64_tr_b16 v[110:111], v203 offset:27136
	s_waitcnt lgkmcnt(13)
	v_mfma_f32_32x32x16_bf16 v[64:79], v[124:127], v[148:151], v[64:79]
	v_add_f32_e32 v112, v82, v112
	v_add_f32_e32 v112, v83, v112
	v_add_f32_e32 v112, v84, v112
	v_add_f32_e32 v112, v85, v112
	v_cvt_pk_bf16_f32 v132, v80, v81
	v_cvt_pk_bf16_f32 v133, v82, v83
	ds_read_b64_tr_b16 v[194:195], v203 offset:30720
	ds_read_b64_tr_b16 v[196:197], v203 offset:31232
	s_waitcnt lgkmcnt(14)
	v_mfma_f32_32x32x16_bf16 v[48:63], v[160:163], v[148:151], v[48:63]
	v_add_f32_e32 v80, v86, v112
	v_add_f32_e32 v80, v87, v80
	v_add_f32_e32 v80, v88, v80
	v_add_f32_e32 v80, v89, v80
	v_cvt_pk_bf16_f32 v134, v84, v85
	v_cvt_pk_bf16_f32 v135, v86, v87
	ds_read_b64_tr_b16 v[198:199], v203 offset:27648
	ds_read_b64_tr_b16 v[200:201], v203 offset:28160
	s_waitcnt lgkmcnt(14)
	v_mfma_f32_32x32x16_bf16 v[64:79], v[164:167], v[144:147], v[64:79]
	v_add_f32_e32 v80, v90, v80
	v_add_f32_e32 v80, v91, v80
	v_add_f32_e32 v80, v92, v80
	v_add_f32_e32 v80, v93, v80
	v_cvt_pk_bf16_f32 v128, v88, v89
	v_cvt_pk_bf16_f32 v129, v90, v91
	ds_read_b64_tr_b16 v[88:89], v203 offset:31744
	ds_read_b64_tr_b16 v[90:91], v203 offset:32256
	v_mfma_f32_32x32x16_bf16 v[48:63], v[186:189], v[144:147], v[48:63]
	v_add_f32_e32 v80, v94, v80
	v_add_f32_e32 v80, v95, v80
	v_add_f32_e32 v80, 0, v80
	v_cvt_pk_bf16_f32 v130, v92, v93
	v_cvt_pk_bf16_f32 v131, v94, v95
	s_add_i32 s52, s35, s33
	s_mov_b32 s54, m0
	s_mov_b32 m0, s52
	s_nop 0
	global_load_lds_dwordx4 v[176:177], off
	s_mov_b32 m0, s54
	s_add_i32 s52, s53, s16
	s_mov_b32 s54, m0
	s_mov_b32 m0, s52
	s_nop 0
	global_load_lds_dwordx4 v[174:175], off
	s_mov_b32 m0, s54
	v_add_f32_e32 v186, v202, v80
	s_waitcnt lgkmcnt(14)
	v_mfma_f32_32x32x16_bf16 v[16:31], v[140:143], v[190:193], v[16:31]
	v_exp_f32_e32 v64, v64
	v_exp_f32_e32 v65, v65
	v_exp_f32_e32 v66, v66
	v_exp_f32_e32 v67, v67
	s_waitcnt lgkmcnt(12)
	v_mfma_f32_32x32x16_bf16 v[32:47], v[140:143], v[96:99], v[32:47]
	v_exp_f32_e32 v68, v68
	v_exp_f32_e32 v69, v69
	v_exp_f32_e32 v70, v70
	v_exp_f32_e32 v71, v71
	v_add_u32_e32 v92, s53, v183
	ds_read_b128 v[84:87], v92
	ds_read_b128 v[80:83], v92 offset:512
	s_waitcnt lgkmcnt(12)
	v_mfma_f32_32x32x16_bf16 v[16:31], v[136:139], v[100:103], v[16:31]
	v_exp_f32_e32 v72, v72
	v_exp_f32_e32 v73, v73
	v_exp_f32_e32 v74, v74
	v_exp_f32_e32 v75, v75
	ds_read_b128 v[164:167], v92 offset:2048
	ds_read_b128 v[160:163], v92 offset:2560
	s_waitcnt lgkmcnt(12)
	v_mfma_f32_32x32x16_bf16 v[32:47], v[136:139], v[104:107], v[32:47]
	v_exp_f32_e32 v76, v76
	v_exp_f32_e32 v77, v77
	v_exp_f32_e32 v78, v78
	v_exp_f32_e32 v79, v79
	ds_read_b128 v[124:127], v92 offset:4096
	ds_read_b128 v[120:123], v92 offset:4608
	s_waitcnt lgkmcnt(12)
	v_mfma_f32_32x32x16_bf16 v[16:31], v[132:135], v[108:111], v[16:31]
	v_exp_f32_e32 v48, v48
	v_exp_f32_e32 v49, v49
	v_exp_f32_e32 v50, v50
	v_exp_f32_e32 v51, v51
	ds_read_b128 v[116:119], v92 offset:6144
	ds_read_b128 v[112:115], v92 offset:6656
	s_waitcnt lgkmcnt(12)
	v_mfma_f32_32x32x16_bf16 v[32:47], v[132:135], v[194:197], v[32:47]
	v_exp_f32_e32 v52, v52
	v_exp_f32_e32 v53, v53
	v_exp_f32_e32 v54, v54
	v_exp_f32_e32 v55, v55
	s_waitcnt lgkmcnt(10)
	v_mfma_f32_32x32x16_bf16 v[16:31], v[128:131], v[198:201], v[16:31]
	v_exp_f32_e32 v56, v56
	v_exp_f32_e32 v57, v57
	v_exp_f32_e32 v58, v58
	v_exp_f32_e32 v59, v59
	s_waitcnt lgkmcnt(8)
	v_mfma_f32_32x32x16_bf16 v[32:47], v[128:131], v[88:91], v[32:47]
	v_exp_f32_e32 v60, v60
	v_exp_f32_e32 v61, v61
	v_exp_f32_e32 v62, v62
	v_exp_f32_e32 v63, v63
	s_add_i32 s55, s53, 0x2000
	s_waitcnt vmcnt(2) lgkmcnt(0)
	s_barrier
	s_cmpk_lg_i32 s53, 0x4000
	s_mov_b32 s54, s35
	s_cselect_b32 s35, s55, 0
	s_add_i32 s34, s34, 2
	v_lshl_add_u64 v[174:175], v[174:175], 0, s[8:9]
	v_lshl_add_u64 v[176:177], v[176:177], 0, s[8:9]
	s_mov_b32 s52, s53
	s_cmpk_lt_u32 s34, 0x79
	s_cbranch_scc1 .LBB0_882
;   #define RESC() do{ if(!NOMAX&&resc){ asm volatile("s_waitcnt lgkmcnt(0)":::"memory"); \
;       _Pragma("unroll") for(int d_=0;d_<2*VM;++d_) _Pragma("unroll") for(int r=0;r<16;++r)o[d_][r]*=wsf[crow(r,hi)]; } }while(0)
;   #define ROT() do{sl_prev=sl_cur;sl_cur=sl_next;sl_next=(sl_next==(NSLOT-1)*SLOTB)?0:sl_next+SLOTB;}while(0)
;   #define ENDW(tt) do{ if((tt)+3<NT){ if constexpr(VM==2){WAIT_BAR(3);}else{WAIT_BAR(2);} } else if((tt)+2<NT){ if constexpr(VM==2){WAIT_BAR(2);}else{WAIT_BAR(1);} } else {WAIT_BAR(0);} }while(0)
; template<int THRL,int VM,bool NOMAX> __device__ __forceinline__ void attn_unit(const bf16*Qb,const bf16*__restrict__ Kh,const bf16*__restrict__ Vh,bf16*Ob,const int NT,const int sp,float*wscr,char*shm){
;     ...
;   for(;t+1<NT;t+=2){
;     STEP(pB0,pB1,pA0,pA1,t,(t+3<NT),(t+1<NT),(t+1<NT));       ENDW(t);   RESC(); ROT();
;     STEP(pA0,pA1,pB0,pB1,t+1,(t+4<NT),(t+2<NT),(t+2<NT));     ENDW(t+1); RESC(); ROT();
	s_and_b32 s29, s29, 0x3fffffc0
	s_lshl_b32 s29, s29, 2
	s_add_i32 s29, s29, 0
	s_cmp_lg_u32 0, -1
	s_cselect_b32 s34, 0, 0
	s_add_i32 s35, s34, 0x6000
	v_add3_u32 v174, v185, s35, v184
	ds_read_b64_tr_b16 v[188:189], v182 offset:40960
	ds_read_b64_tr_b16 v[190:191], v182 offset:41472
	v_add_f32_e32 v88, v64, v65
	v_add_f32_e32 v88, v66, v88
	v_add_f32_e32 v88, v67, v88
	v_add_f32_e32 v88, v68, v88
	v_add_f32_e32 v88, v69, v88
	v_cvt_pk_bf16_f32 v140, v64, v65
	v_cvt_pk_bf16_f32 v141, v66, v67
	s_waitcnt lgkmcnt(9)
	v_mfma_f32_32x32x16_bf16 v[96:111], v[84:87], v[156:159], 0
	ds_read_b64_tr_b16 v[64:65], v182 offset:45056
	ds_read_b64_tr_b16 v[66:67], v182 offset:45568
	v_add_f32_e32 v84, v70, v88
	v_add_f32_e32 v84, v71, v84
	v_add_f32_e32 v84, v72, v84
	v_add_f32_e32 v128, v73, v84
	v_cvt_pk_bf16_f32 v142, v68, v69
	v_cvt_pk_bf16_f32 v143, v70, v71
	s_waitcnt lgkmcnt(10)
	v_mfma_f32_32x32x16_bf16 v[80:95], v[80:83], v[156:159], 0
	ds_read_b64_tr_b16 v[68:69], v182 offset:41984
	ds_read_b64_tr_b16 v[70:71], v182 offset:42496
	v_add_f32_e32 v128, v74, v128
	v_add_f32_e32 v128, v75, v128
	v_add_f32_e32 v128, v76, v128
	v_add_f32_e32 v128, v77, v128
	v_cvt_pk_bf16_f32 v136, v72, v73
	v_cvt_pk_bf16_f32 v137, v74, v75
	s_waitcnt lgkmcnt(11)
	v_mfma_f32_32x32x16_bf16 v[96:111], v[164:167], v[152:155], v[96:111]
	ds_read_b64_tr_b16 v[72:73], v182 offset:46080
	ds_read_b64_tr_b16 v[74:75], v182 offset:46592
	v_add_f32_e32 v128, v78, v128
	v_add_f32_e32 v128, v79, v128
	v_add_f32_e32 v128, v48, v128
	v_add_f32_e32 v128, v49, v128
	v_cvt_pk_bf16_f32 v138, v76, v77
	v_cvt_pk_bf16_f32 v139, v78, v79
	s_waitcnt lgkmcnt(12)
	v_mfma_f32_32x32x16_bf16 v[80:95], v[160:163], v[152:155], v[80:95]
	ds_read_b64_tr_b16 v[76:77], v182 offset:43008
	ds_read_b64_tr_b16 v[78:79], v182 offset:43520
	v_add_f32_e32 v128, v50, v128
	v_add_f32_e32 v128, v51, v128
	v_add_f32_e32 v128, v52, v128
	v_add_f32_e32 v128, v53, v128
	v_cvt_pk_bf16_f32 v132, v48, v49
	v_cvt_pk_bf16_f32 v133, v50, v51
	s_waitcnt lgkmcnt(13)
	v_mfma_f32_32x32x16_bf16 v[96:111], v[124:127], v[148:151], v[96:111]
	ds_read_b64_tr_b16 v[48:49], v182 offset:47104
	ds_read_b64_tr_b16 v[50:51], v182 offset:47616
	v_add_f32_e32 v124, v54, v128
	v_add_f32_e32 v124, v55, v124
	v_add_f32_e32 v124, v56, v124
	v_add_f32_e32 v124, v57, v124
	v_cvt_pk_bf16_f32 v134, v52, v53
	v_cvt_pk_bf16_f32 v135, v54, v55
	s_waitcnt lgkmcnt(14)
	v_mfma_f32_32x32x16_bf16 v[80:95], v[120:123], v[148:151], v[80:95]
	ds_read_b64_tr_b16 v[52:53], v182 offset:44032
	ds_read_b64_tr_b16 v[54:55], v182 offset:44544
	v_add_f32_e32 v120, v58, v124
	v_add_f32_e32 v120, v59, v120
	v_add_f32_e32 v120, v60, v120
	v_add_f32_e32 v120, v61, v120
	v_cvt_pk_bf16_f32 v128, v56, v57
	v_cvt_pk_bf16_f32 v129, v58, v59
	s_waitcnt lgkmcnt(14)
	v_mfma_f32_32x32x16_bf16 v[96:111], v[116:119], v[144:147], v[96:111]
	ds_read_b64_tr_b16 v[56:57], v182 offset:48128
	ds_read_b64_tr_b16 v[58:59], v182 offset:48640
	v_add_f32_e32 v116, v62, v120
	v_add_f32_e32 v116, v63, v116
	v_add_f32_e32 v116, 0, v116
	v_cvt_pk_bf16_f32 v130, v60, v61
	v_cvt_pk_bf16_f32 v131, v62, v63
	v_mfma_f32_32x32x16_bf16 v[80:95], v[112:115], v[144:147], v[80:95]
	v_lshl_add_u64 v[60:61], v[172:173], 0, s[40:41]
	s_mov_b32 s35, m0
	s_mov_b32 m0, s33
	s_nop 0
	global_load_lds_dwordx4 v[60:61], off
	s_mov_b32 m0, s35
	s_add_i32 s33, s34, s17
	v_lshl_add_u64 v[60:61], v[170:171], 0, s[42:43]
	s_add_i32 s17, s33, 0x8000
	s_mov_b32 s34, m0
	s_mov_b32 m0, s17
	s_nop 0
	global_load_lds_dwordx4 v[60:61], off
	s_mov_b32 m0, s34
	v_add_f32_e32 v175, v186, v116
	s_waitcnt lgkmcnt(14)
	v_mfma_f32_32x32x16_bf16 v[16:31], v[140:143], v[188:191], v[16:31]
	v_exp_f32_e32 v96, v96
	v_exp_f32_e32 v97, v97
	v_exp_f32_e32 v98, v98
	v_exp_f32_e32 v99, v99
	s_waitcnt lgkmcnt(12)
	v_mfma_f32_32x32x16_bf16 v[32:47], v[140:143], v[64:67], v[32:47]
	v_exp_f32_e32 v100, v100
	v_exp_f32_e32 v101, v101
	v_exp_f32_e32 v102, v102
	v_exp_f32_e32 v103, v103
	ds_read_b128 v[60:63], v183 offset:8192
	ds_read_b128 v[64:67], v183 offset:8704
	s_waitcnt lgkmcnt(12)
	v_mfma_f32_32x32x16_bf16 v[16:31], v[136:139], v[68:71], v[16:31]
	v_exp_f32_e32 v104, v104
	v_exp_f32_e32 v105, v105
	v_exp_f32_e32 v106, v106
	v_exp_f32_e32 v107, v107
	ds_read_b128 v[68:71], v183 offset:10240
	ds_read_b128 v[160:163], v183 offset:10752
	s_waitcnt lgkmcnt(12)
	v_mfma_f32_32x32x16_bf16 v[32:47], v[136:139], v[72:75], v[32:47]
	v_exp_f32_e32 v108, v108
	v_exp_f32_e32 v109, v109
	v_exp_f32_e32 v110, v110
	v_exp_f32_e32 v111, v111
	ds_read_b128 v[72:75], v183 offset:12288
	ds_read_b128 v[164:167], v183 offset:12800
	s_waitcnt lgkmcnt(12)
	v_mfma_f32_32x32x16_bf16 v[16:31], v[132:135], v[76:79], v[16:31]
	v_exp_f32_e32 v80, v80
	v_exp_f32_e32 v81, v81
	v_exp_f32_e32 v82, v82
	v_exp_f32_e32 v83, v83
	ds_read_b128 v[76:79], v183 offset:14336
	ds_read_b128 v[184:187], v183 offset:14848
	s_waitcnt lgkmcnt(12)
	v_mfma_f32_32x32x16_bf16 v[32:47], v[132:135], v[48:51], v[32:47]
	v_exp_f32_e32 v84, v84
	v_exp_f32_e32 v85, v85
	v_exp_f32_e32 v86, v86
	v_exp_f32_e32 v87, v87
	s_waitcnt lgkmcnt(10)
	v_mfma_f32_32x32x16_bf16 v[16:31], v[128:131], v[52:55], v[16:31]
	v_exp_f32_e32 v88, v88
	v_exp_f32_e32 v89, v89
	v_exp_f32_e32 v90, v90
	v_exp_f32_e32 v91, v91
	s_waitcnt lgkmcnt(8)
	v_mfma_f32_32x32x16_bf16 v[32:47], v[128:131], v[56:59], v[32:47]
	v_exp_f32_e32 v92, v92
	v_exp_f32_e32 v93, v93
	v_exp_f32_e32 v94, v94
	v_exp_f32_e32 v95, v95
	s_waitcnt vmcnt(2) lgkmcnt(0)
	s_barrier
;   #define RESC() do{ if(!NOMAX&&resc){ asm volatile("s_waitcnt lgkmcnt(0)":::"memory"); \
;       _Pragma("unroll") for(int d_=0;d_<2*VM;++d_) _Pragma("unroll") for(int r=0;r<16;++r)o[d_][r]*=wsf[crow(r,hi)]; } }while(0)
;   #define ROT() do{sl_prev=sl_cur;sl_cur=sl_next;sl_next=(sl_next==(NSLOT-1)*SLOTB)?0:sl_next+SLOTB;}while(0)
;   #define ENDW(tt) do{ if((tt)+3<NT){ if constexpr(VM==2){WAIT_BAR(3);}else{WAIT_BAR(2);} } else if((tt)+2<NT){ if constexpr(VM==2){WAIT_BAR(2);}else{WAIT_BAR(1);} } else {WAIT_BAR(0);} }while(0)
; template<int THRL,int VM,bool NOMAX> __device__ __forceinline__ void attn_unit(const bf16*Qb,const bf16*__restrict__ Kh,const bf16*__restrict__ Vh,bf16*Ob,const int NT,const int sp,float*wscr,char*shm){
;     ...
;   for(;t+1<NT;t+=2){
;     STEP(pB0,pB1,pA0,pA1,t,(t+3<NT),(t+1<NT),(t+1<NT));       ENDW(t);   RESC(); ROT();
;     STEP(pA0,pA1,pB0,pB1,t+1,(t+4<NT),(t+2<NT),(t+2<NT));     ENDW(t+1); RESC(); ROT();
	ds_read_b64_tr_b16 v[188:189], v182 offset:24576
	ds_read_b64_tr_b16 v[190:191], v182 offset:25088
	v_add_f32_e32 v48, v96, v97
	v_add_f32_e32 v48, v98, v48
	v_add_f32_e32 v48, v99, v48
	v_add_f32_e32 v48, v100, v48
	v_add_f32_e32 v48, v101, v48
	v_cvt_pk_bf16_f32 v140, v96, v97
	v_cvt_pk_bf16_f32 v141, v98, v99
	s_waitcnt lgkmcnt(9)
	v_mfma_f32_32x32x16_bf16 v[112:127], v[60:63], v[156:159], 0
	ds_read_b64_tr_b16 v[96:97], v182 offset:28672
	ds_read_b64_tr_b16 v[98:99], v182 offset:29184
	v_add_f32_e32 v48, v102, v48
	v_add_f32_e32 v48, v103, v48
	v_add_f32_e32 v48, v104, v48
	v_add_f32_e32 v128, v105, v48
	s_waitcnt lgkmcnt(10)
	v_mfma_f32_32x32x16_bf16 v[48:63], v[64:67], v[156:159], 0
	v_cvt_pk_bf16_f32 v142, v100, v101
	v_cvt_pk_bf16_f32 v143, v102, v103
	ds_read_b64_tr_b16 v[64:65], v182 offset:25600
	ds_read_b64_tr_b16 v[66:67], v182 offset:26112
	v_add_f32_e32 v100, v106, v128
	v_add_f32_e32 v100, v107, v100
	v_add_f32_e32 v100, v108, v100
	v_add_f32_e32 v100, v109, v100
	v_cvt_pk_bf16_f32 v136, v104, v105
	v_cvt_pk_bf16_f32 v137, v106, v107
	s_waitcnt lgkmcnt(11)
	v_mfma_f32_32x32x16_bf16 v[112:127], v[68:71], v[152:155], v[112:127]
	ds_read_b64_tr_b16 v[68:69], v182 offset:29696
	ds_read_b64_tr_b16 v[70:71], v182 offset:30208
	s_waitcnt lgkmcnt(12)
	v_mfma_f32_32x32x16_bf16 v[48:63], v[160:163], v[152:155], v[48:63]
	v_add_f32_e32 v100, v110, v100
	v_add_f32_e32 v100, v111, v100
	v_add_f32_e32 v100, v80, v100
	v_add_f32_e32 v104, v81, v100
	v_cvt_pk_bf16_f32 v138, v108, v109
	v_cvt_pk_bf16_f32 v139, v110, v111
	ds_read_b64_tr_b16 v[100:101], v182 offset:26624
	ds_read_b64_tr_b16 v[102:103], v182 offset:27136
	v_add_f32_e32 v104, v82, v104
	v_add_f32_e32 v104, v83, v104
	v_add_f32_e32 v104, v84, v104
	v_add_f32_e32 v104, v85, v104
	v_cvt_pk_bf16_f32 v132, v80, v81
	v_cvt_pk_bf16_f32 v133, v82, v83
	s_waitcnt lgkmcnt(13)
	v_mfma_f32_32x32x16_bf16 v[112:127], v[72:75], v[148:151], v[112:127]
	ds_read_b64_tr_b16 v[72:73], v182 offset:30720
	ds_read_b64_tr_b16 v[74:75], v182 offset:31232
	s_waitcnt lgkmcnt(14)
	v_mfma_f32_32x32x16_bf16 v[48:63], v[164:167], v[148:151], v[48:63]
	v_add_f32_e32 v80, v86, v104
	v_add_f32_e32 v80, v87, v80
	v_add_f32_e32 v80, v88, v80
	v_add_f32_e32 v104, v89, v80
	v_cvt_pk_bf16_f32 v134, v84, v85
	v_cvt_pk_bf16_f32 v135, v86, v87
	ds_read_b64_tr_b16 v[80:81], v182 offset:27648
	ds_read_b64_tr_b16 v[82:83], v182 offset:28160
	v_add_f32_e32 v84, v90, v104
	v_add_f32_e32 v84, v91, v84
	v_add_f32_e32 v84, v92, v84
	v_add_f32_e32 v84, v93, v84
	v_cvt_pk_bf16_f32 v128, v88, v89
	v_cvt_pk_bf16_f32 v129, v90, v91
	s_waitcnt lgkmcnt(14)
	v_mfma_f32_32x32x16_bf16 v[112:127], v[76:79], v[144:147], v[112:127]
	ds_read_b64_tr_b16 v[76:77], v182 offset:31744
	ds_read_b64_tr_b16 v[78:79], v182 offset:32256
	v_mfma_f32_32x32x16_bf16 v[48:63], v[184:187], v[144:147], v[48:63]
	v_add_f32_e32 v84, v94, v84
	v_add_f32_e32 v84, v95, v84
	v_add_f32_e32 v84, 0, v84
	v_cvt_pk_bf16_f32 v130, v92, v93
	v_cvt_pk_bf16_f32 v131, v94, v95
	s_nop 0
	v_add_f32_e32 v175, v175, v84
	v_lshl_add_u64 v[84:85], v[172:173], 0, s[44:45]
	s_add_i32 s34, s33, 0x2000
	s_mov_b32 s35, m0
	s_mov_b32 m0, s34
	s_nop 0
	global_load_lds_dwordx4 v[84:85], off
	s_mov_b32 m0, s35
	v_lshl_add_u64 v[84:85], v[170:171], 0, s[48:49]
	s_add_i32 s33, s33, 0xa000
	s_mov_b32 s34, m0
	s_mov_b32 m0, s33
	s_nop 0
	global_load_lds_dwordx4 v[84:85], off
	s_mov_b32 m0, s34
	s_waitcnt lgkmcnt(14)
	v_mfma_f32_32x32x16_bf16 v[16:31], v[140:143], v[188:191], v[16:31]
	v_exp_f32_e32 v112, v112
	v_exp_f32_e32 v113, v113
	v_exp_f32_e32 v114, v114
	v_exp_f32_e32 v115, v115
	s_waitcnt lgkmcnt(12)
	v_mfma_f32_32x32x16_bf16 v[32:47], v[140:143], v[96:99], v[32:47]
	v_exp_f32_e32 v116, v116
	v_exp_f32_e32 v117, v117
	v_exp_f32_e32 v118, v118
	v_exp_f32_e32 v119, v119
	ds_read_b128 v[84:87], v183 offset:16384
	ds_read_b128 v[96:99], v183 offset:16896
	s_waitcnt lgkmcnt(12)
	v_mfma_f32_32x32x16_bf16 v[16:31], v[136:139], v[64:67], v[16:31]
	v_exp_f32_e32 v120, v120
	v_exp_f32_e32 v121, v121
	v_exp_f32_e32 v122, v122
	v_exp_f32_e32 v123, v123
	ds_read_b128 v[104:107], v183 offset:18432
	ds_read_b128 v[108:111], v183 offset:18944
	s_waitcnt lgkmcnt(12)
	v_mfma_f32_32x32x16_bf16 v[32:47], v[136:139], v[68:71], v[32:47]
	v_exp_f32_e32 v124, v124
	v_exp_f32_e32 v125, v125
	v_exp_f32_e32 v126, v126
	v_exp_f32_e32 v127, v127
	ds_read_b128 v[160:163], v183 offset:20480
	ds_read_b128 v[164:167], v183 offset:20992
	s_waitcnt lgkmcnt(12)
	v_mfma_f32_32x32x16_bf16 v[16:31], v[132:135], v[100:103], v[16:31]
	v_exp_f32_e32 v48, v48
	v_exp_f32_e32 v49, v49
	v_exp_f32_e32 v50, v50
	v_exp_f32_e32 v51, v51
	ds_read_b128 v[100:103], v183 offset:22528
	ds_read_b128 v[184:187], v183 offset:23040
	s_waitcnt lgkmcnt(12)
	v_mfma_f32_32x32x16_bf16 v[32:47], v[132:135], v[72:75], v[32:47]
	v_exp_f32_e32 v52, v52
	v_exp_f32_e32 v53, v53
	v_exp_f32_e32 v54, v54
	v_exp_f32_e32 v55, v55
	s_waitcnt lgkmcnt(10)
	v_mfma_f32_32x32x16_bf16 v[16:31], v[128:131], v[80:83], v[16:31]
	v_exp_f32_e32 v56, v56
	v_exp_f32_e32 v57, v57
	v_exp_f32_e32 v58, v58
	v_exp_f32_e32 v59, v59
	s_waitcnt lgkmcnt(8)
	v_mfma_f32_32x32x16_bf16 v[32:47], v[128:131], v[76:79], v[32:47]
	v_exp_f32_e32 v60, v60
	v_exp_f32_e32 v61, v61
	v_exp_f32_e32 v62, v62
	v_exp_f32_e32 v63, v63
	s_waitcnt vmcnt(2) lgkmcnt(0)
	s_barrier
;   #define RESC() do{ if(!NOMAX&&resc){ asm volatile("s_waitcnt lgkmcnt(0)":::"memory"); \
;       _Pragma("unroll") for(int d_=0;d_<2*VM;++d_) _Pragma("unroll") for(int r=0;r<16;++r)o[d_][r]*=wsf[crow(r,hi)]; } }while(0)
;   #define ROT() do{sl_prev=sl_cur;sl_cur=sl_next;sl_next=(sl_next==(NSLOT-1)*SLOTB)?0:sl_next+SLOTB;}while(0)
;   #define ENDW(tt) do{ if((tt)+3<NT){ if constexpr(VM==2){WAIT_BAR(3);}else{WAIT_BAR(2);} } else if((tt)+2<NT){ if constexpr(VM==2){WAIT_BAR(2);}else{WAIT_BAR(1);} } else {WAIT_BAR(0);} }while(0)
; template<int THRL,int VM,bool NOMAX> __device__ __forceinline__ void attn_unit(const bf16*Qb,const bf16*__restrict__ Kh,const bf16*__restrict__ Vh,bf16*Ob,const int NT,const int sp,float*wscr,char*shm){
;     ...
;   for(;t+1<NT;t+=2){
;     STEP(pB0,pB1,pA0,pA1,t,(t+3<NT),(t+1<NT),(t+1<NT));       ENDW(t);   RESC(); ROT();
;     STEP(pA0,pA1,pB0,pB1,t+1,(t+4<NT),(t+2<NT),(t+2<NT));     ENDW(t+1); RESC(); ROT();
	ds_read_b64_tr_b16 v[188:189], v182 offset:32768
	ds_read_b64_tr_b16 v[190:191], v182 offset:33280
	v_add_f32_e32 v64, v112, v113
	v_add_f32_e32 v64, v114, v64
	v_add_f32_e32 v64, v115, v64
	v_add_f32_e32 v64, v116, v64
	v_add_f32_e32 v64, v117, v64
	v_cvt_pk_bf16_f32 v140, v112, v113
	v_cvt_pk_bf16_f32 v141, v114, v115
	s_waitcnt lgkmcnt(9)
	v_mfma_f32_32x32x16_bf16 v[80:95], v[84:87], v[156:159], 0
	ds_read_b64_tr_b16 v[112:113], v182 offset:36864
	ds_read_b64_tr_b16 v[114:115], v182 offset:37376
	v_add_f32_e32 v64, v118, v64
	v_add_f32_e32 v64, v119, v64
	v_add_f32_e32 v64, v120, v64
	v_add_f32_e32 v128, v121, v64
	v_cvt_pk_bf16_f32 v142, v116, v117
	v_cvt_pk_bf16_f32 v143, v118, v119
	s_waitcnt lgkmcnt(10)
	v_mfma_f32_32x32x16_bf16 v[64:79], v[96:99], v[156:159], 0
	ds_read_b64_tr_b16 v[96:97], v182 offset:33792
	ds_read_b64_tr_b16 v[98:99], v182 offset:34304
	v_add_f32_e32 v116, v122, v128
	v_add_f32_e32 v116, v123, v116
	v_add_f32_e32 v116, v124, v116
	v_add_f32_e32 v116, v125, v116
	v_cvt_pk_bf16_f32 v136, v120, v121
	v_cvt_pk_bf16_f32 v137, v122, v123
	s_waitcnt lgkmcnt(11)
	v_mfma_f32_32x32x16_bf16 v[80:95], v[104:107], v[152:155], v[80:95]
	ds_read_b64_tr_b16 v[104:105], v182 offset:37888
	ds_read_b64_tr_b16 v[106:107], v182 offset:38400
	v_add_f32_e32 v116, v126, v116
	v_add_f32_e32 v116, v127, v116
	v_add_f32_e32 v116, v48, v116
	v_add_f32_e32 v116, v49, v116
	v_cvt_pk_bf16_f32 v138, v124, v125
	v_cvt_pk_bf16_f32 v139, v126, v127
	s_waitcnt lgkmcnt(12)
	v_mfma_f32_32x32x16_bf16 v[64:79], v[108:111], v[152:155], v[64:79]
	ds_read_b64_tr_b16 v[108:109], v182 offset:34816
	ds_read_b64_tr_b16 v[110:111], v182 offset:35328
	v_add_f32_e32 v116, v50, v116
	v_add_f32_e32 v116, v51, v116
	v_add_f32_e32 v116, v52, v116
	v_add_f32_e32 v116, v53, v116
	v_cvt_pk_bf16_f32 v132, v48, v49
	v_cvt_pk_bf16_f32 v133, v50, v51
	s_waitcnt lgkmcnt(13)
	v_mfma_f32_32x32x16_bf16 v[80:95], v[160:163], v[148:151], v[80:95]
	ds_read_b64_tr_b16 v[48:49], v182 offset:38912
	ds_read_b64_tr_b16 v[50:51], v182 offset:39424
	v_add_f32_e32 v116, v54, v116
	v_add_f32_e32 v116, v55, v116
	v_add_f32_e32 v116, v56, v116
	v_add_f32_e32 v116, v57, v116
	v_cvt_pk_bf16_f32 v134, v52, v53
	v_cvt_pk_bf16_f32 v135, v54, v55
	s_waitcnt lgkmcnt(14)
	v_mfma_f32_32x32x16_bf16 v[64:79], v[164:167], v[148:151], v[64:79]
	ds_read_b64_tr_b16 v[52:53], v182 offset:35840
	ds_read_b64_tr_b16 v[54:55], v182 offset:36352
	v_add_f32_e32 v116, v58, v116
	v_add_f32_e32 v116, v59, v116
	v_add_f32_e32 v116, v60, v116
	v_add_f32_e32 v116, v61, v116
	v_cvt_pk_bf16_f32 v128, v56, v57
	v_cvt_pk_bf16_f32 v129, v58, v59
	s_waitcnt lgkmcnt(14)
	v_mfma_f32_32x32x16_bf16 v[80:95], v[100:103], v[144:147], v[80:95]
	ds_read_b64_tr_b16 v[56:57], v182 offset:39936
	ds_read_b64_tr_b16 v[58:59], v182 offset:40448
	v_add_f32_e32 v100, v62, v116
	v_add_f32_e32 v100, v63, v100
	v_add_f32_e32 v100, 0, v100
	v_cvt_pk_bf16_f32 v130, v60, v61
	v_cvt_pk_bf16_f32 v131, v62, v63
	v_mfma_f32_32x32x16_bf16 v[64:79], v[184:187], v[144:147], v[64:79]
	v_lshl_add_u64 v[60:61], v[170:171], 0, s[40:41]
	s_mov_b32 s33, m0
	s_mov_b32 m0, s16
	s_nop 0
	global_load_lds_dwordx4 v[60:61], off
	s_mov_b32 m0, s33
	v_add_f32_e32 v172, v175, v100
	s_waitcnt lgkmcnt(14)
	v_mfma_f32_32x32x16_bf16 v[16:31], v[140:143], v[188:191], v[16:31]
	v_exp_f32_e32 v80, v80
	v_exp_f32_e32 v81, v81
	v_exp_f32_e32 v82, v82
	v_exp_f32_e32 v83, v83
	s_waitcnt lgkmcnt(12)
	v_mfma_f32_32x32x16_bf16 v[32:47], v[140:143], v[112:115], v[32:47]
	v_exp_f32_e32 v84, v84
	v_exp_f32_e32 v85, v85
	v_exp_f32_e32 v86, v86
	v_exp_f32_e32 v87, v87
	ds_read_b128 v[60:63], v183
	ds_read_b128 v[112:115], v183 offset:512
	s_waitcnt lgkmcnt(12)
	v_mfma_f32_32x32x16_bf16 v[16:31], v[136:139], v[96:99], v[16:31]
	v_exp_f32_e32 v88, v88
	v_exp_f32_e32 v89, v89
	v_exp_f32_e32 v90, v90
	v_exp_f32_e32 v91, v91
	ds_read_b128 v[116:119], v183 offset:2048
	ds_read_b128 v[120:123], v183 offset:2560
	s_waitcnt lgkmcnt(12)
	v_mfma_f32_32x32x16_bf16 v[32:47], v[136:139], v[104:107], v[32:47]
	v_exp_f32_e32 v92, v92
	v_exp_f32_e32 v93, v93
	v_exp_f32_e32 v94, v94
	v_exp_f32_e32 v95, v95
	ds_read_b128 v[124:127], v183 offset:4096
	ds_read_b128 v[160:163], v183 offset:4608
	s_waitcnt lgkmcnt(12)
	v_mfma_f32_32x32x16_bf16 v[16:31], v[132:135], v[108:111], v[16:31]
	v_exp_f32_e32 v64, v64
	v_exp_f32_e32 v65, v65
	v_exp_f32_e32 v66, v66
	v_exp_f32_e32 v67, v67
	ds_read_b128 v[164:167], v183 offset:6144
	ds_read_b128 v[184:187], v183 offset:6656
	s_waitcnt lgkmcnt(12)
	v_mfma_f32_32x32x16_bf16 v[32:47], v[132:135], v[48:51], v[32:47]
	v_exp_f32_e32 v68, v68
	v_exp_f32_e32 v69, v69
	v_exp_f32_e32 v70, v70
	v_exp_f32_e32 v71, v71
	s_waitcnt lgkmcnt(10)
	v_mfma_f32_32x32x16_bf16 v[16:31], v[128:131], v[52:55], v[16:31]
	v_exp_f32_e32 v72, v72
	v_exp_f32_e32 v73, v73
	v_exp_f32_e32 v74, v74
	v_exp_f32_e32 v75, v75
	s_waitcnt lgkmcnt(8)
	v_mfma_f32_32x32x16_bf16 v[32:47], v[128:131], v[56:59], v[32:47]
	v_exp_f32_e32 v76, v76
	v_exp_f32_e32 v77, v77
	v_exp_f32_e32 v78, v78
	v_exp_f32_e32 v79, v79
	s_waitcnt vmcnt(1) lgkmcnt(0)
	s_barrier
;   #define RESC() do{ if(!NOMAX&&resc){ asm volatile("s_waitcnt lgkmcnt(0)":::"memory"); \
;       _Pragma("unroll") for(int d_=0;d_<2*VM;++d_) _Pragma("unroll") for(int r=0;r<16;++r)o[d_][r]*=wsf[crow(r,hi)]; } }while(0)
;   #define ROT() do{sl_prev=sl_cur;sl_cur=sl_next;sl_next=(sl_next==(NSLOT-1)*SLOTB)?0:sl_next+SLOTB;}while(0)
;   #define ENDW(tt) do{ if((tt)+3<NT){ if constexpr(VM==2){WAIT_BAR(3);}else{WAIT_BAR(2);} } else if((tt)+2<NT){ if constexpr(VM==2){WAIT_BAR(2);}else{WAIT_BAR(1);} } else {WAIT_BAR(0);} }while(0)
; template<int THRL,int VM,bool NOMAX> __device__ __forceinline__ void attn_unit(const bf16*Qb,const bf16*__restrict__ Kh,const bf16*__restrict__ Vh,bf16*Ob,const int NT,const int sp,float*wscr,char*shm){
;     ...
;   for(;t+1<NT;t+=2){
;     STEP(pB0,pB1,pA0,pA1,t,(t+3<NT),(t+1<NT),(t+1<NT));       ENDW(t);   RESC(); ROT();
;     STEP(pA0,pA1,pB0,pB1,t+1,(t+4<NT),(t+2<NT),(t+2<NT));     ENDW(t+1); RESC(); ROT();
	ds_read_b64_tr_b16 v[188:189], v182 offset:40960
	ds_read_b64_tr_b16 v[190:191], v182 offset:41472
	v_add_f32_e32 v48, v80, v81
	v_add_f32_e32 v48, v82, v48
	v_add_f32_e32 v48, v83, v48
	v_add_f32_e32 v48, v84, v48
	v_add_f32_e32 v48, v85, v48
	v_cvt_pk_bf16_f32 v140, v80, v81
	v_cvt_pk_bf16_f32 v141, v82, v83
	s_waitcnt lgkmcnt(9)
	v_mfma_f32_32x32x16_bf16 v[96:111], v[60:63], v[156:159], 0
	ds_read_b64_tr_b16 v[80:81], v182 offset:45056
	ds_read_b64_tr_b16 v[82:83], v182 offset:45568
	v_add_f32_e32 v48, v86, v48
	v_add_f32_e32 v48, v87, v48
	v_add_f32_e32 v48, v88, v48
	v_add_f32_e32 v128, v89, v48
	s_waitcnt lgkmcnt(10)
	v_mfma_f32_32x32x16_bf16 v[48:63], v[112:115], v[156:159], 0
	v_cvt_pk_bf16_f32 v142, v84, v85
	v_cvt_pk_bf16_f32 v143, v86, v87
	ds_read_b64_tr_b16 v[84:85], v182 offset:41984
	ds_read_b64_tr_b16 v[86:87], v182 offset:42496
	v_add_f32_e32 v112, v90, v128
	v_add_f32_e32 v112, v91, v112
	v_add_f32_e32 v112, v92, v112
	v_add_f32_e32 v112, v93, v112
	v_cvt_pk_bf16_f32 v136, v88, v89
	v_cvt_pk_bf16_f32 v137, v90, v91
	s_waitcnt lgkmcnt(11)
	v_mfma_f32_32x32x16_bf16 v[96:111], v[116:119], v[152:155], v[96:111]
	ds_read_b64_tr_b16 v[88:89], v182 offset:46080
	ds_read_b64_tr_b16 v[90:91], v182 offset:46592
	s_waitcnt lgkmcnt(12)
	v_mfma_f32_32x32x16_bf16 v[48:63], v[120:123], v[152:155], v[48:63]
	v_add_f32_e32 v112, v94, v112
	v_add_f32_e32 v112, v95, v112
	v_add_f32_e32 v112, v64, v112
	v_add_f32_e32 v112, v65, v112
	v_cvt_pk_bf16_f32 v138, v92, v93
	v_cvt_pk_bf16_f32 v139, v94, v95
	ds_read_b64_tr_b16 v[92:93], v182 offset:43008
	ds_read_b64_tr_b16 v[94:95], v182 offset:43520
	v_add_f32_e32 v112, v66, v112
	v_add_f32_e32 v112, v67, v112
	v_add_f32_e32 v112, v68, v112
	v_add_f32_e32 v112, v69, v112
	v_cvt_pk_bf16_f32 v132, v64, v65
	v_cvt_pk_bf16_f32 v133, v66, v67
	s_waitcnt lgkmcnt(13)
	v_mfma_f32_32x32x16_bf16 v[96:111], v[124:127], v[148:151], v[96:111]
	ds_read_b64_tr_b16 v[64:65], v182 offset:47104
	ds_read_b64_tr_b16 v[66:67], v182 offset:47616
	s_waitcnt lgkmcnt(14)
	v_mfma_f32_32x32x16_bf16 v[48:63], v[160:163], v[148:151], v[48:63]
	v_add_f32_e32 v112, v70, v112
	v_add_f32_e32 v112, v71, v112
	v_add_f32_e32 v112, v72, v112
	v_add_f32_e32 v112, v73, v112
	v_cvt_pk_bf16_f32 v134, v68, v69
	v_cvt_pk_bf16_f32 v135, v70, v71
	ds_read_b64_tr_b16 v[68:69], v182 offset:44032
	ds_read_b64_tr_b16 v[70:71], v182 offset:44544
	v_add_f32_e32 v112, v74, v112
	v_add_f32_e32 v112, v75, v112
	v_add_f32_e32 v112, v76, v112
	v_add_f32_e32 v112, v77, v112
	v_cvt_pk_bf16_f32 v128, v72, v73
	v_cvt_pk_bf16_f32 v129, v74, v75
	s_waitcnt lgkmcnt(14)
	v_mfma_f32_32x32x16_bf16 v[96:111], v[164:167], v[144:147], v[96:111]
	ds_read_b64_tr_b16 v[72:73], v182 offset:48128
	ds_read_b64_tr_b16 v[74:75], v182 offset:48640
	v_mfma_f32_32x32x16_bf16 v[48:63], v[184:187], v[144:147], v[48:63]
	v_add_f32_e32 v112, v78, v112
	v_add_f32_e32 v112, v79, v112
	v_add_f32_e32 v112, 0, v112
	v_cvt_pk_bf16_f32 v130, v76, v77
	v_cvt_pk_bf16_f32 v131, v78, v79
	v_lshl_add_u64 v[76:77], v[170:171], 0, s[44:45]
	s_mov_b32 s16, m0
	s_mov_b32 m0, s17
	s_nop 0
	global_load_lds_dwordx4 v[76:77], off
	s_mov_b32 m0, s16
	v_add_f32_e32 v120, v172, v112
	s_waitcnt lgkmcnt(14)
	v_mfma_f32_32x32x16_bf16 v[16:31], v[140:143], v[188:191], v[16:31]
	v_exp_f32_e32 v96, v96
	v_exp_f32_e32 v97, v97
	v_exp_f32_e32 v98, v98
	v_exp_f32_e32 v99, v99
	s_waitcnt lgkmcnt(12)
	v_mfma_f32_32x32x16_bf16 v[32:47], v[140:143], v[80:83], v[32:47]
	v_exp_f32_e32 v100, v100
	v_exp_f32_e32 v101, v101
	v_exp_f32_e32 v102, v102
	v_exp_f32_e32 v103, v103
	ds_read_b128 v[76:79], v183 offset:8192
	ds_read_b128 v[80:83], v183 offset:8704
	s_waitcnt lgkmcnt(12)
	v_mfma_f32_32x32x16_bf16 v[16:31], v[136:139], v[84:87], v[16:31]
	v_exp_f32_e32 v104, v104
	v_exp_f32_e32 v105, v105
	v_exp_f32_e32 v106, v106
	v_exp_f32_e32 v107, v107
	ds_read_b128 v[122:125], v183 offset:10240
	ds_read_b128 v[160:163], v183 offset:10752
	s_waitcnt lgkmcnt(12)
	v_mfma_f32_32x32x16_bf16 v[32:47], v[136:139], v[88:91], v[32:47]
	v_exp_f32_e32 v108, v108
	v_exp_f32_e32 v109, v109
	v_exp_f32_e32 v110, v110
	v_exp_f32_e32 v111, v111
	ds_read_b128 v[164:167], v183 offset:12288
	ds_read_b128 v[170:173], v183 offset:12800
	s_waitcnt lgkmcnt(12)
	v_mfma_f32_32x32x16_bf16 v[16:31], v[132:135], v[92:95], v[16:31]
	v_exp_f32_e32 v48, v48
	v_exp_f32_e32 v49, v49
	v_exp_f32_e32 v50, v50
	v_exp_f32_e32 v51, v51
	ds_read_b128 v[184:187], v183 offset:14336
	ds_read_b128 v[188:191], v183 offset:14848
	s_waitcnt lgkmcnt(12)
	v_mfma_f32_32x32x16_bf16 v[32:47], v[132:135], v[64:67], v[32:47]
	v_exp_f32_e32 v52, v52
	v_exp_f32_e32 v53, v53
	v_exp_f32_e32 v54, v54
	v_exp_f32_e32 v55, v55
	s_waitcnt lgkmcnt(10)
	v_mfma_f32_32x32x16_bf16 v[16:31], v[128:131], v[68:71], v[16:31]
	v_exp_f32_e32 v56, v56
	v_exp_f32_e32 v57, v57
	v_exp_f32_e32 v58, v58
	v_exp_f32_e32 v59, v59
	s_waitcnt lgkmcnt(8)
	v_mfma_f32_32x32x16_bf16 v[32:47], v[128:131], v[72:75], v[32:47]
	v_exp_f32_e32 v60, v60
	v_exp_f32_e32 v61, v61
	v_exp_f32_e32 v62, v62
	v_exp_f32_e32 v63, v63
	s_waitcnt vmcnt(0) lgkmcnt(0)
	s_barrier
	ds_read_b64_tr_b16 v[112:113], v182 offset:24576
	ds_read_b64_tr_b16 v[114:115], v182 offset:25088
	v_add_f32_e32 v64, v96, v97
	v_add_f32_e32 v64, v98, v64
	v_add_f32_e32 v64, v99, v64
	v_add_f32_e32 v64, v100, v64
	v_add_f32_e32 v84, v101, v64
	v_cvt_pk_bf16_f32 v140, v96, v97
	v_cvt_pk_bf16_f32 v141, v98, v99
	s_waitcnt lgkmcnt(9)
	v_mfma_f32_32x32x16_bf16 v[64:79], v[76:79], v[156:159], 0
	ds_read_b64_tr_b16 v[96:97], v182 offset:28672
	ds_read_b64_tr_b16 v[98:99], v182 offset:29184
	v_add_f32_e32 v84, v102, v84
	v_add_f32_e32 v84, v103, v84
	v_add_f32_e32 v84, v104, v84
	v_add_f32_e32 v121, v105, v84
	v_cvt_pk_bf16_f32 v142, v100, v101
	v_cvt_pk_bf16_f32 v143, v102, v103
	s_waitcnt lgkmcnt(10)
	v_mfma_f32_32x32x16_bf16 v[80:95], v[80:83], v[156:159], 0
	ds_read_b64_tr_b16 v[116:117], v182 offset:25600
	ds_read_b64_tr_b16 v[118:119], v182 offset:26112
	v_add_f32_e32 v100, v106, v121
	v_add_f32_e32 v100, v107, v100
	v_add_f32_e32 v100, v108, v100
	v_add_f32_e32 v121, v109, v100
	v_cvt_pk_bf16_f32 v136, v104, v105
	v_cvt_pk_bf16_f32 v137, v106, v107
	s_waitcnt lgkmcnt(11)
	v_mfma_f32_32x32x16_bf16 v[64:79], v[122:125], v[152:155], v[64:79]
	ds_read_b64_tr_b16 v[100:101], v182 offset:29696
	ds_read_b64_tr_b16 v[102:103], v182 offset:30208
	v_add_f32_e32 v104, v110, v121
	v_add_f32_e32 v104, v111, v104
	v_add_f32_e32 v104, v48, v104
	v_add_f32_e32 v121, v49, v104
	v_cvt_pk_bf16_f32 v138, v108, v109
	v_cvt_pk_bf16_f32 v139, v110, v111
	s_waitcnt lgkmcnt(12)
	v_mfma_f32_32x32x16_bf16 v[80:95], v[160:163], v[152:155], v[80:95]
	ds_read_b64_tr_b16 v[104:105], v182 offset:26624
	ds_read_b64_tr_b16 v[106:107], v182 offset:27136
	v_add_f32_e32 v108, v50, v121
	v_add_f32_e32 v108, v51, v108
	v_add_f32_e32 v108, v52, v108
	v_add_f32_e32 v108, v53, v108
	v_cvt_pk_bf16_f32 v132, v48, v49
	v_cvt_pk_bf16_f32 v133, v50, v51
	s_waitcnt lgkmcnt(13)
	v_mfma_f32_32x32x16_bf16 v[64:79], v[164:167], v[148:151], v[64:79]
	ds_read_b64_tr_b16 v[48:49], v182 offset:30720
	ds_read_b64_tr_b16 v[50:51], v182 offset:31232
	v_add_f32_e32 v108, v54, v108
	v_add_f32_e32 v108, v55, v108
	v_add_f32_e32 v108, v56, v108
	v_add_f32_e32 v121, v57, v108
	v_cvt_pk_bf16_f32 v134, v52, v53
	v_cvt_pk_bf16_f32 v135, v54, v55
	s_waitcnt lgkmcnt(14)
	v_mfma_f32_32x32x16_bf16 v[80:95], v[170:173], v[148:151], v[80:95]
	ds_read_b64_tr_b16 v[108:109], v182 offset:27648
	ds_read_b64_tr_b16 v[110:111], v182 offset:28160
	v_add_f32_e32 v52, v58, v121
	v_add_f32_e32 v52, v59, v52
	v_add_f32_e32 v52, v60, v52
	v_add_f32_e32 v121, v61, v52
	v_cvt_pk_bf16_f32 v128, v56, v57
	v_cvt_pk_bf16_f32 v129, v58, v59
	s_waitcnt lgkmcnt(14)
	v_mfma_f32_32x32x16_bf16 v[64:79], v[184:187], v[144:147], v[64:79]
	ds_read_b64_tr_b16 v[52:53], v182 offset:31744
	ds_read_b64_tr_b16 v[54:55], v182 offset:32256
	v_add_f32_e32 v56, v62, v121
	v_add_f32_e32 v56, v63, v56
	v_add_f32_e32 v56, 0, v56
	v_cvt_pk_bf16_f32 v130, v60, v61
	v_cvt_pk_bf16_f32 v131, v62, v63
	v_mfma_f32_32x32x16_bf16 v[80:95], v[188:191], v[144:147], v[80:95]
	s_nop 3
	v_exp_f32_e32 v64, v64
	v_exp_f32_e32 v65, v65
	v_exp_f32_e32 v66, v66
	v_exp_f32_e32 v67, v67
	s_nop 0
	v_exp_f32_e32 v68, v68
	v_exp_f32_e32 v69, v69
	v_exp_f32_e32 v70, v70
	v_exp_f32_e32 v71, v71
	s_nop 0
	v_exp_f32_e32 v72, v72
	v_exp_f32_e32 v73, v73
	v_exp_f32_e32 v74, v74
	v_exp_f32_e32 v75, v75
	s_nop 0
	v_exp_f32_e32 v76, v76
	v_exp_f32_e32 v77, v77
	v_exp_f32_e32 v78, v78
	v_exp_f32_e32 v79, v79
	v_exp_f32_e32 v80, v80
	v_exp_f32_e32 v81, v81
	v_exp_f32_e32 v82, v82
	v_exp_f32_e32 v83, v83
	s_nop 0
	v_exp_f32_e32 v84, v84
	v_exp_f32_e32 v85, v85
	v_exp_f32_e32 v86, v86
	v_exp_f32_e32 v87, v87
	s_nop 0
	v_exp_f32_e32 v88, v88
	v_exp_f32_e32 v89, v89
	v_exp_f32_e32 v90, v90
	v_exp_f32_e32 v91, v91
	s_nop 0
	v_exp_f32_e32 v92, v92
	v_exp_f32_e32 v93, v93
	v_exp_f32_e32 v94, v94
	v_exp_f32_e32 v95, v95
	s_waitcnt lgkmcnt(14)
; #define SBAR() __builtin_amdgcn_sched_barrier(0)
;   #define RESC() do{ if(!NOMAX&&resc){ asm volatile("s_waitcnt lgkmcnt(0)":::"memory"); \
;       _Pragma("unroll") for(int d_=0;d_<2*VM;++d_) _Pragma("unroll") for(int r=0;r<16;++r)o[d_][r]*=wsf[crow(r,hi)]; } }while(0)
;   #define PKW(P,B) cvtpk_s(P[B],P[B+1])
; template<int THRL,int VM,bool NOMAX> __device__ __forceinline__ void attn_unit(const bf16*Qb,const bf16*__restrict__ Kh,const bf16*__restrict__ Vh,bf16*Ob,const int NT,const int sp,float*wscr,char*shm){
;     ...
;   STEP(pB0,pB1,pA0,pA1,NT-1,false,false,false); RESC();
;   { float sacc=pB0[0]+pB0[1]; _Pragma("unroll") for(int r=2;r<16;++r)sacc+=pB0[r]; _Pragma("unroll") for(int r=0;r<16;++r)sacc+=pB1[r]; l_reg+=sacc;
;     pw0=(u32x4){PKW(pB0,0),PKW(pB0,2),PKW(pB0,4),PKW(pB0,6)};pw1=(u32x4){PKW(pB0,8),PKW(pB0,10),PKW(pB0,12),PKW(pB0,14)};pw2=(u32x4){PKW(pB1,0),PKW(pB1,2),PKW(pB1,4),PKW(pB1,6)};pw3=(u32x4){PKW(pB1,8),PKW(pB1,10),PKW(pB1,12),PKW(pB1,14)};
;     SBAR(); pv(o,vb0+VM*sl_cur,PAF(0),PAF(1),PAF(2),PAF(3)); if constexpr(VM==2) pv(o+2,vb0+VM*sl_cur+8192,PAF(0),PAF(1),PAF(2),PAF(3)); }
;     ...
;   {auto rr=__builtin_amdgcn_permlane32_swap(__float_as_uint(l_reg),__float_as_uint(l_reg),false,false);l_reg=__uint_as_float(rr[0])+__uint_as_float(rr[1]);}
;   if(hi==0)wsf[32+r32]=l_reg;asm volatile("s_waitcnt lgkmcnt(0)":::"memory");
	v_mfma_f32_32x32x16_bf16 v[16:31], v[140:143], v[112:115], v[16:31]
	v_add_f32_e32 v57, v64, v65
	v_add_f32_e32 v57, v66, v57
	v_add_f32_e32 v57, v67, v57
	v_add_f32_e32 v57, v68, v57
	v_add_f32_e32 v57, v69, v57
	v_add_f32_e32 v57, v70, v57
	v_add_f32_e32 v57, v71, v57
	s_waitcnt lgkmcnt(12)
	v_mfma_f32_32x32x16_bf16 v[32:47], v[140:143], v[96:99], v[32:47]
	v_add_f32_e32 v57, v72, v57
	v_add_f32_e32 v57, v73, v57
	v_add_f32_e32 v57, v74, v57
	v_add_f32_e32 v57, v75, v57
	v_add_f32_e32 v57, v76, v57
	v_add_f32_e32 v57, v77, v57
	v_add_f32_e32 v57, v78, v57
	s_waitcnt lgkmcnt(10)
	v_mfma_f32_32x32x16_bf16 v[16:31], v[136:139], v[116:119], v[16:31]
	v_add_f32_e32 v57, v79, v57
	v_add_f32_e32 v57, v80, v57
	v_add_f32_e32 v57, v81, v57
	v_add_f32_e32 v57, v82, v57
	v_add_f32_e32 v57, v83, v57
	v_add_f32_e32 v57, v84, v57
	v_add_f32_e32 v57, v85, v57
	s_waitcnt lgkmcnt(8)
	v_mfma_f32_32x32x16_bf16 v[32:47], v[136:139], v[100:103], v[32:47]
	v_add_f32_e32 v57, v86, v57
	v_add_f32_e32 v57, v87, v57
	v_add_f32_e32 v57, v88, v57
	v_add_f32_e32 v57, v89, v57
	v_add_f32_e32 v57, v90, v57
	v_add_f32_e32 v57, v91, v57
	v_add_f32_e32 v57, v92, v57
	s_waitcnt lgkmcnt(6)
	v_mfma_f32_32x32x16_bf16 v[16:31], v[132:135], v[104:107], v[16:31]
	v_add_f32_e32 v57, v93, v57
	v_add_f32_e32 v57, v94, v57
	v_add_f32_e32 v57, v95, v57
	v_add_f32_e32 v56, v120, v56
	v_add_f32_e32 v56, v56, v57
	v_cvt_pk_bf16_f32 v58, v64, v65
	v_cvt_pk_bf16_f32 v59, v66, v67
	s_waitcnt lgkmcnt(4)
	v_mfma_f32_32x32x16_bf16 v[32:47], v[132:135], v[48:51], v[32:47]
	v_cvt_pk_bf16_f32 v48, v80, v81
	v_cvt_pk_bf16_f32 v60, v68, v69
	v_cvt_pk_bf16_f32 v61, v70, v71
	v_cvt_pk_bf16_f32 v62, v72, v73
	v_cvt_pk_bf16_f32 v63, v74, v75
	v_cvt_pk_bf16_f32 v64, v76, v77
	v_cvt_pk_bf16_f32 v65, v78, v79
	s_waitcnt lgkmcnt(2)
	v_mfma_f32_32x32x16_bf16 v[16:31], v[128:131], v[108:111], v[16:31]
	v_cvt_pk_bf16_f32 v49, v82, v83
	v_cvt_pk_bf16_f32 v50, v84, v85
	v_cvt_pk_bf16_f32 v51, v86, v87
	v_cvt_pk_bf16_f32 v66, v88, v89
	v_cvt_pk_bf16_f32 v67, v90, v91
	v_cvt_pk_bf16_f32 v68, v92, v93
	v_cvt_pk_bf16_f32 v69, v94, v95
	s_waitcnt lgkmcnt(0)
	v_mfma_f32_32x32x16_bf16 v[32:47], v[128:131], v[52:55], v[32:47]
	v_add3_u32 v57, v174, v168, s18
	ds_read_b64_tr_b16 v[52:53],v57 offset:0
	ds_read_b64_tr_b16 v[54:55],v57 offset:512
	ds_read_b64_tr_b16 v[70:71],v57 offset:1024
	ds_read_b64_tr_b16 v[72:73],v57 offset:1536
	ds_read_b64_tr_b16 v[74:75],v57 offset:2048
	ds_read_b64_tr_b16 v[76:77],v57 offset:2560
	ds_read_b64_tr_b16 v[78:79],v57 offset:3072
	ds_read_b64_tr_b16 v[80:81],v57 offset:3584
	s_waitcnt lgkmcnt(0)
	s_nop 0
	v_mfma_f32_32x32x16_bf16 v[16:31], v[58:61], v[52:55], v[16:31]
	ds_read_b64_tr_b16 v[52:53],v57 offset:4096
	ds_read_b64_tr_b16 v[54:55],v57 offset:4608
	v_mfma_f32_32x32x16_bf16 v[16:31], v[62:65], v[70:73], v[16:31]
	ds_read_b64_tr_b16 v[70:71],v57 offset:5120
	ds_read_b64_tr_b16 v[72:73],v57 offset:5632
	v_mfma_f32_32x32x16_bf16 v[16:31], v[48:51], v[74:77], v[16:31]
	ds_read_b64_tr_b16 v[74:75],v57 offset:6144
	ds_read_b64_tr_b16 v[76:77],v57 offset:6656
	ds_read_b64_tr_b16 v[82:83],v57 offset:7168
	ds_read_b64_tr_b16 v[84:85],v57 offset:7680
	s_waitcnt lgkmcnt(0)
	v_mfma_f32_32x32x16_bf16 v[16:31], v[66:69], v[78:81], v[16:31]
	v_mfma_f32_32x32x16_bf16 v[32:47], v[58:61], v[52:55], v[32:47]
	v_cmp_gt_u32_e32 vcc, 32, v178
	v_mfma_f32_32x32x16_bf16 v[32:47], v[62:65], v[70:73], v[32:47]
	v_mfma_f32_32x32x16_bf16 v[32:47], v[48:51], v[74:77], v[32:47]
	v_mov_b32_e32 v48, v56
	s_nop 1
	v_permlane32_swap_b32_e32 v56, v48
	v_mfma_f32_32x32x16_bf16 v[32:47], v[66:69], v[82:85], v[32:47]
	s_and_saveexec_b64 s[16:17], vcc
	s_cbranch_execz .LBB0_878
	v_add_f32_e32 v48, v56, v48
	v_lshl_add_u32 v49, v180, 2, s29
	ds_write_b32 v49, v48 offset:49280
	s_branch .LBB0_878

; #define WAIT_BAR(N) asm volatile("s_waitcnt vmcnt(" #N ") lgkmcnt(0)\n\ts_barrier":::"memory")
;   #define RESC() do{ if(!NOMAX&&resc){ asm volatile("s_waitcnt lgkmcnt(0)":::"memory"); \
;       _Pragma("unroll") for(int d_=0;d_<2*VM;++d_) _Pragma("unroll") for(int r=0;r<16;++r)o[d_][r]*=wsf[crow(r,hi)]; } }while(0)
;   #define ROT() do{sl_prev=sl_cur;sl_cur=sl_next;sl_next=(sl_next==(NSLOT-1)*SLOTB)?0:sl_next+SLOTB;}while(0)
; template<int THRL,int VM,bool NOMAX> __device__ __forceinline__ void attn_unit(const bf16*Qb,const bf16*__restrict__ Kh,const bf16*__restrict__ Vh,bf16*Ob,const int NT,const int sp,float*wscr,char*shm){
;     ...
;   for(;t+5<NT;t+=2){
;     STEP(pB0,pB1,pA0,pA1,t,true,true,true);     if constexpr(VM==2){WAIT_BAR(3);}else{WAIT_BAR(2);} RESC(); ROT();
;     STEP(pA0,pA1,pB0,pB1,t+1,true,true,true);   if constexpr(VM==2){WAIT_BAR(3);}else{WAIT_BAR(2);} RESC(); ROT();
.LBB0_891:
	v_mfma_f32_32x32x16_bf16 v[96:111], v[84:87], v[156:159], 0
	v_add_u32_e32 v187, s52, v168
	ds_read_b64_tr_b16 v[188:189], v187 offset:24576
	ds_read_b64_tr_b16 v[190:191], v187 offset:25088
	v_add_f32_e32 v88, v64, v65
	v_add_f32_e32 v88, v66, v88
	v_add_f32_e32 v88, v67, v88
	v_add_f32_e32 v88, v68, v88
	v_add_f32_e32 v88, v69, v88
	v_cvt_pk_bf16_f32 v140, v64, v65
	v_cvt_pk_bf16_f32 v141, v66, v67
	ds_read_b64_tr_b16 v[64:65], v187 offset:28672
	ds_read_b64_tr_b16 v[66:67], v187 offset:29184
	v_add_f32_e32 v84, v70, v88
	v_add_f32_e32 v84, v71, v84
	v_add_f32_e32 v84, v72, v84
	v_add_f32_e32 v128, v73, v84
	s_waitcnt lgkmcnt(10)
	v_mfma_f32_32x32x16_bf16 v[80:95], v[80:83], v[156:159], 0
	v_cvt_pk_bf16_f32 v142, v68, v69
	v_cvt_pk_bf16_f32 v143, v70, v71
	ds_read_b64_tr_b16 v[68:69], v187 offset:25600
	ds_read_b64_tr_b16 v[70:71], v187 offset:26112
	v_add_f32_e32 v128, v74, v128
	v_add_f32_e32 v128, v75, v128
	v_add_f32_e32 v128, v76, v128
	v_add_f32_e32 v128, v77, v128
	v_cvt_pk_bf16_f32 v136, v72, v73
	v_cvt_pk_bf16_f32 v137, v74, v75
	s_waitcnt lgkmcnt(11)
	v_mfma_f32_32x32x16_bf16 v[96:111], v[164:167], v[152:155], v[96:111]
	ds_read_b64_tr_b16 v[72:73], v187 offset:29696
	ds_read_b64_tr_b16 v[74:75], v187 offset:30208
	s_waitcnt lgkmcnt(12)
	v_mfma_f32_32x32x16_bf16 v[80:95], v[160:163], v[152:155], v[80:95]
	v_add_f32_e32 v128, v78, v128
	v_add_f32_e32 v128, v79, v128
	v_add_f32_e32 v128, v48, v128
	v_add_f32_e32 v128, v49, v128
	v_cvt_pk_bf16_f32 v138, v76, v77
	v_cvt_pk_bf16_f32 v139, v78, v79
	ds_read_b64_tr_b16 v[76:77], v187 offset:26624
	ds_read_b64_tr_b16 v[78:79], v187 offset:27136
	v_add_f32_e32 v128, v50, v128
	v_add_f32_e32 v128, v51, v128
	v_add_f32_e32 v128, v52, v128
	v_add_f32_e32 v128, v53, v128
	v_cvt_pk_bf16_f32 v132, v48, v49
	v_cvt_pk_bf16_f32 v133, v50, v51
	s_waitcnt lgkmcnt(13)
	v_mfma_f32_32x32x16_bf16 v[96:111], v[124:127], v[148:151], v[96:111]
	ds_read_b64_tr_b16 v[48:49], v187 offset:30720
	ds_read_b64_tr_b16 v[50:51], v187 offset:31232
	s_waitcnt lgkmcnt(14)
	v_mfma_f32_32x32x16_bf16 v[80:95], v[120:123], v[148:151], v[80:95]
	v_add_f32_e32 v124, v54, v128
	v_add_f32_e32 v124, v55, v124
	v_add_f32_e32 v124, v56, v124
	v_add_f32_e32 v124, v57, v124
	v_cvt_pk_bf16_f32 v134, v52, v53
	v_cvt_pk_bf16_f32 v135, v54, v55
	ds_read_b64_tr_b16 v[52:53], v187 offset:27648
	ds_read_b64_tr_b16 v[54:55], v187 offset:28160
	v_add_f32_e32 v120, v58, v124
	v_add_f32_e32 v120, v59, v120
	v_add_f32_e32 v120, v60, v120
	v_add_f32_e32 v120, v61, v120
	v_cvt_pk_bf16_f32 v128, v56, v57
	v_cvt_pk_bf16_f32 v129, v58, v59
	s_waitcnt lgkmcnt(14)
	v_mfma_f32_32x32x16_bf16 v[96:111], v[116:119], v[144:147], v[96:111]
	ds_read_b64_tr_b16 v[56:57], v187 offset:31744
	ds_read_b64_tr_b16 v[58:59], v187 offset:32256
	v_mfma_f32_32x32x16_bf16 v[80:95], v[112:115], v[144:147], v[80:95]
	v_add_f32_e32 v116, v62, v120
	v_add_f32_e32 v116, v63, v116
	v_add_f32_e32 v116, 0, v116
	v_cvt_pk_bf16_f32 v130, v60, v61
	v_cvt_pk_bf16_f32 v131, v62, v63
	v_lshl_add_u64 v[60:61], v[176:177], 0, s[38:39]
	s_add_i32 s35, s34, s17
	s_mov_b32 s52, m0
	s_mov_b32 m0, s35
	s_nop 0
	global_load_lds_dwordx4 v[60:61], off
	s_mov_b32 m0, s52
	v_lshl_add_u64 v[60:61], v[174:175], 0, s[38:39]
	s_add_i32 s35, s33, s16
	s_mov_b32 s52, m0
	s_mov_b32 m0, s35
	s_nop 0
	global_load_lds_dwordx4 v[60:61], off
	s_mov_b32 m0, s52
	v_add_f32_e32 v202, v186, v116
	s_waitcnt lgkmcnt(14)
	v_mfma_f32_32x32x16_bf16 v[16:31], v[140:143], v[188:191], v[16:31]
	v_exp_f32_e32 v96, v96
	v_exp_f32_e32 v97, v97
	v_exp_f32_e32 v98, v98
	v_exp_f32_e32 v99, v99
	s_waitcnt lgkmcnt(12)
	v_mfma_f32_32x32x16_bf16 v[32:47], v[140:143], v[64:67], v[32:47]
	v_exp_f32_e32 v100, v100
	v_exp_f32_e32 v101, v101
	v_exp_f32_e32 v102, v102
	v_exp_f32_e32 v103, v103
	v_add_u32_e32 v64, s33, v182
	ds_read_b128 v[60:63], v64
	ds_read_b128 v[112:115], v64 offset:512
	s_waitcnt lgkmcnt(12)
	v_mfma_f32_32x32x16_bf16 v[16:31], v[136:139], v[68:71], v[16:31]
	v_exp_f32_e32 v104, v104
	v_exp_f32_e32 v105, v105
	v_exp_f32_e32 v106, v106
	v_exp_f32_e32 v107, v107
	ds_read_b128 v[116:119], v64 offset:2048
	ds_read_b128 v[120:123], v64 offset:2560
	s_waitcnt lgkmcnt(12)
	v_mfma_f32_32x32x16_bf16 v[32:47], v[136:139], v[72:75], v[32:47]
	v_exp_f32_e32 v108, v108
	v_exp_f32_e32 v109, v109
	v_exp_f32_e32 v110, v110
	v_exp_f32_e32 v111, v111
	ds_read_b128 v[124:127], v64 offset:4096
	ds_read_b128 v[160:163], v64 offset:4608
	s_waitcnt lgkmcnt(12)
	v_mfma_f32_32x32x16_bf16 v[16:31], v[132:135], v[76:79], v[16:31]
	v_exp_f32_e32 v80, v80
	v_exp_f32_e32 v81, v81
	v_exp_f32_e32 v82, v82
	v_exp_f32_e32 v83, v83
	ds_read_b128 v[164:167], v64 offset:6144
	ds_read_b128 v[186:189], v64 offset:6656
	s_waitcnt lgkmcnt(12)
	v_mfma_f32_32x32x16_bf16 v[32:47], v[132:135], v[48:51], v[32:47]
	v_exp_f32_e32 v84, v84
	v_exp_f32_e32 v85, v85
	v_exp_f32_e32 v86, v86
	v_exp_f32_e32 v87, v87
	s_waitcnt lgkmcnt(10)
	v_mfma_f32_32x32x16_bf16 v[16:31], v[128:131], v[52:55], v[16:31]
	v_exp_f32_e32 v88, v88
	v_exp_f32_e32 v89, v89
	v_exp_f32_e32 v90, v90
	v_exp_f32_e32 v91, v91
	s_waitcnt lgkmcnt(8)
	v_mfma_f32_32x32x16_bf16 v[32:47], v[128:131], v[56:59], v[32:47]
	v_exp_f32_e32 v92, v92
	v_exp_f32_e32 v93, v93
	v_exp_f32_e32 v94, v94
	v_exp_f32_e32 v95, v95
	s_waitcnt vmcnt(2) lgkmcnt(0)
	s_barrier
; #define WAIT_BAR(N) asm volatile("s_waitcnt vmcnt(" #N ") lgkmcnt(0)\n\ts_barrier":::"memory")
;   #define RESC() do{ if(!NOMAX&&resc){ asm volatile("s_waitcnt lgkmcnt(0)":::"memory"); \
;       _Pragma("unroll") for(int d_=0;d_<2*VM;++d_) _Pragma("unroll") for(int r=0;r<16;++r)o[d_][r]*=wsf[crow(r,hi)]; } }while(0)
;   #define ROT() do{sl_prev=sl_cur;sl_cur=sl_next;sl_next=(sl_next==(NSLOT-1)*SLOTB)?0:sl_next+SLOTB;}while(0)
; template<int THRL,int VM,bool NOMAX> __device__ __forceinline__ void attn_unit(const bf16*Qb,const bf16*__restrict__ Kh,const bf16*__restrict__ Vh,bf16*Ob,const int NT,const int sp,float*wscr,char*shm){
;     ...
;   for(;t+5<NT;t+=2){
;     STEP(pB0,pB1,pA0,pA1,t,true,true,true);     if constexpr(VM==2){WAIT_BAR(3);}else{WAIT_BAR(2);} RESC(); ROT();
;     STEP(pA0,pA1,pB0,pB1,t+1,true,true,true);   if constexpr(VM==2){WAIT_BAR(3);}else{WAIT_BAR(2);} RESC(); ROT();
	v_mfma_f32_32x32x16_bf16 v[64:79], v[60:63], v[156:159], 0
	s_add_i32 s35, s33, 0x2000
	s_cmpk_lg_i32 s33, 0x4000
	s_cselect_b32 s35, s35, 0
	v_add_u32_e32 v203, s34, v168
	ds_read_b64_tr_b16 v[190:191], v203 offset:24576
	ds_read_b64_tr_b16 v[192:193], v203 offset:25088
	v_add_f32_e32 v48, v96, v97
	v_add_f32_e32 v48, v98, v48
	v_add_f32_e32 v48, v99, v48
	v_add_f32_e32 v48, v100, v48
	v_add_f32_e32 v48, v101, v48
	v_cvt_pk_bf16_f32 v140, v96, v97
	v_cvt_pk_bf16_f32 v141, v98, v99
	ds_read_b64_tr_b16 v[96:97], v203 offset:28672
	ds_read_b64_tr_b16 v[98:99], v203 offset:29184
	v_add_f32_e32 v48, v102, v48
	v_add_f32_e32 v48, v103, v48
	v_add_f32_e32 v48, v104, v48
	v_add_f32_e32 v128, v105, v48
	s_waitcnt lgkmcnt(10)
	v_mfma_f32_32x32x16_bf16 v[48:63], v[112:115], v[156:159], 0
	v_cvt_pk_bf16_f32 v142, v100, v101
	v_cvt_pk_bf16_f32 v143, v102, v103
	ds_read_b64_tr_b16 v[100:101], v203 offset:25600
	ds_read_b64_tr_b16 v[102:103], v203 offset:26112
	s_waitcnt lgkmcnt(11)
	v_mfma_f32_32x32x16_bf16 v[64:79], v[116:119], v[152:155], v[64:79]
	v_add_f32_e32 v112, v106, v128
	v_add_f32_e32 v112, v107, v112
	v_add_f32_e32 v112, v108, v112
	v_add_f32_e32 v112, v109, v112
	v_cvt_pk_bf16_f32 v136, v104, v105
	v_cvt_pk_bf16_f32 v137, v106, v107
	ds_read_b64_tr_b16 v[104:105], v203 offset:29696
	ds_read_b64_tr_b16 v[106:107], v203 offset:30208
	s_waitcnt lgkmcnt(12)
	v_mfma_f32_32x32x16_bf16 v[48:63], v[120:123], v[152:155], v[48:63]
	v_add_f32_e32 v112, v110, v112
	v_add_f32_e32 v112, v111, v112
	v_add_f32_e32 v112, v80, v112
	v_add_f32_e32 v112, v81, v112
	v_cvt_pk_bf16_f32 v138, v108, v109
	v_cvt_pk_bf16_f32 v139, v110, v111
	ds_read_b64_tr_b16 v[108:109], v203 offset:26624
	ds_read_b64_tr_b16 v[110:111], v203 offset:27136
	s_waitcnt lgkmcnt(13)
	v_mfma_f32_32x32x16_bf16 v[64:79], v[124:127], v[148:151], v[64:79]
	v_add_f32_e32 v112, v82, v112
	v_add_f32_e32 v112, v83, v112
	v_add_f32_e32 v112, v84, v112
	v_add_f32_e32 v112, v85, v112
	v_cvt_pk_bf16_f32 v132, v80, v81
	v_cvt_pk_bf16_f32 v133, v82, v83
	ds_read_b64_tr_b16 v[194:195], v203 offset:30720
	ds_read_b64_tr_b16 v[196:197], v203 offset:31232
	s_waitcnt lgkmcnt(14)
	v_mfma_f32_32x32x16_bf16 v[48:63], v[160:163], v[148:151], v[48:63]
	v_add_f32_e32 v80, v86, v112
	v_add_f32_e32 v80, v87, v80
	v_add_f32_e32 v80, v88, v80
	v_add_f32_e32 v80, v89, v80
	v_cvt_pk_bf16_f32 v134, v84, v85
	v_cvt_pk_bf16_f32 v135, v86, v87
	ds_read_b64_tr_b16 v[198:199], v203 offset:27648
	ds_read_b64_tr_b16 v[200:201], v203 offset:28160
	s_waitcnt lgkmcnt(14)
	v_mfma_f32_32x32x16_bf16 v[64:79], v[164:167], v[144:147], v[64:79]
	v_add_f32_e32 v80, v90, v80
	v_add_f32_e32 v80, v91, v80
	v_add_f32_e32 v80, v92, v80
	v_add_f32_e32 v80, v93, v80
	v_cvt_pk_bf16_f32 v128, v88, v89
	v_cvt_pk_bf16_f32 v129, v90, v91
	ds_read_b64_tr_b16 v[88:89], v203 offset:31744
	ds_read_b64_tr_b16 v[90:91], v203 offset:32256
	v_mfma_f32_32x32x16_bf16 v[48:63], v[186:189], v[144:147], v[48:63]
	v_add_f32_e32 v80, v94, v80
	v_add_f32_e32 v80, v95, v80
	v_add_f32_e32 v80, 0, v80
	v_cvt_pk_bf16_f32 v130, v92, v93
	v_cvt_pk_bf16_f32 v131, v94, v95
	s_add_i32 s34, s33, s17
	s_mov_b32 s52, m0
	s_mov_b32 m0, s34
	s_nop 0
	global_load_lds_dwordx4 v[176:177], off
	s_mov_b32 m0, s52
	s_add_i32 s34, s35, s16
	s_mov_b32 s52, m0
	s_mov_b32 m0, s34
	s_nop 0
	global_load_lds_dwordx4 v[174:175], off
	s_mov_b32 m0, s52
	v_add_f32_e32 v186, v202, v80
	s_waitcnt lgkmcnt(14)
	v_mfma_f32_32x32x16_bf16 v[16:31], v[140:143], v[190:193], v[16:31]
	v_exp_f32_e32 v64, v64
	v_exp_f32_e32 v65, v65
	v_exp_f32_e32 v66, v66
	v_exp_f32_e32 v67, v67
	s_waitcnt lgkmcnt(12)
	v_mfma_f32_32x32x16_bf16 v[32:47], v[140:143], v[96:99], v[32:47]
	v_exp_f32_e32 v68, v68
	v_exp_f32_e32 v69, v69
	v_exp_f32_e32 v70, v70
	v_exp_f32_e32 v71, v71
	v_add_u32_e32 v92, s35, v182
	ds_read_b128 v[84:87], v92
	ds_read_b128 v[80:83], v92 offset:512
	s_waitcnt lgkmcnt(12)
	v_mfma_f32_32x32x16_bf16 v[16:31], v[136:139], v[100:103], v[16:31]
	v_exp_f32_e32 v72, v72
	v_exp_f32_e32 v73, v73
	v_exp_f32_e32 v74, v74
	v_exp_f32_e32 v75, v75
	ds_read_b128 v[164:167], v92 offset:2048
	ds_read_b128 v[160:163], v92 offset:2560
	s_waitcnt lgkmcnt(12)
	v_mfma_f32_32x32x16_bf16 v[32:47], v[136:139], v[104:107], v[32:47]
	v_exp_f32_e32 v76, v76
	v_exp_f32_e32 v77, v77
	v_exp_f32_e32 v78, v78
	v_exp_f32_e32 v79, v79
	ds_read_b128 v[124:127], v92 offset:4096
	ds_read_b128 v[120:123], v92 offset:4608
	s_waitcnt lgkmcnt(12)
	v_mfma_f32_32x32x16_bf16 v[16:31], v[132:135], v[108:111], v[16:31]
	v_exp_f32_e32 v48, v48
	v_exp_f32_e32 v49, v49
	v_exp_f32_e32 v50, v50
	v_exp_f32_e32 v51, v51
	ds_read_b128 v[116:119], v92 offset:6144
	ds_read_b128 v[112:115], v92 offset:6656
	s_waitcnt lgkmcnt(12)
	v_mfma_f32_32x32x16_bf16 v[32:47], v[132:135], v[194:197], v[32:47]
	v_exp_f32_e32 v52, v52
	v_exp_f32_e32 v53, v53
	v_exp_f32_e32 v54, v54
	v_exp_f32_e32 v55, v55
	s_waitcnt lgkmcnt(10)
	v_mfma_f32_32x32x16_bf16 v[16:31], v[128:131], v[198:201], v[16:31]
	v_exp_f32_e32 v56, v56
	v_exp_f32_e32 v57, v57
	v_exp_f32_e32 v58, v58
	v_exp_f32_e32 v59, v59
	s_waitcnt lgkmcnt(8)
	v_mfma_f32_32x32x16_bf16 v[32:47], v[128:131], v[88:91], v[32:47]
	v_exp_f32_e32 v60, v60
	v_exp_f32_e32 v61, v61
	v_exp_f32_e32 v62, v62
	v_exp_f32_e32 v63, v63
	s_add_i32 s53, s35, 0x2000
	s_waitcnt vmcnt(2) lgkmcnt(0)
	s_barrier
	s_cmpk_lg_i32 s35, 0x4000
	s_mov_b32 s52, s33
	s_cselect_b32 s33, s53, 0
	s_add_i32 s29, s29, 2
	v_lshl_add_u64 v[174:175], v[174:175], 0, s[8:9]
	v_lshl_add_u64 v[176:177], v[176:177], 0, s[8:9]
	s_mov_b32 s34, s35
	s_cmp_lt_u32 s29, 57
	s_cbranch_scc1 .LBB0_891
;   #define RESC() do{ if(!NOMAX&&resc){ asm volatile("s_waitcnt lgkmcnt(0)":::"memory"); \
;       _Pragma("unroll") for(int d_=0;d_<2*VM;++d_) _Pragma("unroll") for(int r=0;r<16;++r)o[d_][r]*=wsf[crow(r,hi)]; } }while(0)
;   #define ROT() do{sl_prev=sl_cur;sl_cur=sl_next;sl_next=(sl_next==(NSLOT-1)*SLOTB)?0:sl_next+SLOTB;}while(0)
;   #define ENDW(tt) do{ if((tt)+3<NT){ if constexpr(VM==2){WAIT_BAR(3);}else{WAIT_BAR(2);} } else if((tt)+2<NT){ if constexpr(VM==2){WAIT_BAR(2);}else{WAIT_BAR(1);} } else {WAIT_BAR(0);} }while(0)
; template<int THRL,int VM,bool NOMAX> __device__ __forceinline__ void attn_unit(const bf16*Qb,const bf16*__restrict__ Kh,const bf16*__restrict__ Vh,bf16*Ob,const int NT,const int sp,float*wscr,char*shm){
;     ...
;   for(;t+1<NT;t+=2){
;     STEP(pB0,pB1,pA0,pA1,t,(t+3<NT),(t+1<NT),(t+1<NT));       ENDW(t);   RESC(); ROT();
;     STEP(pA0,pA1,pB0,pB1,t+1,(t+4<NT),(t+2<NT),(t+2<NT));     ENDW(t+1); RESC(); ROT();
	s_and_b32 s19, s19, 0x3fffffc0
	s_lshl_b32 s19, s19, 2
	s_add_i32 s19, s19, 0
	s_cmp_lg_u32 0, -1
	s_cselect_b32 s29, 0, 0
	s_add_i32 s33, s29, 0x6000
	v_add_u32_e32 v88, s33, v184
	v_add3_u32 v174, v88, v183, v185
	ds_read_b64_tr_b16 v[188:189], v168 offset:32768
	ds_read_b64_tr_b16 v[190:191], v168 offset:33280
	v_add_f32_e32 v88, v64, v65
	v_add_f32_e32 v88, v66, v88
	v_add_f32_e32 v88, v67, v88
	v_add_f32_e32 v88, v68, v88
	v_add_f32_e32 v88, v69, v88
	v_cvt_pk_bf16_f32 v140, v64, v65
	v_cvt_pk_bf16_f32 v141, v66, v67
	s_waitcnt lgkmcnt(9)
	v_mfma_f32_32x32x16_bf16 v[96:111], v[84:87], v[156:159], 0
	ds_read_b64_tr_b16 v[64:65], v168 offset:36864
	ds_read_b64_tr_b16 v[66:67], v168 offset:37376
	v_add_f32_e32 v84, v70, v88
	v_add_f32_e32 v84, v71, v84
	v_add_f32_e32 v84, v72, v84
	v_add_f32_e32 v128, v73, v84
	v_cvt_pk_bf16_f32 v142, v68, v69
	v_cvt_pk_bf16_f32 v143, v70, v71
	s_waitcnt lgkmcnt(10)
	v_mfma_f32_32x32x16_bf16 v[80:95], v[80:83], v[156:159], 0
	ds_read_b64_tr_b16 v[68:69], v168 offset:33792
	ds_read_b64_tr_b16 v[70:71], v168 offset:34304
	v_add_f32_e32 v128, v74, v128
	v_add_f32_e32 v128, v75, v128
	v_add_f32_e32 v128, v76, v128
	v_add_f32_e32 v128, v77, v128
	v_cvt_pk_bf16_f32 v136, v72, v73
	v_cvt_pk_bf16_f32 v137, v74, v75
	s_waitcnt lgkmcnt(11)
	v_mfma_f32_32x32x16_bf16 v[96:111], v[164:167], v[152:155], v[96:111]
	ds_read_b64_tr_b16 v[72:73], v168 offset:37888
	ds_read_b64_tr_b16 v[74:75], v168 offset:38400
	v_add_f32_e32 v128, v78, v128
	v_add_f32_e32 v128, v79, v128
	v_add_f32_e32 v128, v48, v128
	v_add_f32_e32 v128, v49, v128
	v_cvt_pk_bf16_f32 v138, v76, v77
	v_cvt_pk_bf16_f32 v139, v78, v79
	s_waitcnt lgkmcnt(12)
	v_mfma_f32_32x32x16_bf16 v[80:95], v[160:163], v[152:155], v[80:95]
	ds_read_b64_tr_b16 v[76:77], v168 offset:34816
	ds_read_b64_tr_b16 v[78:79], v168 offset:35328
	v_add_f32_e32 v128, v50, v128
	v_add_f32_e32 v128, v51, v128
	v_add_f32_e32 v128, v52, v128
	v_add_f32_e32 v128, v53, v128
	v_cvt_pk_bf16_f32 v132, v48, v49
	v_cvt_pk_bf16_f32 v133, v50, v51
	s_waitcnt lgkmcnt(13)
	v_mfma_f32_32x32x16_bf16 v[96:111], v[124:127], v[148:151], v[96:111]
	ds_read_b64_tr_b16 v[48:49], v168 offset:38912
	ds_read_b64_tr_b16 v[50:51], v168 offset:39424
	v_add_f32_e32 v124, v54, v128
	v_add_f32_e32 v124, v55, v124
	v_add_f32_e32 v124, v56, v124
	v_add_f32_e32 v124, v57, v124
	v_cvt_pk_bf16_f32 v134, v52, v53
	v_cvt_pk_bf16_f32 v135, v54, v55
	s_waitcnt lgkmcnt(14)
	v_mfma_f32_32x32x16_bf16 v[80:95], v[120:123], v[148:151], v[80:95]
	ds_read_b64_tr_b16 v[52:53], v168 offset:35840
	ds_read_b64_tr_b16 v[54:55], v168 offset:36352
	v_add_f32_e32 v120, v58, v124
	v_add_f32_e32 v120, v59, v120
	v_add_f32_e32 v120, v60, v120
	v_add_f32_e32 v120, v61, v120
	v_cvt_pk_bf16_f32 v128, v56, v57
	v_cvt_pk_bf16_f32 v129, v58, v59
	s_waitcnt lgkmcnt(14)
	v_mfma_f32_32x32x16_bf16 v[96:111], v[116:119], v[144:147], v[96:111]
	ds_read_b64_tr_b16 v[56:57], v168 offset:39936
	ds_read_b64_tr_b16 v[58:59], v168 offset:40448
	v_add_f32_e32 v116, v62, v120
	v_add_f32_e32 v116, v63, v116
	v_add_f32_e32 v116, 0, v116
	v_cvt_pk_bf16_f32 v130, v60, v61
	v_cvt_pk_bf16_f32 v131, v62, v63
	v_mfma_f32_32x32x16_bf16 v[80:95], v[112:115], v[144:147], v[80:95]
	s_add_i32 s28, s29, s28
	v_lshl_add_u64 v[60:61], v[172:173], 0, s[40:41]
	s_add_i32 s29, s28, 0x4000
	s_mov_b32 s33, m0
	s_mov_b32 m0, s29
	s_nop 0
	global_load_lds_dwordx4 v[60:61], off
	s_mov_b32 m0, s33
	v_lshl_add_u64 v[60:61], v[170:171], 0, s[42:43]
	s_mov_b32 s29, m0
	s_mov_b32 m0, s16
	s_nop 0
	global_load_lds_dwordx4 v[60:61], off
	s_mov_b32 m0, s29
	v_add_f32_e32 v175, v186, v116
	s_waitcnt lgkmcnt(14)
	v_mfma_f32_32x32x16_bf16 v[16:31], v[140:143], v[188:191], v[16:31]
	v_exp_f32_e32 v96, v96
	v_exp_f32_e32 v97, v97
	v_exp_f32_e32 v98, v98
	v_exp_f32_e32 v99, v99
	s_waitcnt lgkmcnt(12)
	v_mfma_f32_32x32x16_bf16 v[32:47], v[140:143], v[64:67], v[32:47]
	v_exp_f32_e32 v100, v100
	v_exp_f32_e32 v101, v101
	v_exp_f32_e32 v102, v102
	v_exp_f32_e32 v103, v103
	ds_read_b128 v[60:63], v182
	ds_read_b128 v[64:67], v182 offset:512
	s_waitcnt lgkmcnt(12)
	v_mfma_f32_32x32x16_bf16 v[16:31], v[136:139], v[68:71], v[16:31]
	v_exp_f32_e32 v104, v104
	v_exp_f32_e32 v105, v105
	v_exp_f32_e32 v106, v106
	v_exp_f32_e32 v107, v107
	ds_read_b128 v[68:71], v182 offset:2048
	ds_read_b128 v[160:163], v182 offset:2560
	s_waitcnt lgkmcnt(12)
	v_mfma_f32_32x32x16_bf16 v[32:47], v[136:139], v[72:75], v[32:47]
	v_exp_f32_e32 v108, v108
	v_exp_f32_e32 v109, v109
	v_exp_f32_e32 v110, v110
	v_exp_f32_e32 v111, v111
	ds_read_b128 v[72:75], v182 offset:4096
	ds_read_b128 v[164:167], v182 offset:4608
	s_waitcnt lgkmcnt(12)
	v_mfma_f32_32x32x16_bf16 v[16:31], v[132:135], v[76:79], v[16:31]
	v_exp_f32_e32 v80, v80
	v_exp_f32_e32 v81, v81
	v_exp_f32_e32 v82, v82
	v_exp_f32_e32 v83, v83
	ds_read_b128 v[76:79], v182 offset:6144
	ds_read_b128 v[184:187], v182 offset:6656
	s_waitcnt lgkmcnt(12)
	v_mfma_f32_32x32x16_bf16 v[32:47], v[132:135], v[48:51], v[32:47]
	v_exp_f32_e32 v84, v84
	v_exp_f32_e32 v85, v85
	v_exp_f32_e32 v86, v86
	v_exp_f32_e32 v87, v87
	s_waitcnt lgkmcnt(10)
	v_mfma_f32_32x32x16_bf16 v[16:31], v[128:131], v[52:55], v[16:31]
	v_exp_f32_e32 v88, v88
	v_exp_f32_e32 v89, v89
	v_exp_f32_e32 v90, v90
	v_exp_f32_e32 v91, v91
	s_waitcnt lgkmcnt(8)
	v_mfma_f32_32x32x16_bf16 v[32:47], v[128:131], v[56:59], v[32:47]
	v_exp_f32_e32 v92, v92
	v_exp_f32_e32 v93, v93
	v_exp_f32_e32 v94, v94
	v_exp_f32_e32 v95, v95
	s_waitcnt vmcnt(2) lgkmcnt(0)
	s_barrier
;   #define RESC() do{ if(!NOMAX&&resc){ asm volatile("s_waitcnt lgkmcnt(0)":::"memory"); \
;       _Pragma("unroll") for(int d_=0;d_<2*VM;++d_) _Pragma("unroll") for(int r=0;r<16;++r)o[d_][r]*=wsf[crow(r,hi)]; } }while(0)
;   #define ROT() do{sl_prev=sl_cur;sl_cur=sl_next;sl_next=(sl_next==(NSLOT-1)*SLOTB)?0:sl_next+SLOTB;}while(0)
;   #define ENDW(tt) do{ if((tt)+3<NT){ if constexpr(VM==2){WAIT_BAR(3);}else{WAIT_BAR(2);} } else if((tt)+2<NT){ if constexpr(VM==2){WAIT_BAR(2);}else{WAIT_BAR(1);} } else {WAIT_BAR(0);} }while(0)
; template<int THRL,int VM,bool NOMAX> __device__ __forceinline__ void attn_unit(const bf16*Qb,const bf16*__restrict__ Kh,const bf16*__restrict__ Vh,bf16*Ob,const int NT,const int sp,float*wscr,char*shm){
;     ...
;   for(;t+1<NT;t+=2){
;     STEP(pB0,pB1,pA0,pA1,t,(t+3<NT),(t+1<NT),(t+1<NT));       ENDW(t);   RESC(); ROT();
;     STEP(pA0,pA1,pB0,pB1,t+1,(t+4<NT),(t+2<NT),(t+2<NT));     ENDW(t+1); RESC(); ROT();
	ds_read_b64_tr_b16 v[188:189], v168 offset:40960
	ds_read_b64_tr_b16 v[190:191], v168 offset:41472
	v_add_f32_e32 v48, v96, v97
	v_add_f32_e32 v48, v98, v48
	v_add_f32_e32 v48, v99, v48
	v_add_f32_e32 v48, v100, v48
	v_add_f32_e32 v48, v101, v48
	v_cvt_pk_bf16_f32 v140, v96, v97
	v_cvt_pk_bf16_f32 v141, v98, v99
	s_waitcnt lgkmcnt(9)
	v_mfma_f32_32x32x16_bf16 v[112:127], v[60:63], v[156:159], 0
	ds_read_b64_tr_b16 v[96:97], v168 offset:45056
	ds_read_b64_tr_b16 v[98:99], v168 offset:45568
	v_add_f32_e32 v48, v102, v48
	v_add_f32_e32 v48, v103, v48
	v_add_f32_e32 v48, v104, v48
	v_add_f32_e32 v128, v105, v48
	s_waitcnt lgkmcnt(10)
	v_mfma_f32_32x32x16_bf16 v[48:63], v[64:67], v[156:159], 0
	v_cvt_pk_bf16_f32 v142, v100, v101
	v_cvt_pk_bf16_f32 v143, v102, v103
	ds_read_b64_tr_b16 v[64:65], v168 offset:41984
	ds_read_b64_tr_b16 v[66:67], v168 offset:42496
	v_add_f32_e32 v100, v106, v128
	v_add_f32_e32 v100, v107, v100
	v_add_f32_e32 v100, v108, v100
	v_add_f32_e32 v100, v109, v100
	v_cvt_pk_bf16_f32 v136, v104, v105
	v_cvt_pk_bf16_f32 v137, v106, v107
	s_waitcnt lgkmcnt(11)
	v_mfma_f32_32x32x16_bf16 v[112:127], v[68:71], v[152:155], v[112:127]
	ds_read_b64_tr_b16 v[68:69], v168 offset:46080
	ds_read_b64_tr_b16 v[70:71], v168 offset:46592
	s_waitcnt lgkmcnt(12)
	v_mfma_f32_32x32x16_bf16 v[48:63], v[160:163], v[152:155], v[48:63]
	v_add_f32_e32 v100, v110, v100
	v_add_f32_e32 v100, v111, v100
	v_add_f32_e32 v100, v80, v100
	v_add_f32_e32 v104, v81, v100
	v_cvt_pk_bf16_f32 v138, v108, v109
	v_cvt_pk_bf16_f32 v139, v110, v111
	ds_read_b64_tr_b16 v[100:101], v168 offset:43008
	ds_read_b64_tr_b16 v[102:103], v168 offset:43520
	v_add_f32_e32 v104, v82, v104
	v_add_f32_e32 v104, v83, v104
	v_add_f32_e32 v104, v84, v104
	v_add_f32_e32 v104, v85, v104
	v_cvt_pk_bf16_f32 v132, v80, v81
	v_cvt_pk_bf16_f32 v133, v82, v83
	s_waitcnt lgkmcnt(13)
	v_mfma_f32_32x32x16_bf16 v[112:127], v[72:75], v[148:151], v[112:127]
	ds_read_b64_tr_b16 v[72:73], v168 offset:47104
	ds_read_b64_tr_b16 v[74:75], v168 offset:47616
	s_waitcnt lgkmcnt(14)
	v_mfma_f32_32x32x16_bf16 v[48:63], v[164:167], v[148:151], v[48:63]
	v_add_f32_e32 v80, v86, v104
	v_add_f32_e32 v80, v87, v80
	v_add_f32_e32 v80, v88, v80
	v_add_f32_e32 v104, v89, v80
	v_cvt_pk_bf16_f32 v134, v84, v85
	v_cvt_pk_bf16_f32 v135, v86, v87
	ds_read_b64_tr_b16 v[80:81], v168 offset:44032
	ds_read_b64_tr_b16 v[82:83], v168 offset:44544
	v_add_f32_e32 v84, v90, v104
	v_add_f32_e32 v84, v91, v84
	v_add_f32_e32 v84, v92, v84
	v_add_f32_e32 v84, v93, v84
	v_cvt_pk_bf16_f32 v128, v88, v89
	v_cvt_pk_bf16_f32 v129, v90, v91
	s_waitcnt lgkmcnt(14)
	v_mfma_f32_32x32x16_bf16 v[112:127], v[76:79], v[144:147], v[112:127]
	ds_read_b64_tr_b16 v[76:77], v168 offset:48128
	ds_read_b64_tr_b16 v[78:79], v168 offset:48640
	v_mfma_f32_32x32x16_bf16 v[48:63], v[184:187], v[144:147], v[48:63]
	v_add_f32_e32 v84, v94, v84
	v_add_f32_e32 v84, v95, v84
	v_add_f32_e32 v84, 0, v84
	v_cvt_pk_bf16_f32 v130, v92, v93
	v_cvt_pk_bf16_f32 v131, v94, v95
	s_nop 0
	v_add_f32_e32 v175, v175, v84
	v_lshl_add_u64 v[84:85], v[172:173], 0, s[44:45]
	s_mov_b32 s29, m0
	s_mov_b32 m0, s17
	s_nop 0
	global_load_lds_dwordx4 v[84:85], off
	s_mov_b32 m0, s29
	v_lshl_add_u64 v[84:85], v[170:171], 0, s[48:49]
	s_add_i32 s17, s28, 0x8000
	s_mov_b32 s29, m0
	s_mov_b32 m0, s17
	s_nop 0
	global_load_lds_dwordx4 v[84:85], off
	s_mov_b32 m0, s29
	s_waitcnt lgkmcnt(14)
	v_mfma_f32_32x32x16_bf16 v[16:31], v[140:143], v[188:191], v[16:31]
	v_exp_f32_e32 v112, v112
	v_exp_f32_e32 v113, v113
	v_exp_f32_e32 v114, v114
	v_exp_f32_e32 v115, v115
	s_waitcnt lgkmcnt(12)
	v_mfma_f32_32x32x16_bf16 v[32:47], v[140:143], v[96:99], v[32:47]
	v_exp_f32_e32 v116, v116
	v_exp_f32_e32 v117, v117
	v_exp_f32_e32 v118, v118
	v_exp_f32_e32 v119, v119
	ds_read_b128 v[84:87], v182 offset:8192
	ds_read_b128 v[96:99], v182 offset:8704
	s_waitcnt lgkmcnt(12)
	v_mfma_f32_32x32x16_bf16 v[16:31], v[136:139], v[64:67], v[16:31]
	v_exp_f32_e32 v120, v120
	v_exp_f32_e32 v121, v121
	v_exp_f32_e32 v122, v122
	v_exp_f32_e32 v123, v123
	ds_read_b128 v[104:107], v182 offset:10240
	ds_read_b128 v[108:111], v182 offset:10752
	s_waitcnt lgkmcnt(12)
	v_mfma_f32_32x32x16_bf16 v[32:47], v[136:139], v[68:71], v[32:47]
	v_exp_f32_e32 v124, v124
	v_exp_f32_e32 v125, v125
	v_exp_f32_e32 v126, v126
	v_exp_f32_e32 v127, v127
	ds_read_b128 v[160:163], v182 offset:12288
	ds_read_b128 v[164:167], v182 offset:12800
	s_waitcnt lgkmcnt(12)
	v_mfma_f32_32x32x16_bf16 v[16:31], v[132:135], v[100:103], v[16:31]
	v_exp_f32_e32 v48, v48
	v_exp_f32_e32 v49, v49
	v_exp_f32_e32 v50, v50
	v_exp_f32_e32 v51, v51
	ds_read_b128 v[100:103], v182 offset:14336
	ds_read_b128 v[184:187], v182 offset:14848
	s_waitcnt lgkmcnt(12)
	v_mfma_f32_32x32x16_bf16 v[32:47], v[132:135], v[72:75], v[32:47]
	v_exp_f32_e32 v52, v52
	v_exp_f32_e32 v53, v53
	v_exp_f32_e32 v54, v54
	v_exp_f32_e32 v55, v55
	s_waitcnt lgkmcnt(10)
	v_mfma_f32_32x32x16_bf16 v[16:31], v[128:131], v[80:83], v[16:31]
	v_exp_f32_e32 v56, v56
	v_exp_f32_e32 v57, v57
	v_exp_f32_e32 v58, v58
	v_exp_f32_e32 v59, v59
	s_waitcnt lgkmcnt(8)
	v_mfma_f32_32x32x16_bf16 v[32:47], v[128:131], v[76:79], v[32:47]
	v_exp_f32_e32 v60, v60
	v_exp_f32_e32 v61, v61
	v_exp_f32_e32 v62, v62
	v_exp_f32_e32 v63, v63
	s_waitcnt vmcnt(2) lgkmcnt(0)
	s_barrier
;   #define RESC() do{ if(!NOMAX&&resc){ asm volatile("s_waitcnt lgkmcnt(0)":::"memory"); \
;       _Pragma("unroll") for(int d_=0;d_<2*VM;++d_) _Pragma("unroll") for(int r=0;r<16;++r)o[d_][r]*=wsf[crow(r,hi)]; } }while(0)
;   #define ROT() do{sl_prev=sl_cur;sl_cur=sl_next;sl_next=(sl_next==(NSLOT-1)*SLOTB)?0:sl_next+SLOTB;}while(0)
;   #define ENDW(tt) do{ if((tt)+3<NT){ if constexpr(VM==2){WAIT_BAR(3);}else{WAIT_BAR(2);} } else if((tt)+2<NT){ if constexpr(VM==2){WAIT_BAR(2);}else{WAIT_BAR(1);} } else {WAIT_BAR(0);} }while(0)
; template<int THRL,int VM,bool NOMAX> __device__ __forceinline__ void attn_unit(const bf16*Qb,const bf16*__restrict__ Kh,const bf16*__restrict__ Vh,bf16*Ob,const int NT,const int sp,float*wscr,char*shm){
;     ...
;   for(;t+1<NT;t+=2){
;     STEP(pB0,pB1,pA0,pA1,t,(t+3<NT),(t+1<NT),(t+1<NT));       ENDW(t);   RESC(); ROT();
;     STEP(pA0,pA1,pB0,pB1,t+1,(t+4<NT),(t+2<NT),(t+2<NT));     ENDW(t+1); RESC(); ROT();
	ds_read_b64_tr_b16 v[188:189], v168 offset:24576
	ds_read_b64_tr_b16 v[190:191], v168 offset:25088
	v_add_f32_e32 v64, v112, v113
	v_add_f32_e32 v64, v114, v64
	v_add_f32_e32 v64, v115, v64
	v_add_f32_e32 v64, v116, v64
	v_add_f32_e32 v64, v117, v64
	v_cvt_pk_bf16_f32 v140, v112, v113
	v_cvt_pk_bf16_f32 v141, v114, v115
	s_waitcnt lgkmcnt(9)
	v_mfma_f32_32x32x16_bf16 v[80:95], v[84:87], v[156:159], 0
	ds_read_b64_tr_b16 v[112:113], v168 offset:28672
	ds_read_b64_tr_b16 v[114:115], v168 offset:29184
	v_add_f32_e32 v64, v118, v64
	v_add_f32_e32 v64, v119, v64
	v_add_f32_e32 v64, v120, v64
	v_add_f32_e32 v128, v121, v64
	v_cvt_pk_bf16_f32 v142, v116, v117
	v_cvt_pk_bf16_f32 v143, v118, v119
	s_waitcnt lgkmcnt(10)
	v_mfma_f32_32x32x16_bf16 v[64:79], v[96:99], v[156:159], 0
	ds_read_b64_tr_b16 v[96:97], v168 offset:25600
	ds_read_b64_tr_b16 v[98:99], v168 offset:26112
	v_add_f32_e32 v116, v122, v128
	v_add_f32_e32 v116, v123, v116
	v_add_f32_e32 v116, v124, v116
	v_add_f32_e32 v116, v125, v116
	v_cvt_pk_bf16_f32 v136, v120, v121
	v_cvt_pk_bf16_f32 v137, v122, v123
	s_waitcnt lgkmcnt(11)
	v_mfma_f32_32x32x16_bf16 v[80:95], v[104:107], v[152:155], v[80:95]
	ds_read_b64_tr_b16 v[104:105], v168 offset:29696
	ds_read_b64_tr_b16 v[106:107], v168 offset:30208
	v_add_f32_e32 v116, v126, v116
	v_add_f32_e32 v116, v127, v116
	v_add_f32_e32 v116, v48, v116
	v_add_f32_e32 v116, v49, v116
	v_cvt_pk_bf16_f32 v138, v124, v125
	v_cvt_pk_bf16_f32 v139, v126, v127
	s_waitcnt lgkmcnt(12)
	v_mfma_f32_32x32x16_bf16 v[64:79], v[108:111], v[152:155], v[64:79]
	ds_read_b64_tr_b16 v[108:109], v168 offset:26624
	ds_read_b64_tr_b16 v[110:111], v168 offset:27136
	v_add_f32_e32 v116, v50, v116
	v_add_f32_e32 v116, v51, v116
	v_add_f32_e32 v116, v52, v116
	v_add_f32_e32 v116, v53, v116
	v_cvt_pk_bf16_f32 v132, v48, v49
	v_cvt_pk_bf16_f32 v133, v50, v51
	s_waitcnt lgkmcnt(13)
	v_mfma_f32_32x32x16_bf16 v[80:95], v[160:163], v[148:151], v[80:95]
	ds_read_b64_tr_b16 v[48:49], v168 offset:30720
	ds_read_b64_tr_b16 v[50:51], v168 offset:31232
	v_add_f32_e32 v116, v54, v116
	v_add_f32_e32 v116, v55, v116
	v_add_f32_e32 v116, v56, v116
	v_add_f32_e32 v116, v57, v116
	v_cvt_pk_bf16_f32 v134, v52, v53
	v_cvt_pk_bf16_f32 v135, v54, v55
	s_waitcnt lgkmcnt(14)
	v_mfma_f32_32x32x16_bf16 v[64:79], v[164:167], v[148:151], v[64:79]
	ds_read_b64_tr_b16 v[52:53], v168 offset:27648
	ds_read_b64_tr_b16 v[54:55], v168 offset:28160
	v_add_f32_e32 v116, v58, v116
	v_add_f32_e32 v116, v59, v116
	v_add_f32_e32 v116, v60, v116
	v_add_f32_e32 v116, v61, v116
	v_cvt_pk_bf16_f32 v128, v56, v57
	v_cvt_pk_bf16_f32 v129, v58, v59
	s_waitcnt lgkmcnt(14)
	v_mfma_f32_32x32x16_bf16 v[80:95], v[100:103], v[144:147], v[80:95]
	ds_read_b64_tr_b16 v[56:57], v168 offset:31744
	ds_read_b64_tr_b16 v[58:59], v168 offset:32256
	v_add_f32_e32 v100, v62, v116
	v_add_f32_e32 v100, v63, v100
	v_add_f32_e32 v100, 0, v100
	v_cvt_pk_bf16_f32 v130, v60, v61
	v_cvt_pk_bf16_f32 v131, v62, v63
	v_mfma_f32_32x32x16_bf16 v[64:79], v[184:187], v[144:147], v[64:79]
	v_lshl_add_u64 v[60:61], v[170:171], 0, s[40:41]
	s_add_i32 s28, s28, 0xa000
	s_mov_b32 s17, m0
	s_mov_b32 m0, s28
	s_nop 0
	global_load_lds_dwordx4 v[60:61], off
	s_mov_b32 m0, s17
	v_add_f32_e32 v172, v175, v100
	s_waitcnt lgkmcnt(14)
	v_mfma_f32_32x32x16_bf16 v[16:31], v[140:143], v[188:191], v[16:31]
	v_exp_f32_e32 v80, v80
	v_exp_f32_e32 v81, v81
	v_exp_f32_e32 v82, v82
	v_exp_f32_e32 v83, v83
	s_waitcnt lgkmcnt(12)
	v_mfma_f32_32x32x16_bf16 v[32:47], v[140:143], v[112:115], v[32:47]
	v_exp_f32_e32 v84, v84
	v_exp_f32_e32 v85, v85
	v_exp_f32_e32 v86, v86
	v_exp_f32_e32 v87, v87
	ds_read_b128 v[60:63], v182 offset:16384
	ds_read_b128 v[112:115], v182 offset:16896
	s_waitcnt lgkmcnt(12)
	v_mfma_f32_32x32x16_bf16 v[16:31], v[136:139], v[96:99], v[16:31]
	v_exp_f32_e32 v88, v88
	v_exp_f32_e32 v89, v89
	v_exp_f32_e32 v90, v90
	v_exp_f32_e32 v91, v91
	ds_read_b128 v[116:119], v182 offset:18432
	ds_read_b128 v[120:123], v182 offset:18944
	s_waitcnt lgkmcnt(12)
	v_mfma_f32_32x32x16_bf16 v[32:47], v[136:139], v[104:107], v[32:47]
	v_exp_f32_e32 v92, v92
	v_exp_f32_e32 v93, v93
	v_exp_f32_e32 v94, v94
	v_exp_f32_e32 v95, v95
	ds_read_b128 v[124:127], v182 offset:20480
	ds_read_b128 v[160:163], v182 offset:20992
	s_waitcnt lgkmcnt(12)
	v_mfma_f32_32x32x16_bf16 v[16:31], v[132:135], v[108:111], v[16:31]
	v_exp_f32_e32 v64, v64
	v_exp_f32_e32 v65, v65
	v_exp_f32_e32 v66, v66
	v_exp_f32_e32 v67, v67
	ds_read_b128 v[164:167], v182 offset:22528
	ds_read_b128 v[184:187], v182 offset:23040
	s_waitcnt lgkmcnt(12)
	v_mfma_f32_32x32x16_bf16 v[32:47], v[132:135], v[48:51], v[32:47]
	v_exp_f32_e32 v68, v68
	v_exp_f32_e32 v69, v69
	v_exp_f32_e32 v70, v70
	v_exp_f32_e32 v71, v71
	s_waitcnt lgkmcnt(10)
	v_mfma_f32_32x32x16_bf16 v[16:31], v[128:131], v[52:55], v[16:31]
	v_exp_f32_e32 v72, v72
	v_exp_f32_e32 v73, v73
	v_exp_f32_e32 v74, v74
	v_exp_f32_e32 v75, v75
	s_waitcnt lgkmcnt(8)
	v_mfma_f32_32x32x16_bf16 v[32:47], v[128:131], v[56:59], v[32:47]
	v_exp_f32_e32 v76, v76
	v_exp_f32_e32 v77, v77
	v_exp_f32_e32 v78, v78
	v_exp_f32_e32 v79, v79
	s_waitcnt vmcnt(1) lgkmcnt(0)
	s_barrier
;   #define RESC() do{ if(!NOMAX&&resc){ asm volatile("s_waitcnt lgkmcnt(0)":::"memory"); \
;       _Pragma("unroll") for(int d_=0;d_<2*VM;++d_) _Pragma("unroll") for(int r=0;r<16;++r)o[d_][r]*=wsf[crow(r,hi)]; } }while(0)
;   #define ROT() do{sl_prev=sl_cur;sl_cur=sl_next;sl_next=(sl_next==(NSLOT-1)*SLOTB)?0:sl_next+SLOTB;}while(0)
;   #define ENDW(tt) do{ if((tt)+3<NT){ if constexpr(VM==2){WAIT_BAR(3);}else{WAIT_BAR(2);} } else if((tt)+2<NT){ if constexpr(VM==2){WAIT_BAR(2);}else{WAIT_BAR(1);} } else {WAIT_BAR(0);} }while(0)
; template<int THRL,int VM,bool NOMAX> __device__ __forceinline__ void attn_unit(const bf16*Qb,const bf16*__restrict__ Kh,const bf16*__restrict__ Vh,bf16*Ob,const int NT,const int sp,float*wscr,char*shm){
;     ...
;   for(;t+1<NT;t+=2){
;     STEP(pB0,pB1,pA0,pA1,t,(t+3<NT),(t+1<NT),(t+1<NT));       ENDW(t);   RESC(); ROT();
;     STEP(pA0,pA1,pB0,pB1,t+1,(t+4<NT),(t+2<NT),(t+2<NT));     ENDW(t+1); RESC(); ROT();
	ds_read_b64_tr_b16 v[188:189], v168 offset:32768
	ds_read_b64_tr_b16 v[190:191], v168 offset:33280
	v_add_f32_e32 v48, v80, v81
	v_add_f32_e32 v48, v82, v48
	v_add_f32_e32 v48, v83, v48
	v_add_f32_e32 v48, v84, v48
	v_add_f32_e32 v48, v85, v48
	v_cvt_pk_bf16_f32 v140, v80, v81
	v_cvt_pk_bf16_f32 v141, v82, v83
	s_waitcnt lgkmcnt(9)
	v_mfma_f32_32x32x16_bf16 v[96:111], v[60:63], v[156:159], 0
	ds_read_b64_tr_b16 v[80:81], v168 offset:36864
	ds_read_b64_tr_b16 v[82:83], v168 offset:37376
	v_add_f32_e32 v48, v86, v48
	v_add_f32_e32 v48, v87, v48
	v_add_f32_e32 v48, v88, v48
	v_add_f32_e32 v128, v89, v48
	s_waitcnt lgkmcnt(10)
	v_mfma_f32_32x32x16_bf16 v[48:63], v[112:115], v[156:159], 0
	v_cvt_pk_bf16_f32 v142, v84, v85
	v_cvt_pk_bf16_f32 v143, v86, v87
	ds_read_b64_tr_b16 v[84:85], v168 offset:33792
	ds_read_b64_tr_b16 v[86:87], v168 offset:34304
	v_add_f32_e32 v112, v90, v128
	v_add_f32_e32 v112, v91, v112
	v_add_f32_e32 v112, v92, v112
	v_add_f32_e32 v112, v93, v112
	v_cvt_pk_bf16_f32 v136, v88, v89
	v_cvt_pk_bf16_f32 v137, v90, v91
	s_waitcnt lgkmcnt(11)
	v_mfma_f32_32x32x16_bf16 v[96:111], v[116:119], v[152:155], v[96:111]
	ds_read_b64_tr_b16 v[88:89], v168 offset:37888
	ds_read_b64_tr_b16 v[90:91], v168 offset:38400
	s_waitcnt lgkmcnt(12)
	v_mfma_f32_32x32x16_bf16 v[48:63], v[120:123], v[152:155], v[48:63]
	v_add_f32_e32 v112, v94, v112
	v_add_f32_e32 v112, v95, v112
	v_add_f32_e32 v112, v64, v112
	v_add_f32_e32 v112, v65, v112
	v_cvt_pk_bf16_f32 v138, v92, v93
	v_cvt_pk_bf16_f32 v139, v94, v95
	ds_read_b64_tr_b16 v[92:93], v168 offset:34816
	ds_read_b64_tr_b16 v[94:95], v168 offset:35328
	v_add_f32_e32 v112, v66, v112
	v_add_f32_e32 v112, v67, v112
	v_add_f32_e32 v112, v68, v112
	v_add_f32_e32 v112, v69, v112
	v_cvt_pk_bf16_f32 v132, v64, v65
	v_cvt_pk_bf16_f32 v133, v66, v67
	s_waitcnt lgkmcnt(13)
	v_mfma_f32_32x32x16_bf16 v[96:111], v[124:127], v[148:151], v[96:111]
	ds_read_b64_tr_b16 v[64:65], v168 offset:38912
	ds_read_b64_tr_b16 v[66:67], v168 offset:39424
	s_waitcnt lgkmcnt(14)
	v_mfma_f32_32x32x16_bf16 v[48:63], v[160:163], v[148:151], v[48:63]
	v_add_f32_e32 v112, v70, v112
	v_add_f32_e32 v112, v71, v112
	v_add_f32_e32 v112, v72, v112
	v_add_f32_e32 v112, v73, v112
	v_cvt_pk_bf16_f32 v134, v68, v69
	v_cvt_pk_bf16_f32 v135, v70, v71
	ds_read_b64_tr_b16 v[68:69], v168 offset:35840
	ds_read_b64_tr_b16 v[70:71], v168 offset:36352
	v_add_f32_e32 v112, v74, v112
	v_add_f32_e32 v112, v75, v112
	v_add_f32_e32 v112, v76, v112
	v_add_f32_e32 v112, v77, v112
	v_cvt_pk_bf16_f32 v128, v72, v73
	v_cvt_pk_bf16_f32 v129, v74, v75
	s_waitcnt lgkmcnt(14)
	v_mfma_f32_32x32x16_bf16 v[96:111], v[164:167], v[144:147], v[96:111]
	ds_read_b64_tr_b16 v[72:73], v168 offset:39936
	ds_read_b64_tr_b16 v[74:75], v168 offset:40448
	v_mfma_f32_32x32x16_bf16 v[48:63], v[184:187], v[144:147], v[48:63]
	v_add_f32_e32 v112, v78, v112
	v_add_f32_e32 v112, v79, v112
	v_add_f32_e32 v112, 0, v112
	v_cvt_pk_bf16_f32 v130, v76, v77
	v_cvt_pk_bf16_f32 v131, v78, v79
	v_lshl_add_u64 v[76:77], v[170:171], 0, s[44:45]
	s_mov_b32 s17, m0
	s_mov_b32 m0, s16
	s_nop 0
	global_load_lds_dwordx4 v[76:77], off
	s_mov_b32 m0, s17
	v_add_f32_e32 v120, v172, v112
	s_waitcnt lgkmcnt(14)
	v_mfma_f32_32x32x16_bf16 v[16:31], v[140:143], v[188:191], v[16:31]
	v_exp_f32_e32 v96, v96
	v_exp_f32_e32 v97, v97
	v_exp_f32_e32 v98, v98
	v_exp_f32_e32 v99, v99
	s_waitcnt lgkmcnt(12)
	v_mfma_f32_32x32x16_bf16 v[32:47], v[140:143], v[80:83], v[32:47]
	v_exp_f32_e32 v100, v100
	v_exp_f32_e32 v101, v101
	v_exp_f32_e32 v102, v102
	v_exp_f32_e32 v103, v103
	ds_read_b128 v[76:79], v182
	ds_read_b128 v[80:83], v182 offset:512
	s_waitcnt lgkmcnt(12)
	v_mfma_f32_32x32x16_bf16 v[16:31], v[136:139], v[84:87], v[16:31]
	v_exp_f32_e32 v104, v104
	v_exp_f32_e32 v105, v105
	v_exp_f32_e32 v106, v106
	v_exp_f32_e32 v107, v107
	ds_read_b128 v[122:125], v182 offset:2048
	ds_read_b128 v[160:163], v182 offset:2560
	s_waitcnt lgkmcnt(12)
	v_mfma_f32_32x32x16_bf16 v[32:47], v[136:139], v[88:91], v[32:47]
	v_exp_f32_e32 v108, v108
	v_exp_f32_e32 v109, v109
	v_exp_f32_e32 v110, v110
	v_exp_f32_e32 v111, v111
	ds_read_b128 v[164:167], v182 offset:4096
	ds_read_b128 v[170:173], v182 offset:4608
	s_waitcnt lgkmcnt(12)
	v_mfma_f32_32x32x16_bf16 v[16:31], v[132:135], v[92:95], v[16:31]
	v_exp_f32_e32 v48, v48
	v_exp_f32_e32 v49, v49
	v_exp_f32_e32 v50, v50
	v_exp_f32_e32 v51, v51
	ds_read_b128 v[184:187], v182 offset:6144
	ds_read_b128 v[188:191], v182 offset:6656
	s_waitcnt lgkmcnt(12)
	v_mfma_f32_32x32x16_bf16 v[32:47], v[132:135], v[64:67], v[32:47]
	v_exp_f32_e32 v52, v52
	v_exp_f32_e32 v53, v53
	v_exp_f32_e32 v54, v54
	v_exp_f32_e32 v55, v55
	s_waitcnt lgkmcnt(10)
	v_mfma_f32_32x32x16_bf16 v[16:31], v[128:131], v[68:71], v[16:31]
	v_exp_f32_e32 v56, v56
	v_exp_f32_e32 v57, v57
	v_exp_f32_e32 v58, v58
	v_exp_f32_e32 v59, v59
	s_waitcnt lgkmcnt(8)
	v_mfma_f32_32x32x16_bf16 v[32:47], v[128:131], v[72:75], v[32:47]
	v_exp_f32_e32 v60, v60
	v_exp_f32_e32 v61, v61
	v_exp_f32_e32 v62, v62
	v_exp_f32_e32 v63, v63
	s_waitcnt vmcnt(0) lgkmcnt(0)
	s_barrier
	ds_read_b64_tr_b16 v[112:113], v168 offset:40960
	ds_read_b64_tr_b16 v[114:115], v168 offset:41472
	v_add_f32_e32 v64, v96, v97
	v_add_f32_e32 v64, v98, v64
	v_add_f32_e32 v64, v99, v64
	v_add_f32_e32 v64, v100, v64
	v_add_f32_e32 v84, v101, v64
	v_cvt_pk_bf16_f32 v140, v96, v97
	v_cvt_pk_bf16_f32 v141, v98, v99
	s_waitcnt lgkmcnt(9)
	v_mfma_f32_32x32x16_bf16 v[64:79], v[76:79], v[156:159], 0
	ds_read_b64_tr_b16 v[96:97], v168 offset:45056
	ds_read_b64_tr_b16 v[98:99], v168 offset:45568
	v_add_f32_e32 v84, v102, v84
	v_add_f32_e32 v84, v103, v84
	v_add_f32_e32 v84, v104, v84
	v_add_f32_e32 v121, v105, v84
	v_cvt_pk_bf16_f32 v142, v100, v101
	v_cvt_pk_bf16_f32 v143, v102, v103
	s_waitcnt lgkmcnt(10)
	v_mfma_f32_32x32x16_bf16 v[80:95], v[80:83], v[156:159], 0
	ds_read_b64_tr_b16 v[116:117], v168 offset:41984
	ds_read_b64_tr_b16 v[118:119], v168 offset:42496
	v_add_f32_e32 v100, v106, v121
	v_add_f32_e32 v100, v107, v100
	v_add_f32_e32 v100, v108, v100
	v_add_f32_e32 v121, v109, v100
	v_cvt_pk_bf16_f32 v136, v104, v105
	v_cvt_pk_bf16_f32 v137, v106, v107
	s_waitcnt lgkmcnt(11)
	v_mfma_f32_32x32x16_bf16 v[64:79], v[122:125], v[152:155], v[64:79]
	ds_read_b64_tr_b16 v[100:101], v168 offset:46080
	ds_read_b64_tr_b16 v[102:103], v168 offset:46592
	v_add_f32_e32 v104, v110, v121
	v_add_f32_e32 v104, v111, v104
	v_add_f32_e32 v104, v48, v104
	v_add_f32_e32 v121, v49, v104
	v_cvt_pk_bf16_f32 v138, v108, v109
	v_cvt_pk_bf16_f32 v139, v110, v111
	s_waitcnt lgkmcnt(12)
	v_mfma_f32_32x32x16_bf16 v[80:95], v[160:163], v[152:155], v[80:95]
	ds_read_b64_tr_b16 v[104:105], v168 offset:43008
	ds_read_b64_tr_b16 v[106:107], v168 offset:43520
	v_add_f32_e32 v108, v50, v121
	v_add_f32_e32 v108, v51, v108
	v_add_f32_e32 v108, v52, v108
	v_add_f32_e32 v108, v53, v108
	v_cvt_pk_bf16_f32 v132, v48, v49
	v_cvt_pk_bf16_f32 v133, v50, v51
	s_waitcnt lgkmcnt(13)
	v_mfma_f32_32x32x16_bf16 v[64:79], v[164:167], v[148:151], v[64:79]
	ds_read_b64_tr_b16 v[48:49], v168 offset:47104
	ds_read_b64_tr_b16 v[50:51], v168 offset:47616
	v_add_f32_e32 v108, v54, v108
	v_add_f32_e32 v108, v55, v108
	v_add_f32_e32 v108, v56, v108
	v_add_f32_e32 v121, v57, v108
	v_cvt_pk_bf16_f32 v134, v52, v53
	v_cvt_pk_bf16_f32 v135, v54, v55
	s_waitcnt lgkmcnt(14)
	v_mfma_f32_32x32x16_bf16 v[80:95], v[170:173], v[148:151], v[80:95]
	ds_read_b64_tr_b16 v[108:109], v168 offset:44032
	ds_read_b64_tr_b16 v[110:111], v168 offset:44544
	v_add_f32_e32 v52, v58, v121
	v_add_f32_e32 v52, v59, v52
	v_add_f32_e32 v52, v60, v52
	v_add_f32_e32 v121, v61, v52
	v_cvt_pk_bf16_f32 v128, v56, v57
	v_cvt_pk_bf16_f32 v129, v58, v59
	s_waitcnt lgkmcnt(14)
	v_mfma_f32_32x32x16_bf16 v[64:79], v[184:187], v[144:147], v[64:79]
	ds_read_b64_tr_b16 v[52:53], v168 offset:48128
	ds_read_b64_tr_b16 v[54:55], v168 offset:48640
	v_add_f32_e32 v56, v62, v121
	v_add_f32_e32 v56, v63, v56
	v_add_f32_e32 v56, 0, v56
	v_cvt_pk_bf16_f32 v130, v60, v61
	v_cvt_pk_bf16_f32 v131, v62, v63
	v_mfma_f32_32x32x16_bf16 v[80:95], v[188:191], v[144:147], v[80:95]
	s_nop 3
	v_exp_f32_e32 v64, v64
	v_exp_f32_e32 v65, v65
	v_exp_f32_e32 v66, v66
	v_exp_f32_e32 v67, v67
	s_nop 0
	v_exp_f32_e32 v68, v68
	v_exp_f32_e32 v69, v69
	v_exp_f32_e32 v70, v70
	v_exp_f32_e32 v71, v71
	s_nop 0
	v_exp_f32_e32 v72, v72
	v_exp_f32_e32 v73, v73
	v_exp_f32_e32 v74, v74
	v_exp_f32_e32 v75, v75
	s_nop 0
	v_exp_f32_e32 v76, v76
	v_exp_f32_e32 v77, v77
	v_exp_f32_e32 v78, v78
	v_exp_f32_e32 v79, v79
	v_exp_f32_e32 v80, v80
	v_exp_f32_e32 v81, v81
	v_exp_f32_e32 v82, v82
	v_exp_f32_e32 v83, v83
	s_nop 0
	v_exp_f32_e32 v84, v84
	v_exp_f32_e32 v85, v85
	v_exp_f32_e32 v86, v86
	v_exp_f32_e32 v87, v87
	s_nop 0
	v_exp_f32_e32 v88, v88
	v_exp_f32_e32 v89, v89
	v_exp_f32_e32 v90, v90
	v_exp_f32_e32 v91, v91
	s_nop 0
	v_exp_f32_e32 v92, v92
	v_exp_f32_e32 v93, v93
	v_exp_f32_e32 v94, v94
	v_exp_f32_e32 v95, v95
	s_waitcnt lgkmcnt(14)
; #define SBAR() __builtin_amdgcn_sched_barrier(0)
;   #define RESC() do{ if(!NOMAX&&resc){ asm volatile("s_waitcnt lgkmcnt(0)":::"memory"); \
;       _Pragma("unroll") for(int d_=0;d_<2*VM;++d_) _Pragma("unroll") for(int r=0;r<16;++r)o[d_][r]*=wsf[crow(r,hi)]; } }while(0)
;   #define PKW(P,B) cvtpk_s(P[B],P[B+1])
; template<int THRL,int VM,bool NOMAX> __device__ __forceinline__ void attn_unit(const bf16*Qb,const bf16*__restrict__ Kh,const bf16*__restrict__ Vh,bf16*Ob,const int NT,const int sp,float*wscr,char*shm){
;     ...
;   STEP(pB0,pB1,pA0,pA1,NT-1,false,false,false); RESC();
;   { float sacc=pB0[0]+pB0[1]; _Pragma("unroll") for(int r=2;r<16;++r)sacc+=pB0[r]; _Pragma("unroll") for(int r=0;r<16;++r)sacc+=pB1[r]; l_reg+=sacc;
;     pw0=(u32x4){PKW(pB0,0),PKW(pB0,2),PKW(pB0,4),PKW(pB0,6)};pw1=(u32x4){PKW(pB0,8),PKW(pB0,10),PKW(pB0,12),PKW(pB0,14)};pw2=(u32x4){PKW(pB1,0),PKW(pB1,2),PKW(pB1,4),PKW(pB1,6)};pw3=(u32x4){PKW(pB1,8),PKW(pB1,10),PKW(pB1,12),PKW(pB1,14)};
;     SBAR(); pv(o,vb0+VM*sl_cur,PAF(0),PAF(1),PAF(2),PAF(3)); if constexpr(VM==2) pv(o+2,vb0+VM*sl_cur+8192,PAF(0),PAF(1),PAF(2),PAF(3)); }
;     ...
;   {auto rr=__builtin_amdgcn_permlane32_swap(__float_as_uint(l_reg),__float_as_uint(l_reg),false,false);l_reg=__uint_as_float(rr[0])+__uint_as_float(rr[1]);}
;   if(hi==0)wsf[32+r32]=l_reg;asm volatile("s_waitcnt lgkmcnt(0)":::"memory");
	v_mfma_f32_32x32x16_bf16 v[16:31], v[140:143], v[112:115], v[16:31]
	v_add_f32_e32 v57, v64, v65
	v_add_f32_e32 v57, v66, v57
	v_add_f32_e32 v57, v67, v57
	v_add_f32_e32 v57, v68, v57
	v_add_f32_e32 v57, v69, v57
	v_add_f32_e32 v57, v70, v57
	v_add_f32_e32 v57, v71, v57
	s_waitcnt lgkmcnt(12)
	v_mfma_f32_32x32x16_bf16 v[32:47], v[140:143], v[96:99], v[32:47]
	v_add_f32_e32 v57, v72, v57
	v_add_f32_e32 v57, v73, v57
	v_add_f32_e32 v57, v74, v57
	v_add_f32_e32 v57, v75, v57
	v_add_f32_e32 v57, v76, v57
	v_add_f32_e32 v57, v77, v57
	v_add_f32_e32 v57, v78, v57
	s_waitcnt lgkmcnt(10)
	v_mfma_f32_32x32x16_bf16 v[16:31], v[136:139], v[116:119], v[16:31]
	v_add_f32_e32 v57, v79, v57
	v_add_f32_e32 v57, v80, v57
	v_add_f32_e32 v57, v81, v57
	v_add_f32_e32 v57, v82, v57
	v_add_f32_e32 v57, v83, v57
	v_add_f32_e32 v57, v84, v57
	v_add_f32_e32 v57, v85, v57
	s_waitcnt lgkmcnt(8)
	v_mfma_f32_32x32x16_bf16 v[32:47], v[136:139], v[100:103], v[32:47]
	v_add_f32_e32 v57, v86, v57
	v_add_f32_e32 v57, v87, v57
	v_add_f32_e32 v57, v88, v57
	v_add_f32_e32 v57, v89, v57
	v_add_f32_e32 v57, v90, v57
	v_add_f32_e32 v57, v91, v57
	v_add_f32_e32 v57, v92, v57
	s_waitcnt lgkmcnt(6)
	v_mfma_f32_32x32x16_bf16 v[16:31], v[132:135], v[104:107], v[16:31]
	v_add_f32_e32 v57, v93, v57
	v_add_f32_e32 v57, v94, v57
	v_add_f32_e32 v57, v95, v57
	v_add_f32_e32 v56, v120, v56
	v_add_f32_e32 v56, v56, v57
	v_cvt_pk_bf16_f32 v58, v64, v65
	v_cvt_pk_bf16_f32 v59, v66, v67
	s_waitcnt lgkmcnt(4)
	v_mfma_f32_32x32x16_bf16 v[32:47], v[132:135], v[48:51], v[32:47]
	v_cvt_pk_bf16_f32 v48, v80, v81
	v_cvt_pk_bf16_f32 v60, v68, v69
	v_cvt_pk_bf16_f32 v61, v70, v71
	v_cvt_pk_bf16_f32 v62, v72, v73
	v_cvt_pk_bf16_f32 v63, v74, v75
	v_cvt_pk_bf16_f32 v64, v76, v77
	v_cvt_pk_bf16_f32 v65, v78, v79
	s_waitcnt lgkmcnt(2)
	v_mfma_f32_32x32x16_bf16 v[16:31], v[128:131], v[108:111], v[16:31]
	v_cvt_pk_bf16_f32 v49, v82, v83
	v_cvt_pk_bf16_f32 v50, v84, v85
	v_cvt_pk_bf16_f32 v51, v86, v87
	v_cvt_pk_bf16_f32 v66, v88, v89
	v_cvt_pk_bf16_f32 v67, v90, v91
	v_cvt_pk_bf16_f32 v68, v92, v93
	v_cvt_pk_bf16_f32 v69, v94, v95
	s_waitcnt lgkmcnt(0)
	v_mfma_f32_32x32x16_bf16 v[32:47], v[128:131], v[52:55], v[32:47]
	ds_read_b64_tr_b16 v[52:53],v174 offset:0
	ds_read_b64_tr_b16 v[54:55],v174 offset:512
	ds_read_b64_tr_b16 v[70:71],v174 offset:1024
	ds_read_b64_tr_b16 v[72:73],v174 offset:1536
	ds_read_b64_tr_b16 v[74:75],v174 offset:2048
	ds_read_b64_tr_b16 v[76:77],v174 offset:2560
	ds_read_b64_tr_b16 v[78:79],v174 offset:3072
	ds_read_b64_tr_b16 v[80:81],v174 offset:3584
	s_waitcnt lgkmcnt(0)
	s_nop 0
	v_mfma_f32_32x32x16_bf16 v[16:31], v[58:61], v[52:55], v[16:31]
	ds_read_b64_tr_b16 v[52:53],v174 offset:4096
	ds_read_b64_tr_b16 v[54:55],v174 offset:4608
	v_mfma_f32_32x32x16_bf16 v[16:31], v[62:65], v[70:73], v[16:31]
	ds_read_b64_tr_b16 v[70:71],v174 offset:5120
	ds_read_b64_tr_b16 v[72:73],v174 offset:5632
	v_mfma_f32_32x32x16_bf16 v[16:31], v[48:51], v[74:77], v[16:31]
	ds_read_b64_tr_b16 v[74:75],v174 offset:6144
	ds_read_b64_tr_b16 v[76:77],v174 offset:6656
	ds_read_b64_tr_b16 v[82:83],v174 offset:7168
	ds_read_b64_tr_b16 v[84:85],v174 offset:7680
	s_waitcnt lgkmcnt(0)
	v_mfma_f32_32x32x16_bf16 v[16:31], v[66:69], v[78:81], v[16:31]
	v_mfma_f32_32x32x16_bf16 v[32:47], v[58:61], v[52:55], v[32:47]
	v_cmp_gt_u32_e32 vcc, 32, v178
	v_mfma_f32_32x32x16_bf16 v[32:47], v[62:65], v[70:73], v[32:47]
	v_mfma_f32_32x32x16_bf16 v[32:47], v[48:51], v[74:77], v[32:47]
	v_mov_b32_e32 v48, v56
	s_nop 1
	v_permlane32_swap_b32_e32 v56, v48
	v_mfma_f32_32x32x16_bf16 v[32:47], v[66:69], v[82:85], v[32:47]
	s_and_saveexec_b64 s[16:17], vcc
	s_cbranch_execz .LBB0_887
	v_add_f32_e32 v48, v56, v48
	v_lshl_add_u32 v49, v180, 2, s19
	ds_write_b32 v49, v48 offset:49280
	s_branch .LBB0_887
